# GEMM K-loops: two more SGPR-base stages and nine duplicate scalar half-step adds removed
# speedup vs baseline: 1.0107x; 1.0037x over previous
.LBB0_305:
	s_add_u32 s30, s4, 0xfffc0080
	s_addc_u32 s31, s5, -1
	s_add_i32 s52, 0, 0x10000
	ds_read_b128 v[150:153], v133
	ds_read_b128 v[156:159], v133 offset:1024
	ds_read_b128 v[160:163], v133 offset:2048
	ds_read_b128 v[164:167], v133 offset:3072
	s_cmp_eq_u32 s51, 12
	s_cselect_b32 s35, s27, s31
	s_cselect_b32 s34, s26, s30
	s_cselect_b32 s31, s29, s25
	s_cselect_b32 s30, s28, s23
	s_add_i32 m0, s42, 0xc000
	ds_read_b128 v[168:171], v155
	ds_read_b128 v[172:175], v155 offset:1024
	ds_read_b128 v[176:179], v155 offset:2048
	ds_read_b128 v[180:183], v155 offset:3072
	ds_read_b128 v[184:187], v155 offset:4096
	ds_read_b128 v[188:191], v155 offset:5120
	ds_read_b128 v[198:201], v155 offset:6144
	ds_read_b128 v[202:205], v155 offset:7168
	global_load_lds_dwordx4 v146, s[4:5]
	s_add_i32 m0, s42, 0xe000
	s_nop 0
	global_load_lds_dwordx4 v148, s[4:5]
	s_waitcnt lgkmcnt(8)
	s_barrier
	s_waitcnt lgkmcnt(0)
	s_setprio 1
	s_waitcnt lgkmcnt(0)
	v_mfma_f32_16x16x32_bf16 v[126:129], v[150:153], v[168:171], v[126:129]
	v_mfma_f32_16x16x32_bf16 v[122:125], v[160:163], v[168:171], v[122:125]
	v_mfma_f32_16x16x32_bf16 v[110:113], v[150:153], v[176:179], v[110:113]
	v_mfma_f32_16x16x32_bf16 v[106:109], v[160:163], v[176:179], v[106:109]
	v_mfma_f32_16x16x32_bf16 v[94:97], v[150:153], v[184:187], v[94:97]
	v_mfma_f32_16x16x32_bf16 v[90:93], v[160:163], v[184:187], v[90:93]
	v_mfma_f32_16x16x32_bf16 v[78:81], v[150:153], v[198:201], v[78:81]
	v_mfma_f32_16x16x32_bf16 v[74:77], v[160:163], v[198:201], v[74:77]
	v_mfma_f32_16x16x32_bf16 v[126:129], v[156:159], v[172:175], v[126:129]
	v_mfma_f32_16x16x32_bf16 v[122:125], v[164:167], v[172:175], v[122:125]
	v_mfma_f32_16x16x32_bf16 v[110:113], v[156:159], v[180:183], v[110:113]
	v_mfma_f32_16x16x32_bf16 v[106:109], v[164:167], v[180:183], v[106:109]
	v_mfma_f32_16x16x32_bf16 v[94:97], v[156:159], v[188:191], v[94:97]
	v_mfma_f32_16x16x32_bf16 v[90:93], v[164:167], v[188:191], v[90:93]
	v_mfma_f32_16x16x32_bf16 v[78:81], v[156:159], v[202:205], v[78:81]
	v_mfma_f32_16x16x32_bf16 v[74:77], v[164:167], v[202:205], v[74:77]
	s_setprio 0
	s_barrier
	s_add_i32 s54, 0, 0x14000
	s_add_i32 s52, s52, s41
	s_mov_b32 m0, s52
	ds_read_b128 v[206:209], v133 offset:16384
	ds_read_b128 v[210:213], v133 offset:17408
	ds_read_b128 v[214:217], v133 offset:18432
	ds_read_b128 v[218:221], v133 offset:19456
	global_load_lds_dwordx4 v132, s[30:31]
	s_add_i32 m0, s52, 0x2000
	s_nop 0
	global_load_lds_dwordx4 v136, s[30:31]
	s_barrier
	s_waitcnt lgkmcnt(0)
	s_setprio 1
	s_waitcnt lgkmcnt(0)
	v_mfma_f32_16x16x32_bf16 v[118:121], v[206:209], v[168:171], v[118:121]
	v_mfma_f32_16x16x32_bf16 v[114:117], v[214:217], v[168:171], v[114:117]
	v_mfma_f32_16x16x32_bf16 v[102:105], v[206:209], v[176:179], v[102:105]
	v_mfma_f32_16x16x32_bf16 v[98:101], v[214:217], v[176:179], v[98:101]
	v_mfma_f32_16x16x32_bf16 v[86:89], v[206:209], v[184:187], v[86:89]
	v_mfma_f32_16x16x32_bf16 v[82:85], v[214:217], v[184:187], v[82:85]
	v_mfma_f32_16x16x32_bf16 v[70:73], v[206:209], v[198:201], v[70:73]
	v_mfma_f32_16x16x32_bf16 v[66:69], v[214:217], v[198:201], v[66:69]
	v_mfma_f32_16x16x32_bf16 v[118:121], v[210:213], v[172:175], v[118:121]
	v_mfma_f32_16x16x32_bf16 v[114:117], v[218:221], v[172:175], v[114:117]
	v_mfma_f32_16x16x32_bf16 v[102:105], v[210:213], v[180:183], v[102:105]
	v_mfma_f32_16x16x32_bf16 v[98:101], v[218:221], v[180:183], v[98:101]
	v_mfma_f32_16x16x32_bf16 v[86:89], v[210:213], v[188:191], v[86:89]
	v_mfma_f32_16x16x32_bf16 v[82:85], v[218:221], v[188:191], v[82:85]
	v_mfma_f32_16x16x32_bf16 v[70:73], v[210:213], v[202:205], v[70:73]
	v_mfma_f32_16x16x32_bf16 v[66:69], v[218:221], v[202:205], v[66:69]
	s_setprio 0
	s_mov_b32 m0, s42
	v_lshl_add_u64 v[242:243], s[34:35], 0, v[130:131]
	s_barrier
	ds_read_b128 v[168:171], v155 offset:16384
	ds_read_b128 v[172:175], v155 offset:17408
	ds_read_b128 v[176:179], v155 offset:18432
	ds_read_b128 v[180:183], v155 offset:19456
	ds_read_b128 v[184:187], v155 offset:20480
	ds_read_b128 v[188:191], v155 offset:21504
	ds_read_b128 v[198:201], v155 offset:22528
	ds_read_b128 v[202:205], v155 offset:23552
	global_load_lds_dwordx4 v[242:243], off
	v_lshl_add_u64 v[244:245], s[34:35], 0, v[134:135]
	s_mov_b32 m0, s43
	s_nop 0
	global_load_lds_dwordx4 v[244:245], off
	s_barrier
	s_waitcnt lgkmcnt(0)
	s_setprio 1
	s_waitcnt lgkmcnt(0)
	v_mfma_f32_16x16x32_bf16 v[62:65], v[150:153], v[168:171], v[62:65]
	v_mfma_f32_16x16x32_bf16 v[58:61], v[160:163], v[168:171], v[58:61]
	v_mfma_f32_16x16x32_bf16 v[44:47], v[150:153], v[176:179], v[44:47]
	v_mfma_f32_16x16x32_bf16 v[40:43], v[160:163], v[176:179], v[40:43]
	v_mfma_f32_16x16x32_bf16 v[28:31], v[150:153], v[184:187], v[28:31]
	v_mfma_f32_16x16x32_bf16 v[24:27], v[160:163], v[184:187], v[24:27]
	v_mfma_f32_16x16x32_bf16 v[12:15], v[150:153], v[198:201], v[12:15]
	v_mfma_f32_16x16x32_bf16 v[8:11], v[160:163], v[198:201], v[8:11]
	v_mfma_f32_16x16x32_bf16 v[62:65], v[156:159], v[172:175], v[62:65]
	v_mfma_f32_16x16x32_bf16 v[58:61], v[164:167], v[172:175], v[58:61]
	v_mfma_f32_16x16x32_bf16 v[44:47], v[156:159], v[180:183], v[44:47]
	v_mfma_f32_16x16x32_bf16 v[40:43], v[164:167], v[180:183], v[40:43]
	v_mfma_f32_16x16x32_bf16 v[28:31], v[156:159], v[188:191], v[28:31]
	v_mfma_f32_16x16x32_bf16 v[24:27], v[164:167], v[188:191], v[24:27]
	v_mfma_f32_16x16x32_bf16 v[12:15], v[156:159], v[202:205], v[12:15]
	v_mfma_f32_16x16x32_bf16 v[8:11], v[164:167], v[202:205], v[8:11]
	s_setprio 0
	s_barrier
	s_add_u32 s52, s30, 0x40000
	s_addc_u32 s53, s31, 0
	s_add_i32 s54, s54, s41
	s_mov_b32 m0, s54
	s_nop 0
	global_load_lds_dwordx4 v132, s[52:53]
	s_add_i32 m0, s54, 0x2000
	s_nop 0
	global_load_lds_dwordx4 v136, s[52:53]
	s_waitcnt vmcnt(6)
	s_barrier
	s_setprio 1
	v_mfma_f32_16x16x32_bf16 v[54:57], v[206:209], v[168:171], v[54:57]
	v_mfma_f32_16x16x32_bf16 v[50:53], v[214:217], v[168:171], v[50:53]
	v_mfma_f32_16x16x32_bf16 v[36:39], v[206:209], v[176:179], v[36:39]
	v_mfma_f32_16x16x32_bf16 v[32:35], v[214:217], v[176:179], v[32:35]
	v_mfma_f32_16x16x32_bf16 v[20:23], v[206:209], v[184:187], v[20:23]
	v_mfma_f32_16x16x32_bf16 v[16:19], v[214:217], v[184:187], v[16:19]
	v_mfma_f32_16x16x32_bf16 v[4:7], v[206:209], v[198:201], v[4:7]
	v_mfma_f32_16x16x32_bf16 v[0:3], v[214:217], v[198:201], v[0:3]
	v_mfma_f32_16x16x32_bf16 v[54:57], v[210:213], v[172:175], v[54:57]
	v_mfma_f32_16x16x32_bf16 v[50:53], v[218:221], v[172:175], v[50:53]
	v_mfma_f32_16x16x32_bf16 v[36:39], v[210:213], v[180:183], v[36:39]
	v_mfma_f32_16x16x32_bf16 v[32:35], v[218:221], v[180:183], v[32:35]
	v_mfma_f32_16x16x32_bf16 v[20:23], v[210:213], v[188:191], v[20:23]
	v_mfma_f32_16x16x32_bf16 v[16:19], v[218:221], v[188:191], v[16:19]
	v_mfma_f32_16x16x32_bf16 v[4:7], v[210:213], v[202:205], v[4:7]
	v_mfma_f32_16x16x32_bf16 v[0:3], v[218:221], v[202:205], v[0:3]
	s_setprio 0
	s_add_i32 s52, 0, 0x18000
	s_barrier
	ds_read_b128 v[150:153], v133 offset:32768
	ds_read_b128 v[156:159], v133 offset:33792
	ds_read_b128 v[160:163], v133 offset:34816
	ds_read_b128 v[164:167], v133 offset:35840
	s_add_u32 s34, s34, 0x40000
	s_addc_u32 s35, s35, 0
	s_mov_b32 m0, s44
	ds_read_b128 v[168:171], v155 offset:32768
	ds_read_b128 v[172:175], v155 offset:33792
	ds_read_b128 v[176:179], v155 offset:34816
	ds_read_b128 v[180:183], v155 offset:35840
	ds_read_b128 v[184:187], v155 offset:36864
	ds_read_b128 v[188:191], v155 offset:37888
	ds_read_b128 v[198:201], v155 offset:38912
	ds_read_b128 v[202:205], v155 offset:39936
	global_load_lds_dwordx4 v130, s[34:35]
	s_mov_b32 m0, s45
	s_nop 0
	global_load_lds_dwordx4 v134, s[34:35]
	s_waitcnt lgkmcnt(8)
	s_barrier
	s_waitcnt lgkmcnt(0)
	s_setprio 1
	s_waitcnt lgkmcnt(0)
	v_mfma_f32_16x16x32_bf16 v[126:129], v[150:153], v[168:171], v[126:129]
	v_mfma_f32_16x16x32_bf16 v[122:125], v[160:163], v[168:171], v[122:125]
	v_mfma_f32_16x16x32_bf16 v[110:113], v[150:153], v[176:179], v[110:113]
	v_mfma_f32_16x16x32_bf16 v[106:109], v[160:163], v[176:179], v[106:109]
	v_mfma_f32_16x16x32_bf16 v[94:97], v[150:153], v[184:187], v[94:97]
	v_mfma_f32_16x16x32_bf16 v[90:93], v[160:163], v[184:187], v[90:93]
	v_mfma_f32_16x16x32_bf16 v[78:81], v[150:153], v[198:201], v[78:81]
	v_mfma_f32_16x16x32_bf16 v[74:77], v[160:163], v[198:201], v[74:77]
	v_mfma_f32_16x16x32_bf16 v[126:129], v[156:159], v[172:175], v[126:129]
	v_mfma_f32_16x16x32_bf16 v[122:125], v[164:167], v[172:175], v[122:125]
	v_mfma_f32_16x16x32_bf16 v[110:113], v[156:159], v[180:183], v[110:113]
	v_mfma_f32_16x16x32_bf16 v[106:109], v[164:167], v[180:183], v[106:109]
	v_mfma_f32_16x16x32_bf16 v[94:97], v[156:159], v[188:191], v[94:97]
	v_mfma_f32_16x16x32_bf16 v[90:93], v[164:167], v[188:191], v[90:93]
	v_mfma_f32_16x16x32_bf16 v[78:81], v[156:159], v[202:205], v[78:81]
	v_mfma_f32_16x16x32_bf16 v[74:77], v[164:167], v[202:205], v[74:77]
	s_setprio 0
	s_barrier
	s_add_i32 s34, 0, 0x1c000
	s_add_i32 s35, s52, s41
	s_add_u32 s52, s30, s66
	s_addc_u32 s53, s31, s67
	s_mov_b32 m0, s35
	ds_read_b128 v[206:209], v133 offset:49152
	ds_read_b128 v[210:213], v133 offset:50176
	ds_read_b128 v[214:217], v133 offset:51200
	ds_read_b128 v[218:221], v133 offset:52224
	global_load_lds_dwordx4 v132, s[52:53]
	s_add_i32 m0, s35, 0x2000
	s_nop 0
	global_load_lds_dwordx4 v136, s[52:53]
	s_barrier
	s_waitcnt lgkmcnt(0)
	s_setprio 1
	s_waitcnt lgkmcnt(0)
	v_mfma_f32_16x16x32_bf16 v[118:121], v[206:209], v[168:171], v[118:121]
	v_mfma_f32_16x16x32_bf16 v[114:117], v[214:217], v[168:171], v[114:117]
	v_mfma_f32_16x16x32_bf16 v[102:105], v[206:209], v[176:179], v[102:105]
	v_mfma_f32_16x16x32_bf16 v[98:101], v[214:217], v[176:179], v[98:101]
	v_mfma_f32_16x16x32_bf16 v[86:89], v[206:209], v[184:187], v[86:89]
	v_mfma_f32_16x16x32_bf16 v[82:85], v[214:217], v[184:187], v[82:85]
	v_mfma_f32_16x16x32_bf16 v[70:73], v[206:209], v[198:201], v[70:73]
	v_mfma_f32_16x16x32_bf16 v[66:69], v[214:217], v[198:201], v[66:69]
	v_mfma_f32_16x16x32_bf16 v[118:121], v[210:213], v[172:175], v[118:121]
	v_mfma_f32_16x16x32_bf16 v[114:117], v[218:221], v[172:175], v[114:117]
	v_mfma_f32_16x16x32_bf16 v[102:105], v[210:213], v[180:183], v[102:105]
	v_mfma_f32_16x16x32_bf16 v[98:101], v[218:221], v[180:183], v[98:101]
	v_mfma_f32_16x16x32_bf16 v[86:89], v[210:213], v[188:191], v[86:89]
	v_mfma_f32_16x16x32_bf16 v[82:85], v[218:221], v[188:191], v[82:85]
	v_mfma_f32_16x16x32_bf16 v[70:73], v[210:213], v[202:205], v[70:73]
	v_mfma_f32_16x16x32_bf16 v[66:69], v[218:221], v[202:205], v[66:69]
	s_setprio 0
	s_mov_b32 m0, s46
	v_lshl_add_u64 v[192:193], v[242:243], 0, s[66:67]
	s_barrier
	ds_read_b128 v[168:171], v155 offset:49152
	ds_read_b128 v[172:175], v155 offset:50176
	ds_read_b128 v[176:179], v155 offset:51200
	ds_read_b128 v[180:183], v155 offset:52224
	ds_read_b128 v[184:187], v155 offset:53248
	ds_read_b128 v[188:191], v155 offset:54272
	ds_read_b128 v[198:201], v155 offset:55296
	ds_read_b128 v[202:205], v155 offset:56320
	global_load_lds_dwordx4 v[192:193], off
	v_lshl_add_u64 v[192:193], v[244:245], 0, s[66:67]
	s_mov_b32 m0, s47
	s_nop 0
	global_load_lds_dwordx4 v[192:193], off
	s_barrier
	s_waitcnt lgkmcnt(0)
	s_setprio 1
	s_waitcnt lgkmcnt(0)
	v_mfma_f32_16x16x32_bf16 v[62:65], v[150:153], v[168:171], v[62:65]
	v_mfma_f32_16x16x32_bf16 v[58:61], v[160:163], v[168:171], v[58:61]
	v_mfma_f32_16x16x32_bf16 v[44:47], v[150:153], v[176:179], v[44:47]
	v_mfma_f32_16x16x32_bf16 v[40:43], v[160:163], v[176:179], v[40:43]
	v_mfma_f32_16x16x32_bf16 v[28:31], v[150:153], v[184:187], v[28:31]
	v_mfma_f32_16x16x32_bf16 v[24:27], v[160:163], v[184:187], v[24:27]
	v_mfma_f32_16x16x32_bf16 v[12:15], v[150:153], v[198:201], v[12:15]
	v_mfma_f32_16x16x32_bf16 v[8:11], v[160:163], v[198:201], v[8:11]
	v_mfma_f32_16x16x32_bf16 v[62:65], v[156:159], v[172:175], v[62:65]
	v_mfma_f32_16x16x32_bf16 v[58:61], v[164:167], v[172:175], v[58:61]
	v_mfma_f32_16x16x32_bf16 v[44:47], v[156:159], v[180:183], v[44:47]
	v_mfma_f32_16x16x32_bf16 v[40:43], v[164:167], v[180:183], v[40:43]
	v_mfma_f32_16x16x32_bf16 v[28:31], v[156:159], v[188:191], v[28:31]
	v_mfma_f32_16x16x32_bf16 v[24:27], v[164:167], v[188:191], v[24:27]
	v_mfma_f32_16x16x32_bf16 v[12:15], v[156:159], v[202:205], v[12:15]
	v_mfma_f32_16x16x32_bf16 v[8:11], v[164:167], v[202:205], v[8:11]
	s_setprio 0
	s_barrier
	s_add_u32 s30, s30, 0x40080
	s_addc_u32 s31, s31, 0
	s_add_i32 s34, s34, s41
	s_mov_b32 m0, s34
	s_nop 0
	global_load_lds_dwordx4 v132, s[30:31]
	s_add_i32 m0, s34, 0x2000
	s_nop 0
	global_load_lds_dwordx4 v136, s[30:31]
	s_waitcnt vmcnt(6)
	s_barrier
	s_setprio 1
	v_mfma_f32_16x16x32_bf16 v[54:57], v[206:209], v[168:171], v[54:57]
	v_mfma_f32_16x16x32_bf16 v[50:53], v[214:217], v[168:171], v[50:53]
	v_mfma_f32_16x16x32_bf16 v[36:39], v[206:209], v[176:179], v[36:39]
	v_mfma_f32_16x16x32_bf16 v[32:35], v[214:217], v[176:179], v[32:35]
	v_mfma_f32_16x16x32_bf16 v[20:23], v[206:209], v[184:187], v[20:23]
	v_mfma_f32_16x16x32_bf16 v[16:19], v[214:217], v[184:187], v[16:19]
	v_mfma_f32_16x16x32_bf16 v[4:7], v[206:209], v[198:201], v[4:7]
	v_mfma_f32_16x16x32_bf16 v[0:3], v[214:217], v[198:201], v[0:3]
	v_mfma_f32_16x16x32_bf16 v[54:57], v[210:213], v[172:175], v[54:57]
	v_mfma_f32_16x16x32_bf16 v[50:53], v[218:221], v[172:175], v[50:53]
	v_mfma_f32_16x16x32_bf16 v[36:39], v[210:213], v[180:183], v[36:39]
	v_mfma_f32_16x16x32_bf16 v[32:35], v[218:221], v[180:183], v[32:35]
	v_mfma_f32_16x16x32_bf16 v[20:23], v[210:213], v[188:191], v[20:23]
	v_mfma_f32_16x16x32_bf16 v[16:19], v[218:221], v[188:191], v[16:19]
	v_mfma_f32_16x16x32_bf16 v[4:7], v[210:213], v[202:205], v[4:7]
	v_mfma_f32_16x16x32_bf16 v[0:3], v[218:221], v[202:205], v[0:3]
	s_setprio 0
	s_add_i32 s51, s51, 2
	s_add_u32 s4, s4, 0x100
	s_addc_u32 s5, s5, 0
	s_add_u32 s23, s23, 0x100
	s_addc_u32 s25, s25, 0
	s_cmp_gt_u32 s51, 13
	s_barrier
	s_cbranch_scc0 .LBB0_305
	v_lshl_add_u32 v156, s50, 8, v139
	v_ashrrev_i32_e32 v48, 31, v156
	v_alignbit_b32 v150, v48, v156, 6
	v_mad_u64_u32 v[150:151], s[4:5], v150, s71, 0
	v_mad_i32_i24 v151, v48, s71, v151
	v_lshlrev_b32_e32 v48, 3, v156
	s_cmp_lg_u32 s49, 0
	v_and_b32_e32 v48, 0x78, v48
	s_cselect_b64 s[30:31], -1, 0
	s_and_b64 vcc, exec, s[30:31]
	v_lshl_add_u32 v157, s49, 8, v145
	v_lshlrev_b32_e32 v48, 1, v48
	s_cbranch_vccz .LBB0_314
	v_ashrrev_i32_e32 v152, 3, v157
	v_ashrrev_i32_e32 v153, 31, v152
	v_lshl_add_u64 v[152:153], v[150:151], 0, v[152:153]
	v_lshlrev_b64 v[152:153], 10, v[152:153]
	v_lshl_add_u64 v[152:153], s[18:19], 0, v[152:153]
	v_lshl_add_u64 v[152:153], v[152:153], 0, v[48:49]
	v_ashrrev_i32_e32 v159, 5, v156
	v_add_u32_e32 v158, v159, v140
	s_cbranch_execnz .LBB0_309

.LBB0_641:
	s_add_u32 s24, s22, 0x100
	s_addc_u32 s25, s23, 0
	s_add_i32 s50, 0, 0x10000
	ds_read_b128 v[146:149], v131
	ds_read_b128 v[150:153], v131 offset:1024
	ds_read_b128 v[154:157], v131 offset:2048
	ds_read_b128 v[158:161], v131 offset:3072
	s_cmp_eq_u32 s49, 4
	s_cselect_b32 s29, s19, s25
	s_cselect_b32 s28, s18, s24
	s_cselect_b32 s27, s21, s48
	s_cselect_b32 s26, s20, s5
	v_lshl_add_u64 v[198:199], s[22:23], 0, v[138:139]
	s_add_i32 m0, s38, 0xc000
	ds_read_b128 v[162:165], v144
	ds_read_b128 v[166:169], v144 offset:1024
	ds_read_b128 v[170:173], v144 offset:2048
	ds_read_b128 v[174:177], v144 offset:3072
	ds_read_b128 v[178:181], v144 offset:4096
	ds_read_b128 v[182:185], v144 offset:5120
	ds_read_b128 v[186:189], v144 offset:6144
	ds_read_b128 v[190:193], v144 offset:7168
	global_load_lds_dwordx4 v[198:199], off
	v_lshl_add_u64 v[198:199], s[22:23], 0, v[140:141]
	s_add_i32 m0, s38, 0xe000
	s_nop 0
	global_load_lds_dwordx4 v[198:199], off
	s_waitcnt lgkmcnt(8)
	s_barrier
	s_waitcnt lgkmcnt(0)
	s_setprio 1
	s_waitcnt lgkmcnt(0)
	v_mfma_f32_16x16x32_bf16 v[126:129], v[146:149], v[162:165], v[126:129]
	v_mfma_f32_16x16x32_bf16 v[122:125], v[154:157], v[162:165], v[122:125]
	v_mfma_f32_16x16x32_bf16 v[118:121], v[146:149], v[170:173], v[118:121]
	v_mfma_f32_16x16x32_bf16 v[114:117], v[154:157], v[170:173], v[114:117]
	v_mfma_f32_16x16x32_bf16 v[106:109], v[146:149], v[178:181], v[106:109]
	v_mfma_f32_16x16x32_bf16 v[98:101], v[154:157], v[178:181], v[98:101]
	v_mfma_f32_16x16x32_bf16 v[90:93], v[146:149], v[186:189], v[90:93]
	v_mfma_f32_16x16x32_bf16 v[82:85], v[154:157], v[186:189], v[82:85]
	v_mfma_f32_16x16x32_bf16 v[126:129], v[150:153], v[166:169], v[126:129]
	v_mfma_f32_16x16x32_bf16 v[122:125], v[158:161], v[166:169], v[122:125]
	v_mfma_f32_16x16x32_bf16 v[118:121], v[150:153], v[174:177], v[118:121]
	v_mfma_f32_16x16x32_bf16 v[114:117], v[158:161], v[174:177], v[114:117]
	v_mfma_f32_16x16x32_bf16 v[106:109], v[150:153], v[182:185], v[106:109]
	v_mfma_f32_16x16x32_bf16 v[98:101], v[158:161], v[182:185], v[98:101]
	v_mfma_f32_16x16x32_bf16 v[90:93], v[150:153], v[190:193], v[90:93]
	v_mfma_f32_16x16x32_bf16 v[82:85], v[158:161], v[190:193], v[82:85]
	s_setprio 0
	s_barrier
	s_add_i32 s51, 0, 0x14000
	s_add_i32 s22, s50, s37
	s_mov_b32 m0, s22
	ds_read_b128 v[198:201], v131 offset:16384
	ds_read_b128 v[202:205], v131 offset:17408
	ds_read_b128 v[206:209], v131 offset:18432
	ds_read_b128 v[210:213], v131 offset:19456
	global_load_lds_dwordx4 v48, s[26:27]
	s_add_i32 m0, s22, 0x2000
	s_nop 0
	global_load_lds_dwordx4 v130, s[26:27]
	s_barrier
	s_waitcnt lgkmcnt(0)
	s_setprio 1
	s_waitcnt lgkmcnt(0)
	v_mfma_f32_16x16x32_bf16 v[110:113], v[198:201], v[162:165], v[110:113]
	v_mfma_f32_16x16x32_bf16 v[102:105], v[206:209], v[162:165], v[102:105]
	v_mfma_f32_16x16x32_bf16 v[94:97], v[198:201], v[170:173], v[94:97]
	v_mfma_f32_16x16x32_bf16 v[86:89], v[206:209], v[170:173], v[86:89]
	v_mfma_f32_16x16x32_bf16 v[78:81], v[198:201], v[178:181], v[78:81]
	v_mfma_f32_16x16x32_bf16 v[74:77], v[206:209], v[178:181], v[74:77]
	v_mfma_f32_16x16x32_bf16 v[70:73], v[198:201], v[186:189], v[70:73]
	v_mfma_f32_16x16x32_bf16 v[66:69], v[206:209], v[186:189], v[66:69]
	v_mfma_f32_16x16x32_bf16 v[110:113], v[202:205], v[166:169], v[110:113]
	v_mfma_f32_16x16x32_bf16 v[102:105], v[210:213], v[166:169], v[102:105]
	v_mfma_f32_16x16x32_bf16 v[94:97], v[202:205], v[174:177], v[94:97]
	v_mfma_f32_16x16x32_bf16 v[86:89], v[210:213], v[174:177], v[86:89]
	v_mfma_f32_16x16x32_bf16 v[78:81], v[202:205], v[182:185], v[78:81]
	v_mfma_f32_16x16x32_bf16 v[74:77], v[210:213], v[182:185], v[74:77]
	v_mfma_f32_16x16x32_bf16 v[70:73], v[202:205], v[190:193], v[70:73]
	v_mfma_f32_16x16x32_bf16 v[66:69], v[210:213], v[190:193], v[66:69]
	s_setprio 0
	s_mov_b32 m0, s38
	v_lshl_add_u64 v[218:219], s[28:29], 0, v[134:135]
	s_barrier
	ds_read_b128 v[162:165], v144 offset:16384
	ds_read_b128 v[166:169], v144 offset:17408
	ds_read_b128 v[170:173], v144 offset:18432
	ds_read_b128 v[174:177], v144 offset:19456
	ds_read_b128 v[178:181], v144 offset:20480
	ds_read_b128 v[182:185], v144 offset:21504
	ds_read_b128 v[186:189], v144 offset:22528
	ds_read_b128 v[190:193], v144 offset:23552
	global_load_lds_dwordx4 v[218:219], off
	v_lshl_add_u64 v[220:221], s[28:29], 0, v[132:133]
	s_mov_b32 m0, s39
	s_nop 0
	global_load_lds_dwordx4 v[220:221], off
	s_barrier
	s_waitcnt lgkmcnt(0)
	s_setprio 1
	s_waitcnt lgkmcnt(0)
	v_mfma_f32_16x16x32_bf16 v[62:65], v[146:149], v[162:165], v[62:65]
	v_mfma_f32_16x16x32_bf16 v[58:61], v[154:157], v[162:165], v[58:61]
	v_mfma_f32_16x16x32_bf16 v[54:57], v[146:149], v[170:173], v[54:57]
	v_mfma_f32_16x16x32_bf16 v[50:53], v[154:157], v[170:173], v[50:53]
	v_mfma_f32_16x16x32_bf16 v[36:39], v[146:149], v[178:181], v[36:39]
	v_mfma_f32_16x16x32_bf16 v[32:35], v[154:157], v[178:181], v[32:35]
	v_mfma_f32_16x16x32_bf16 v[20:23], v[146:149], v[186:189], v[20:23]
	v_mfma_f32_16x16x32_bf16 v[16:19], v[154:157], v[186:189], v[16:19]
	v_mfma_f32_16x16x32_bf16 v[62:65], v[150:153], v[166:169], v[62:65]
	v_mfma_f32_16x16x32_bf16 v[58:61], v[158:161], v[166:169], v[58:61]
	v_mfma_f32_16x16x32_bf16 v[54:57], v[150:153], v[174:177], v[54:57]
	v_mfma_f32_16x16x32_bf16 v[50:53], v[158:161], v[174:177], v[50:53]
	v_mfma_f32_16x16x32_bf16 v[36:39], v[150:153], v[182:185], v[36:39]
	v_mfma_f32_16x16x32_bf16 v[32:35], v[158:161], v[182:185], v[32:35]
	v_mfma_f32_16x16x32_bf16 v[20:23], v[150:153], v[190:193], v[20:23]
	v_mfma_f32_16x16x32_bf16 v[16:19], v[158:161], v[190:193], v[16:19]
	s_setprio 0
	s_barrier
	s_add_u32 s22, s26, 0x20000
	s_addc_u32 s23, s27, 0
	s_add_i32 s50, s51, s37
	s_mov_b32 m0, s50
	s_nop 0
	global_load_lds_dwordx4 v48, s[22:23]
	s_add_i32 m0, s50, 0x2000
	s_nop 0
	global_load_lds_dwordx4 v130, s[22:23]
	s_waitcnt vmcnt(6)
	s_barrier
	s_setprio 1
	v_mfma_f32_16x16x32_bf16 v[44:47], v[198:201], v[162:165], v[44:47]
	v_mfma_f32_16x16x32_bf16 v[40:43], v[206:209], v[162:165], v[40:43]
	v_mfma_f32_16x16x32_bf16 v[28:31], v[198:201], v[170:173], v[28:31]
	v_mfma_f32_16x16x32_bf16 v[24:27], v[206:209], v[170:173], v[24:27]
	v_mfma_f32_16x16x32_bf16 v[12:15], v[198:201], v[178:181], v[12:15]
	v_mfma_f32_16x16x32_bf16 v[8:11], v[206:209], v[178:181], v[8:11]
	v_mfma_f32_16x16x32_bf16 v[4:7], v[198:201], v[186:189], v[4:7]
	v_mfma_f32_16x16x32_bf16 v[0:3], v[206:209], v[186:189], v[0:3]
	v_mfma_f32_16x16x32_bf16 v[44:47], v[202:205], v[166:169], v[44:47]
	v_mfma_f32_16x16x32_bf16 v[40:43], v[210:213], v[166:169], v[40:43]
	v_mfma_f32_16x16x32_bf16 v[28:31], v[202:205], v[174:177], v[28:31]
	v_mfma_f32_16x16x32_bf16 v[24:27], v[210:213], v[174:177], v[24:27]
	v_mfma_f32_16x16x32_bf16 v[12:15], v[202:205], v[182:185], v[12:15]
	v_mfma_f32_16x16x32_bf16 v[8:11], v[210:213], v[182:185], v[8:11]
	v_mfma_f32_16x16x32_bf16 v[4:7], v[202:205], v[190:193], v[4:7]
	v_mfma_f32_16x16x32_bf16 v[0:3], v[210:213], v[190:193], v[0:3]
	s_setprio 0
	s_add_i32 s50, 0, 0x18000
	s_barrier
	ds_read_b128 v[146:149], v131 offset:32768
	ds_read_b128 v[150:153], v131 offset:33792
	ds_read_b128 v[154:157], v131 offset:34816
	ds_read_b128 v[158:161], v131 offset:35840
	s_add_u32 s22, s28, 0x30000
	s_addc_u32 s23, s29, 0
	s_mov_b32 m0, s40
	ds_read_b128 v[162:165], v144 offset:32768
	ds_read_b128 v[166:169], v144 offset:33792
	ds_read_b128 v[170:173], v144 offset:34816
	ds_read_b128 v[174:177], v144 offset:35840
	ds_read_b128 v[178:181], v144 offset:36864
	ds_read_b128 v[182:185], v144 offset:37888
	ds_read_b128 v[186:189], v144 offset:38912
	ds_read_b128 v[190:193], v144 offset:39936
	global_load_lds_dwordx4 v134, s[22:23]
	s_mov_b32 m0, s41
	s_nop 0
	global_load_lds_dwordx4 v132, s[22:23]
	s_waitcnt lgkmcnt(8)
	s_barrier
	s_waitcnt lgkmcnt(0)
	s_setprio 1
	s_waitcnt lgkmcnt(0)
	v_mfma_f32_16x16x32_bf16 v[126:129], v[146:149], v[162:165], v[126:129]
	v_mfma_f32_16x16x32_bf16 v[122:125], v[154:157], v[162:165], v[122:125]
	v_mfma_f32_16x16x32_bf16 v[118:121], v[146:149], v[170:173], v[118:121]
	v_mfma_f32_16x16x32_bf16 v[114:117], v[154:157], v[170:173], v[114:117]
	v_mfma_f32_16x16x32_bf16 v[106:109], v[146:149], v[178:181], v[106:109]
	v_mfma_f32_16x16x32_bf16 v[98:101], v[154:157], v[178:181], v[98:101]
	v_mfma_f32_16x16x32_bf16 v[90:93], v[146:149], v[186:189], v[90:93]
	v_mfma_f32_16x16x32_bf16 v[82:85], v[154:157], v[186:189], v[82:85]
	v_mfma_f32_16x16x32_bf16 v[126:129], v[150:153], v[166:169], v[126:129]
	v_mfma_f32_16x16x32_bf16 v[122:125], v[158:161], v[166:169], v[122:125]
	v_mfma_f32_16x16x32_bf16 v[118:121], v[150:153], v[174:177], v[118:121]
	v_mfma_f32_16x16x32_bf16 v[114:117], v[158:161], v[174:177], v[114:117]
	v_mfma_f32_16x16x32_bf16 v[106:109], v[150:153], v[182:185], v[106:109]
	v_mfma_f32_16x16x32_bf16 v[98:101], v[158:161], v[182:185], v[98:101]
	v_mfma_f32_16x16x32_bf16 v[90:93], v[150:153], v[190:193], v[90:93]
	v_mfma_f32_16x16x32_bf16 v[82:85], v[158:161], v[190:193], v[82:85]
	s_setprio 0
	s_barrier
	s_add_i32 s28, 0, 0x1c000
	s_add_i32 s22, s50, s37
	s_add_u32 s52, s26, s66
	s_addc_u32 s53, s27, s67
	s_mov_b32 m0, s22
	ds_read_b128 v[198:201], v131 offset:49152
	ds_read_b128 v[202:205], v131 offset:50176
	ds_read_b128 v[206:209], v131 offset:51200
	ds_read_b128 v[210:213], v131 offset:52224
	global_load_lds_dwordx4 v48, s[52:53]
	s_add_i32 m0, s22, 0x2000
	s_nop 0
	global_load_lds_dwordx4 v130, s[52:53]
	s_barrier
	s_waitcnt lgkmcnt(0)
	s_setprio 1
	s_waitcnt lgkmcnt(0)
	v_mfma_f32_16x16x32_bf16 v[110:113], v[198:201], v[162:165], v[110:113]
	v_mfma_f32_16x16x32_bf16 v[102:105], v[206:209], v[162:165], v[102:105]
	v_mfma_f32_16x16x32_bf16 v[94:97], v[198:201], v[170:173], v[94:97]
	v_mfma_f32_16x16x32_bf16 v[86:89], v[206:209], v[170:173], v[86:89]
	v_mfma_f32_16x16x32_bf16 v[78:81], v[198:201], v[178:181], v[78:81]
	v_mfma_f32_16x16x32_bf16 v[74:77], v[206:209], v[178:181], v[74:77]
	v_mfma_f32_16x16x32_bf16 v[70:73], v[198:201], v[186:189], v[70:73]
	v_mfma_f32_16x16x32_bf16 v[66:69], v[206:209], v[186:189], v[66:69]
	v_mfma_f32_16x16x32_bf16 v[110:113], v[202:205], v[166:169], v[110:113]
	v_mfma_f32_16x16x32_bf16 v[102:105], v[210:213], v[166:169], v[102:105]
	v_mfma_f32_16x16x32_bf16 v[94:97], v[202:205], v[174:177], v[94:97]
	v_mfma_f32_16x16x32_bf16 v[86:89], v[210:213], v[174:177], v[86:89]
	v_mfma_f32_16x16x32_bf16 v[78:81], v[202:205], v[182:185], v[78:81]
	v_mfma_f32_16x16x32_bf16 v[74:77], v[210:213], v[182:185], v[74:77]
	v_mfma_f32_16x16x32_bf16 v[70:73], v[202:205], v[190:193], v[70:73]
	v_mfma_f32_16x16x32_bf16 v[66:69], v[210:213], v[190:193], v[66:69]
	s_setprio 0
	s_mov_b32 m0, s42
	v_lshl_add_u64 v[214:215], v[218:219], 0, s[66:67]
	s_barrier
	ds_read_b128 v[162:165], v144 offset:49152
	ds_read_b128 v[166:169], v144 offset:50176
	ds_read_b128 v[170:173], v144 offset:51200
	ds_read_b128 v[174:177], v144 offset:52224
	ds_read_b128 v[178:181], v144 offset:53248
	ds_read_b128 v[182:185], v144 offset:54272
	ds_read_b128 v[186:189], v144 offset:55296
	ds_read_b128 v[190:193], v144 offset:56320
	global_load_lds_dwordx4 v[214:215], off
	v_lshl_add_u64 v[214:215], v[220:221], 0, s[66:67]
	s_mov_b32 m0, s43
	s_nop 0
	global_load_lds_dwordx4 v[214:215], off
	s_barrier
	s_waitcnt lgkmcnt(0)
	s_setprio 1
	s_waitcnt lgkmcnt(0)
	v_mfma_f32_16x16x32_bf16 v[62:65], v[146:149], v[162:165], v[62:65]
	v_mfma_f32_16x16x32_bf16 v[58:61], v[154:157], v[162:165], v[58:61]
	v_mfma_f32_16x16x32_bf16 v[54:57], v[146:149], v[170:173], v[54:57]
	v_mfma_f32_16x16x32_bf16 v[50:53], v[154:157], v[170:173], v[50:53]
	v_mfma_f32_16x16x32_bf16 v[36:39], v[146:149], v[178:181], v[36:39]
	v_mfma_f32_16x16x32_bf16 v[32:35], v[154:157], v[178:181], v[32:35]
	v_mfma_f32_16x16x32_bf16 v[20:23], v[146:149], v[186:189], v[20:23]
	v_mfma_f32_16x16x32_bf16 v[16:19], v[154:157], v[186:189], v[16:19]
	v_mfma_f32_16x16x32_bf16 v[62:65], v[150:153], v[166:169], v[62:65]
	v_mfma_f32_16x16x32_bf16 v[58:61], v[158:161], v[166:169], v[58:61]
	v_mfma_f32_16x16x32_bf16 v[54:57], v[150:153], v[174:177], v[54:57]
	v_mfma_f32_16x16x32_bf16 v[50:53], v[158:161], v[174:177], v[50:53]
	v_mfma_f32_16x16x32_bf16 v[36:39], v[150:153], v[182:185], v[36:39]
	v_mfma_f32_16x16x32_bf16 v[32:35], v[158:161], v[182:185], v[32:35]
	v_mfma_f32_16x16x32_bf16 v[20:23], v[150:153], v[190:193], v[20:23]
	v_mfma_f32_16x16x32_bf16 v[16:19], v[158:161], v[190:193], v[16:19]
	s_setprio 0
	s_barrier
	s_add_u32 s22, s26, 0x20080
	s_addc_u32 s23, s27, 0
	s_add_i32 s26, s28, s37
	s_mov_b32 m0, s26
	s_nop 0
	global_load_lds_dwordx4 v48, s[22:23]
	s_add_i32 m0, s26, 0x2000
	s_nop 0
	global_load_lds_dwordx4 v130, s[22:23]
	s_waitcnt vmcnt(6)
	s_barrier
	s_setprio 1
	v_mfma_f32_16x16x32_bf16 v[44:47], v[198:201], v[162:165], v[44:47]
	v_mfma_f32_16x16x32_bf16 v[40:43], v[206:209], v[162:165], v[40:43]
	v_mfma_f32_16x16x32_bf16 v[28:31], v[198:201], v[170:173], v[28:31]
	v_mfma_f32_16x16x32_bf16 v[24:27], v[206:209], v[170:173], v[24:27]
	v_mfma_f32_16x16x32_bf16 v[12:15], v[198:201], v[178:181], v[12:15]
	v_mfma_f32_16x16x32_bf16 v[8:11], v[206:209], v[178:181], v[8:11]
	v_mfma_f32_16x16x32_bf16 v[4:7], v[198:201], v[186:189], v[4:7]
	v_mfma_f32_16x16x32_bf16 v[0:3], v[206:209], v[186:189], v[0:3]
	v_mfma_f32_16x16x32_bf16 v[44:47], v[202:205], v[166:169], v[44:47]
	v_mfma_f32_16x16x32_bf16 v[40:43], v[210:213], v[166:169], v[40:43]
	v_mfma_f32_16x16x32_bf16 v[28:31], v[202:205], v[174:177], v[28:31]
	v_mfma_f32_16x16x32_bf16 v[24:27], v[210:213], v[174:177], v[24:27]
	v_mfma_f32_16x16x32_bf16 v[12:15], v[202:205], v[182:185], v[12:15]
	v_mfma_f32_16x16x32_bf16 v[8:11], v[210:213], v[182:185], v[8:11]
	v_mfma_f32_16x16x32_bf16 v[4:7], v[202:205], v[190:193], v[4:7]
	v_mfma_f32_16x16x32_bf16 v[0:3], v[210:213], v[190:193], v[0:3]
	s_setprio 0
	s_add_i32 s49, s49, 2
	s_add_u32 s5, s5, 0x100
	s_addc_u32 s48, s48, 0
	s_cmp_gt_u32 s49, 5
	s_mov_b64 s[22:23], s[24:25]
	s_barrier
	s_cbranch_scc0 .LBB0_641
	v_lshl_add_u32 v146, s47, 8, v142
	v_mov_b32_e32 v145, 0x240000
	v_ashrrev_i32_e32 v147, 31, v146
	v_mad_i64_i32 v[148:149], s[22:23], s46, v145, v[136:137]
	v_lshlrev_b64 v[150:151], 10, v[146:147]
	v_lshl_add_u64 v[150:151], v[148:149], 0, v[150:151]
	global_store_dwordx4 v[150:151], v[126:129], off
	global_store_dwordx4 v[150:151], v[122:125], off offset:64
	global_store_dwordx4 v[150:151], v[110:113], off offset:512
	global_store_dwordx4 v[150:151], v[102:105], off offset:576
	s_mov_b32 s5, 0x20000
	s_mov_b64 s[22:23], 0x20000
	v_or_b32_e32 v102, 16, v146
	v_ashrrev_i32_e32 v103, 31, v102
	v_lshlrev_b64 v[102:103], 10, v[102:103]
	v_lshl_add_u64 v[102:103], v[148:149], 0, v[102:103]
	global_store_dwordx4 v[102:103], v[118:121], off
	global_store_dwordx4 v[102:103], v[114:117], off offset:64
	global_store_dwordx4 v[102:103], v[94:97], off offset:512
	global_store_dwordx4 v[102:103], v[86:89], off offset:576
	s_mov_b32 s46, s4
	s_mov_b32 s47, s45
	v_or_b32_e32 v86, 32, v146
	v_ashrrev_i32_e32 v87, 31, v86
	v_lshlrev_b64 v[86:87], 10, v[86:87]
	v_lshl_add_u64 v[86:87], v[148:149], 0, v[86:87]
	global_store_dwordx4 v[86:87], v[106:109], off
	global_store_dwordx4 v[86:87], v[98:101], off offset:64
	global_store_dwordx4 v[86:87], v[78:81], off offset:512
	global_store_dwordx4 v[86:87], v[74:77], off offset:576
	s_mov_b64 s[24:25], s[20:21]
	s_nop 0
	v_or_b32_e32 v74, 48, v146
	v_ashrrev_i32_e32 v75, 31, v74
	v_lshlrev_b64 v[74:75], 10, v[74:75]
	v_lshl_add_u64 v[74:75], v[148:149], 0, v[74:75]
	global_store_dwordx4 v[74:75], v[90:93], off
	global_store_dwordx4 v[74:75], v[82:85], off offset:64
	global_store_dwordx4 v[74:75], v[70:73], off offset:512
	global_store_dwordx4 v[74:75], v[66:69], off offset:576
	s_nop 1
	v_add_co_u32_e32 v68, vcc, s5, v150
	s_mov_b32 s5, 0x24000
	s_nop 0
	v_addc_co_u32_e32 v69, vcc, 0, v151, vcc
	v_lshl_add_u64 v[66:67], v[150:151], 0, s[22:23]
	global_store_dwordx4 v[68:69], v[62:65], off
	global_store_dwordx4 v[66:67], v[58:61], off offset:64
	global_store_dwordx4 v[66:67], v[44:47], off offset:512
	global_store_dwordx4 v[66:67], v[40:43], off offset:576
	s_mov_b64 s[22:23], 0x24000
	s_nop 0
	v_add_co_u32_e32 v42, vcc, s5, v150
	s_mov_b32 s5, 0x28000
	s_nop 0
	v_addc_co_u32_e32 v43, vcc, 0, v151, vcc
	v_lshl_add_u64 v[40:41], v[150:151], 0, s[22:23]
	global_store_dwordx4 v[42:43], v[54:57], off
	global_store_dwordx4 v[40:41], v[50:53], off offset:64
	global_store_dwordx4 v[40:41], v[28:31], off offset:512
	global_store_dwordx4 v[40:41], v[24:27], off offset:576
	s_mov_b64 s[22:23], 0x28000
	s_nop 0
	v_add_co_u32_e32 v26, vcc, s5, v150
	v_lshl_add_u64 v[24:25], v[150:151], 0, s[22:23]
	s_nop 0
	v_addc_co_u32_e32 v27, vcc, 0, v151, vcc
	global_store_dwordx4 v[26:27], v[36:39], off
	global_store_dwordx4 v[24:25], v[32:35], off offset:64
	global_store_dwordx4 v[24:25], v[12:15], off offset:512
	global_store_dwordx4 v[24:25], v[8:11], off offset:576
	s_mov_b64 s[22:23], 0x2c000
	s_nop 0
	v_add_co_u32_e32 v10, vcc, 0x2c000, v150
	v_lshl_add_u64 v[8:9], v[150:151], 0, s[22:23]
	s_nop 0
	v_addc_co_u32_e32 v11, vcc, 0, v151, vcc
	s_and_b64 vcc, exec, s[0:1]
	s_mov_b64 s[22:23], s[18:19]
	global_store_dwordx4 v[10:11], v[20:23], off
	global_store_dwordx4 v[8:9], v[16:19], off offset:64
	global_store_dwordx4 v[8:9], v[4:7], off offset:512
	global_store_dwordx4 v[8:9], v[0:3], off offset:576
	s_cbranch_vccz .LBB0_638
	s_waitcnt vmcnt(0)
	s_cmpk_gt_u32 s30, 0xff
	s_cbranch_scc1 .LBB0_645
	s_barrier

.LBB0_822:
	s_add_u32 s12, s10, 0x100
	s_addc_u32 s13, s11, 0
	s_add_i32 s42, 0, 0x10000
	ds_read_b128 v[142:145], v131
	ds_read_b128 v[150:153], v131 offset:1024
	ds_read_b128 v[154:157], v131 offset:2048
	ds_read_b128 v[158:161], v131 offset:3072
	s_cmp_eq_u32 s41, 8
	s_cselect_b32 s17, s5, s13
	s_cselect_b32 s16, s4, s12
	s_cselect_b32 s15, s7, s40
	s_cselect_b32 s14, s6, s39
	v_lshl_add_u64 v[198:199], s[10:11], 0, v[138:139]
	s_add_i32 m0, s24, 0xc000
	ds_read_b128 v[162:165], v149
	ds_read_b128 v[166:169], v149 offset:1024
	ds_read_b128 v[170:173], v149 offset:2048
	ds_read_b128 v[174:177], v149 offset:3072
	ds_read_b128 v[178:181], v149 offset:4096
	ds_read_b128 v[182:185], v149 offset:5120
	ds_read_b128 v[186:189], v149 offset:6144
	ds_read_b128 v[190:193], v149 offset:7168
	global_load_lds_dwordx4 v[198:199], off
	v_lshl_add_u64 v[198:199], s[10:11], 0, v[140:141]
	s_add_i32 m0, s24, 0xe000
	s_nop 0
	global_load_lds_dwordx4 v[198:199], off
	s_waitcnt lgkmcnt(8)
	s_barrier
	s_waitcnt lgkmcnt(0)
	s_setprio 1
	s_waitcnt lgkmcnt(0)
	v_mfma_f32_16x16x32_bf16 v[126:129], v[142:145], v[162:165], v[126:129]
	v_mfma_f32_16x16x32_bf16 v[122:125], v[154:157], v[162:165], v[122:125]
	v_mfma_f32_16x16x32_bf16 v[110:113], v[142:145], v[170:173], v[110:113]
	v_mfma_f32_16x16x32_bf16 v[106:109], v[154:157], v[170:173], v[106:109]
	v_mfma_f32_16x16x32_bf16 v[94:97], v[142:145], v[178:181], v[94:97]
	v_mfma_f32_16x16x32_bf16 v[90:93], v[154:157], v[178:181], v[90:93]
	v_mfma_f32_16x16x32_bf16 v[78:81], v[142:145], v[186:189], v[78:81]
	v_mfma_f32_16x16x32_bf16 v[74:77], v[154:157], v[186:189], v[74:77]
	v_mfma_f32_16x16x32_bf16 v[126:129], v[150:153], v[166:169], v[126:129]
	v_mfma_f32_16x16x32_bf16 v[122:125], v[158:161], v[166:169], v[122:125]
	v_mfma_f32_16x16x32_bf16 v[110:113], v[150:153], v[174:177], v[110:113]
	v_mfma_f32_16x16x32_bf16 v[106:109], v[158:161], v[174:177], v[106:109]
	v_mfma_f32_16x16x32_bf16 v[94:97], v[150:153], v[182:185], v[94:97]
	v_mfma_f32_16x16x32_bf16 v[90:93], v[158:161], v[182:185], v[90:93]
	v_mfma_f32_16x16x32_bf16 v[78:81], v[150:153], v[190:193], v[78:81]
	v_mfma_f32_16x16x32_bf16 v[74:77], v[158:161], v[190:193], v[74:77]
	s_setprio 0
	s_barrier
	s_add_i32 s43, 0, 0x14000
	s_add_i32 s10, s42, s23
	s_mov_b32 m0, s10
	ds_read_b128 v[198:201], v131 offset:16384
	ds_read_b128 v[202:205], v131 offset:17408
	ds_read_b128 v[206:209], v131 offset:18432
	ds_read_b128 v[210:213], v131 offset:19456
	global_load_lds_dwordx4 v134, s[14:15]
	s_add_i32 m0, s10, 0x2000
	s_nop 0
	global_load_lds_dwordx4 v130, s[14:15]
	s_barrier
	s_waitcnt lgkmcnt(0)
	s_setprio 1
	s_waitcnt lgkmcnt(0)
	v_mfma_f32_16x16x32_bf16 v[118:121], v[198:201], v[162:165], v[118:121]
	v_mfma_f32_16x16x32_bf16 v[114:117], v[206:209], v[162:165], v[114:117]
	v_mfma_f32_16x16x32_bf16 v[102:105], v[198:201], v[170:173], v[102:105]
	v_mfma_f32_16x16x32_bf16 v[98:101], v[206:209], v[170:173], v[98:101]
	v_mfma_f32_16x16x32_bf16 v[86:89], v[198:201], v[178:181], v[86:89]
	v_mfma_f32_16x16x32_bf16 v[82:85], v[206:209], v[178:181], v[82:85]
	v_mfma_f32_16x16x32_bf16 v[70:73], v[198:201], v[186:189], v[70:73]
	v_mfma_f32_16x16x32_bf16 v[66:69], v[206:209], v[186:189], v[66:69]
	v_mfma_f32_16x16x32_bf16 v[118:121], v[202:205], v[166:169], v[118:121]
	v_mfma_f32_16x16x32_bf16 v[114:117], v[210:213], v[166:169], v[114:117]
	v_mfma_f32_16x16x32_bf16 v[102:105], v[202:205], v[174:177], v[102:105]
	v_mfma_f32_16x16x32_bf16 v[98:101], v[210:213], v[174:177], v[98:101]
	v_mfma_f32_16x16x32_bf16 v[86:89], v[202:205], v[182:185], v[86:89]
	v_mfma_f32_16x16x32_bf16 v[82:85], v[210:213], v[182:185], v[82:85]
	v_mfma_f32_16x16x32_bf16 v[70:73], v[202:205], v[190:193], v[70:73]
	v_mfma_f32_16x16x32_bf16 v[66:69], v[210:213], v[190:193], v[66:69]
	s_setprio 0
	s_mov_b32 m0, s24
	v_lshl_add_u64 v[218:219], s[16:17], 0, v[136:137]
	s_barrier
	ds_read_b128 v[162:165], v149 offset:16384
	ds_read_b128 v[166:169], v149 offset:17408
	ds_read_b128 v[170:173], v149 offset:18432
	ds_read_b128 v[174:177], v149 offset:19456
	ds_read_b128 v[178:181], v149 offset:20480
	ds_read_b128 v[182:185], v149 offset:21504
	ds_read_b128 v[186:189], v149 offset:22528
	ds_read_b128 v[190:193], v149 offset:23552
	global_load_lds_dwordx4 v[218:219], off
	v_lshl_add_u64 v[220:221], s[16:17], 0, v[132:133]
	s_mov_b32 m0, s25
	s_nop 0
	global_load_lds_dwordx4 v[220:221], off
	s_barrier
	s_waitcnt lgkmcnt(0)
	s_setprio 1
	s_waitcnt lgkmcnt(0)
	v_mfma_f32_16x16x32_bf16 v[62:65], v[142:145], v[162:165], v[62:65]
	v_mfma_f32_16x16x32_bf16 v[58:61], v[154:157], v[162:165], v[58:61]
	v_mfma_f32_16x16x32_bf16 v[44:47], v[142:145], v[170:173], v[44:47]
	v_mfma_f32_16x16x32_bf16 v[40:43], v[154:157], v[170:173], v[40:43]
	v_mfma_f32_16x16x32_bf16 v[28:31], v[142:145], v[178:181], v[28:31]
	v_mfma_f32_16x16x32_bf16 v[24:27], v[154:157], v[178:181], v[24:27]
	v_mfma_f32_16x16x32_bf16 v[12:15], v[142:145], v[186:189], v[12:15]
	v_mfma_f32_16x16x32_bf16 v[8:11], v[154:157], v[186:189], v[8:11]
	v_mfma_f32_16x16x32_bf16 v[62:65], v[150:153], v[166:169], v[62:65]
	v_mfma_f32_16x16x32_bf16 v[58:61], v[158:161], v[166:169], v[58:61]
	v_mfma_f32_16x16x32_bf16 v[44:47], v[150:153], v[174:177], v[44:47]
	v_mfma_f32_16x16x32_bf16 v[40:43], v[158:161], v[174:177], v[40:43]
	v_mfma_f32_16x16x32_bf16 v[28:31], v[150:153], v[182:185], v[28:31]
	v_mfma_f32_16x16x32_bf16 v[24:27], v[158:161], v[182:185], v[24:27]
	v_mfma_f32_16x16x32_bf16 v[12:15], v[150:153], v[190:193], v[12:15]
	v_mfma_f32_16x16x32_bf16 v[8:11], v[158:161], v[190:193], v[8:11]
	s_setprio 0
	s_barrier
	s_add_u32 s10, s14, 0x30000
	s_addc_u32 s11, s15, 0
	s_add_i32 s42, s43, s23
	s_mov_b32 m0, s42
	s_nop 0
	global_load_lds_dwordx4 v134, s[10:11]
	s_add_i32 m0, s42, 0x2000
	s_nop 0
	global_load_lds_dwordx4 v130, s[10:11]
	s_waitcnt vmcnt(6)
	s_barrier
	s_setprio 1
	v_mfma_f32_16x16x32_bf16 v[54:57], v[198:201], v[162:165], v[54:57]
	v_mfma_f32_16x16x32_bf16 v[50:53], v[206:209], v[162:165], v[50:53]
	v_mfma_f32_16x16x32_bf16 v[36:39], v[198:201], v[170:173], v[36:39]
	v_mfma_f32_16x16x32_bf16 v[32:35], v[206:209], v[170:173], v[32:35]
	v_mfma_f32_16x16x32_bf16 v[20:23], v[198:201], v[178:181], v[20:23]
	v_mfma_f32_16x16x32_bf16 v[16:19], v[206:209], v[178:181], v[16:19]
	v_mfma_f32_16x16x32_bf16 v[4:7], v[198:201], v[186:189], v[4:7]
	v_mfma_f32_16x16x32_bf16 v[0:3], v[206:209], v[186:189], v[0:3]
	v_mfma_f32_16x16x32_bf16 v[54:57], v[202:205], v[166:169], v[54:57]
	v_mfma_f32_16x16x32_bf16 v[50:53], v[210:213], v[166:169], v[50:53]
	v_mfma_f32_16x16x32_bf16 v[36:39], v[202:205], v[174:177], v[36:39]
	v_mfma_f32_16x16x32_bf16 v[32:35], v[210:213], v[174:177], v[32:35]
	v_mfma_f32_16x16x32_bf16 v[20:23], v[202:205], v[182:185], v[20:23]
	v_mfma_f32_16x16x32_bf16 v[16:19], v[210:213], v[182:185], v[16:19]
	v_mfma_f32_16x16x32_bf16 v[4:7], v[202:205], v[190:193], v[4:7]
	v_mfma_f32_16x16x32_bf16 v[0:3], v[210:213], v[190:193], v[0:3]
	s_setprio 0
	s_add_i32 s42, 0, 0x18000
	s_barrier
	ds_read_b128 v[142:145], v131 offset:32768
	ds_read_b128 v[150:153], v131 offset:33792
	ds_read_b128 v[154:157], v131 offset:34816
	ds_read_b128 v[158:161], v131 offset:35840
	s_add_u32 s10, s16, 0x30000
	s_addc_u32 s11, s17, 0
	s_mov_b32 m0, s26
	ds_read_b128 v[162:165], v149 offset:32768
	ds_read_b128 v[166:169], v149 offset:33792
	ds_read_b128 v[170:173], v149 offset:34816
	ds_read_b128 v[174:177], v149 offset:35840
	ds_read_b128 v[178:181], v149 offset:36864
	ds_read_b128 v[182:185], v149 offset:37888
	ds_read_b128 v[186:189], v149 offset:38912
	ds_read_b128 v[190:193], v149 offset:39936
	global_load_lds_dwordx4 v136, s[10:11]
	s_mov_b32 m0, s27
	s_nop 0
	global_load_lds_dwordx4 v132, s[10:11]
	s_waitcnt lgkmcnt(8)
	s_barrier
	s_waitcnt lgkmcnt(0)
	s_setprio 1
	s_waitcnt lgkmcnt(0)
	v_mfma_f32_16x16x32_bf16 v[126:129], v[142:145], v[162:165], v[126:129]
	v_mfma_f32_16x16x32_bf16 v[122:125], v[154:157], v[162:165], v[122:125]
	v_mfma_f32_16x16x32_bf16 v[110:113], v[142:145], v[170:173], v[110:113]
	v_mfma_f32_16x16x32_bf16 v[106:109], v[154:157], v[170:173], v[106:109]
	v_mfma_f32_16x16x32_bf16 v[94:97], v[142:145], v[178:181], v[94:97]
	v_mfma_f32_16x16x32_bf16 v[90:93], v[154:157], v[178:181], v[90:93]
	v_mfma_f32_16x16x32_bf16 v[78:81], v[142:145], v[186:189], v[78:81]
	v_mfma_f32_16x16x32_bf16 v[74:77], v[154:157], v[186:189], v[74:77]
	v_mfma_f32_16x16x32_bf16 v[126:129], v[150:153], v[166:169], v[126:129]
	v_mfma_f32_16x16x32_bf16 v[122:125], v[158:161], v[166:169], v[122:125]
	v_mfma_f32_16x16x32_bf16 v[110:113], v[150:153], v[174:177], v[110:113]
	v_mfma_f32_16x16x32_bf16 v[106:109], v[158:161], v[174:177], v[106:109]
	v_mfma_f32_16x16x32_bf16 v[94:97], v[150:153], v[182:185], v[94:97]
	v_mfma_f32_16x16x32_bf16 v[90:93], v[158:161], v[182:185], v[90:93]
	v_mfma_f32_16x16x32_bf16 v[78:81], v[150:153], v[190:193], v[78:81]
	v_mfma_f32_16x16x32_bf16 v[74:77], v[158:161], v[190:193], v[74:77]
	s_setprio 0
	s_barrier
	s_add_i32 s16, 0, 0x1c000
	s_add_i32 s10, s42, s23
	s_add_u32 s72, s14, s66
	s_addc_u32 s73, s15, s67
	s_mov_b32 m0, s10
	ds_read_b128 v[198:201], v131 offset:49152
	ds_read_b128 v[202:205], v131 offset:50176
	ds_read_b128 v[206:209], v131 offset:51200
	ds_read_b128 v[210:213], v131 offset:52224
	global_load_lds_dwordx4 v134, s[72:73]
	s_add_i32 m0, s10, 0x2000
	s_nop 0
	global_load_lds_dwordx4 v130, s[72:73]
	s_barrier
	s_waitcnt lgkmcnt(0)
	s_setprio 1
	s_waitcnt lgkmcnt(0)
	v_mfma_f32_16x16x32_bf16 v[118:121], v[198:201], v[162:165], v[118:121]
	v_mfma_f32_16x16x32_bf16 v[114:117], v[206:209], v[162:165], v[114:117]
	v_mfma_f32_16x16x32_bf16 v[102:105], v[198:201], v[170:173], v[102:105]
	v_mfma_f32_16x16x32_bf16 v[98:101], v[206:209], v[170:173], v[98:101]
	v_mfma_f32_16x16x32_bf16 v[86:89], v[198:201], v[178:181], v[86:89]
	v_mfma_f32_16x16x32_bf16 v[82:85], v[206:209], v[178:181], v[82:85]
	v_mfma_f32_16x16x32_bf16 v[70:73], v[198:201], v[186:189], v[70:73]
	v_mfma_f32_16x16x32_bf16 v[66:69], v[206:209], v[186:189], v[66:69]
	v_mfma_f32_16x16x32_bf16 v[118:121], v[202:205], v[166:169], v[118:121]
	v_mfma_f32_16x16x32_bf16 v[114:117], v[210:213], v[166:169], v[114:117]
	v_mfma_f32_16x16x32_bf16 v[102:105], v[202:205], v[174:177], v[102:105]
	v_mfma_f32_16x16x32_bf16 v[98:101], v[210:213], v[174:177], v[98:101]
	v_mfma_f32_16x16x32_bf16 v[86:89], v[202:205], v[182:185], v[86:89]
	v_mfma_f32_16x16x32_bf16 v[82:85], v[210:213], v[182:185], v[82:85]
	v_mfma_f32_16x16x32_bf16 v[70:73], v[202:205], v[190:193], v[70:73]
	v_mfma_f32_16x16x32_bf16 v[66:69], v[210:213], v[190:193], v[66:69]
	s_setprio 0
	s_mov_b32 m0, s28
	v_lshl_add_u64 v[214:215], v[218:219], 0, s[66:67]
	s_barrier
	ds_read_b128 v[162:165], v149 offset:49152
	ds_read_b128 v[166:169], v149 offset:50176
	ds_read_b128 v[170:173], v149 offset:51200
	ds_read_b128 v[174:177], v149 offset:52224
	ds_read_b128 v[178:181], v149 offset:53248
	ds_read_b128 v[182:185], v149 offset:54272
	ds_read_b128 v[186:189], v149 offset:55296
	ds_read_b128 v[190:193], v149 offset:56320
	global_load_lds_dwordx4 v[214:215], off
	v_lshl_add_u64 v[214:215], v[220:221], 0, s[66:67]
	s_mov_b32 m0, s29
	s_nop 0
	global_load_lds_dwordx4 v[214:215], off
	s_barrier
	s_waitcnt lgkmcnt(0)
	s_setprio 1
	s_waitcnt lgkmcnt(0)
	v_mfma_f32_16x16x32_bf16 v[62:65], v[142:145], v[162:165], v[62:65]
	v_mfma_f32_16x16x32_bf16 v[58:61], v[154:157], v[162:165], v[58:61]
	v_mfma_f32_16x16x32_bf16 v[44:47], v[142:145], v[170:173], v[44:47]
	v_mfma_f32_16x16x32_bf16 v[40:43], v[154:157], v[170:173], v[40:43]
	v_mfma_f32_16x16x32_bf16 v[28:31], v[142:145], v[178:181], v[28:31]
	v_mfma_f32_16x16x32_bf16 v[24:27], v[154:157], v[178:181], v[24:27]
	v_mfma_f32_16x16x32_bf16 v[12:15], v[142:145], v[186:189], v[12:15]
	v_mfma_f32_16x16x32_bf16 v[8:11], v[154:157], v[186:189], v[8:11]
	v_mfma_f32_16x16x32_bf16 v[62:65], v[150:153], v[166:169], v[62:65]
	v_mfma_f32_16x16x32_bf16 v[58:61], v[158:161], v[166:169], v[58:61]
	v_mfma_f32_16x16x32_bf16 v[44:47], v[150:153], v[174:177], v[44:47]
	v_mfma_f32_16x16x32_bf16 v[40:43], v[158:161], v[174:177], v[40:43]
	v_mfma_f32_16x16x32_bf16 v[28:31], v[150:153], v[182:185], v[28:31]
	v_mfma_f32_16x16x32_bf16 v[24:27], v[158:161], v[182:185], v[24:27]
	v_mfma_f32_16x16x32_bf16 v[12:15], v[150:153], v[190:193], v[12:15]
	v_mfma_f32_16x16x32_bf16 v[8:11], v[158:161], v[190:193], v[8:11]
	s_setprio 0
	s_barrier
	s_add_u32 s10, s14, 0x30080
	s_addc_u32 s11, s15, 0
	s_add_i32 s14, s16, s23
	s_mov_b32 m0, s14
	s_nop 0
	global_load_lds_dwordx4 v134, s[10:11]
	s_add_i32 m0, s14, 0x2000
	s_nop 0
	global_load_lds_dwordx4 v130, s[10:11]
	s_waitcnt vmcnt(6)
	s_barrier
	s_setprio 1
	v_mfma_f32_16x16x32_bf16 v[54:57], v[198:201], v[162:165], v[54:57]
	v_mfma_f32_16x16x32_bf16 v[50:53], v[206:209], v[162:165], v[50:53]
	v_mfma_f32_16x16x32_bf16 v[36:39], v[198:201], v[170:173], v[36:39]
	v_mfma_f32_16x16x32_bf16 v[32:35], v[206:209], v[170:173], v[32:35]
	v_mfma_f32_16x16x32_bf16 v[20:23], v[198:201], v[178:181], v[20:23]
	v_mfma_f32_16x16x32_bf16 v[16:19], v[206:209], v[178:181], v[16:19]
	v_mfma_f32_16x16x32_bf16 v[4:7], v[198:201], v[186:189], v[4:7]
	v_mfma_f32_16x16x32_bf16 v[0:3], v[206:209], v[186:189], v[0:3]
	v_mfma_f32_16x16x32_bf16 v[54:57], v[202:205], v[166:169], v[54:57]
	v_mfma_f32_16x16x32_bf16 v[50:53], v[210:213], v[166:169], v[50:53]
	v_mfma_f32_16x16x32_bf16 v[36:39], v[202:205], v[174:177], v[36:39]
	v_mfma_f32_16x16x32_bf16 v[32:35], v[210:213], v[174:177], v[32:35]
	v_mfma_f32_16x16x32_bf16 v[20:23], v[202:205], v[182:185], v[20:23]
	v_mfma_f32_16x16x32_bf16 v[16:19], v[210:213], v[182:185], v[16:19]
	v_mfma_f32_16x16x32_bf16 v[4:7], v[202:205], v[190:193], v[4:7]
	v_mfma_f32_16x16x32_bf16 v[0:3], v[210:213], v[190:193], v[0:3]
	s_setprio 0
	s_add_i32 s41, s41, 2
	s_add_u32 s39, s39, 0x100
	s_addc_u32 s40, s40, 0
	s_cmp_gt_u32 s41, 9
	s_mov_b64 s[10:11], s[12:13]
	s_barrier
	s_cbranch_scc0 .LBB0_822
	v_lshl_add_u32 v142, s38, 8, v146
	v_ashrrev_i32_e32 v143, 31, v142
	v_lshlrev_b64 v[144:145], 14, v[142:143]
	v_mul_f32_e32 v143, 0x3d372713, v126
	v_mul_f32_e32 v143, v126, v143
	v_fma_f32 v143, v126, v143, v126
	v_mul_f32_e32 v143, 0xbfcc422a, v143
	v_mul_f32_e32 v143, 0x3fb8aa3b, v143
	v_exp_f32_e32 v150, v143
	v_mul_f32_e32 v143, 0x3d372713, v122
	v_mul_f32_e32 v143, v122, v143
	v_fma_f32 v143, v122, v143, v122
	v_mul_f32_e32 v143, 0xbfcc422a, v143
	v_mul_f32_e32 v143, 0x3fb8aa3b, v143
	v_exp_f32_e32 v152, v143
	v_mul_f32_e32 v143, 0x3d372713, v127
	v_mul_f32_e32 v143, v127, v143
	v_fma_f32 v143, v127, v143, v127
	v_mul_f32_e32 v143, 0xbfcc422a, v143
	v_mul_f32_e32 v143, 0x3fb8aa3b, v143
	v_exp_f32_e32 v151, v143
	v_lshl_or_b32 v154, s37, 8, v148
	s_lshl_b32 s10, s36, 4
	s_ashr_i32 s11, s10, 31
	v_pk_add_f32 v[150:151], v[150:151], 1.0 op_sel_hi:[1,0]
	s_lshl_b64 s[10:11], s[10:11], 1
	s_mov_b32 s36, s31
	s_mov_b32 s37, s35
	s_mov_b32 s38, s34
	v_rcp_f32_e32 v143, v151
	s_nop 0
	v_mul_f32_e32 v143, v127, v143
	s_nop 0
	v_rcp_f32_e32 v127, v150
	s_nop 0
	v_mul_f32_e32 v150, v126, v127
	v_mul_f32_e32 v126, 0x3d372713, v123
	v_mul_f32_e32 v126, v123, v126
	v_fma_f32 v126, v123, v126, v123
	v_mul_f32_e32 v126, 0xbfcc422a, v126
	v_mul_f32_e32 v126, 0x3fb8aa3b, v126
	v_exp_f32_e32 v153, v126
	v_cvt_pk_bf16_f32 v150, v150, v143
	v_pk_add_f32 v[126:127], v[152:153], 1.0 op_sel_hi:[1,0]
	s_nop 0
	s_nop 0
	v_rcp_f32_e32 v151, v127
	s_nop 0
	v_mul_f32_e32 v152, v123, v151
	s_nop 0
	v_rcp_f32_e32 v123, v126
	s_nop 0
	v_mul_f32_e32 v153, v122, v123
	v_mul_f32_e32 v123, 0x3d372713, v124
	v_mul_f32_e32 v123, v124, v123
	v_fma_f32 v123, v124, v123, v124
	v_mul_f32_e32 v123, 0xbfcc422a, v123
	v_mul_f32_e32 v123, 0x3fb8aa3b, v123
	v_mul_f32_e32 v122, 0x3d372713, v128
	v_exp_f32_e32 v126, v123
	v_mul_f32_e32 v123, 0x3d372713, v129
	v_mul_f32_e32 v122, v128, v122
	v_mul_f32_e32 v123, v129, v123
	v_fma_f32 v122, v128, v122, v128
	v_fma_f32 v123, v129, v123, v129
	v_mul_f32_e32 v122, 0xbfcc422a, v122
	v_mul_f32_e32 v123, 0xbfcc422a, v123
	v_mul_f32_e32 v122, 0x3fb8aa3b, v122
	v_mul_f32_e32 v123, 0x3fb8aa3b, v123
	v_exp_f32_e32 v122, v122
	v_exp_f32_e32 v123, v123
	v_cvt_pk_bf16_f32 v152, v153, v152
	v_pk_add_f32 v[122:123], v[122:123], 1.0 op_sel_hi:[1,0]
	s_nop 0
	s_nop 0
	v_rcp_f32_e32 v127, v123
	s_nop 0
	v_mul_f32_e32 v129, v129, v127
	s_nop 0
	v_rcp_f32_e32 v123, v122
	s_nop 0
	v_mul_f32_e32 v128, v128, v123
	v_mul_f32_e32 v122, 0x3d372713, v125
	v_mul_f32_e32 v122, v125, v122
	v_fma_f32 v122, v125, v122, v125
	v_mul_f32_e32 v122, 0xbfcc422a, v122
	v_mul_f32_e32 v122, 0x3fb8aa3b, v122
	v_exp_f32_e32 v127, v122
	s_nop 0
	v_pk_add_f32 v[122:123], v[126:127], 1.0 op_sel_hi:[1,0]
	s_nop 0
	s_nop 0
	v_rcp_f32_e32 v126, v123
	s_nop 0
	v_mul_f32_e32 v123, v125, v126
	s_nop 0
	v_ashrrev_i32_e32 v126, 4, v154
	v_ashrrev_i32_e32 v127, 31, v126
	v_rcp_f32_e32 v125, v122
	s_nop 0
	v_mul_f32_e32 v122, v124, v125
	v_lshlrev_b64 v[124:125], 9, v[126:127]
	v_mul_f32_e32 v127, 0x3d372713, v118
	v_cvt_pk_bf16_f32 v153, v122, v123
	v_lshl_add_u64 v[122:123], s[0:1], 0, v[144:145]
	v_mul_f32_e32 v127, v118, v127
	v_cvt_pk_bf16_f32 v151, v128, v129
	v_lshl_add_u64 v[128:129], v[122:123], 0, v[124:125]
	v_fma_f32 v127, v118, v127, v118
	v_lshl_add_u64 v[128:129], v[128:129], 0, s[10:11]
	v_mul_f32_e32 v127, 0xbfcc422a, v127
	v_lshl_add_u64 v[128:129], v[128:129], 0, v[48:49]
	v_mul_f32_e32 v127, 0x3fb8aa3b, v127
	global_store_dwordx4 v[128:129], v[150:153], off
	v_exp_f32_e32 v128, v127
	v_mul_f32_e32 v127, 0x3d372713, v114
	v_mul_f32_e32 v127, v114, v127
	v_fma_f32 v127, v114, v127, v114
	v_mul_f32_e32 v127, 0xbfcc422a, v127
	v_mul_f32_e32 v127, 0x3fb8aa3b, v127
	v_exp_f32_e32 v144, v127
	v_mul_f32_e32 v127, 0x3d372713, v119
	v_mul_f32_e32 v127, v119, v127
	v_fma_f32 v127, v119, v127, v119
	v_mul_f32_e32 v127, 0xbfcc422a, v127
	v_mul_f32_e32 v127, 0x3fb8aa3b, v127
	v_exp_f32_e32 v129, v127
	s_nop 0
	v_pk_add_f32 v[128:129], v[128:129], 1.0 op_sel_hi:[1,0]
	s_nop 0
	s_nop 0
	v_rcp_f32_e32 v127, v129
	s_nop 0
	v_mul_f32_e32 v127, v119, v127
	s_nop 0
	v_rcp_f32_e32 v119, v128
	s_nop 0
	v_mul_f32_e32 v128, v118, v119
	v_mul_f32_e32 v118, 0x3d372713, v115
	v_mul_f32_e32 v118, v115, v118
	v_fma_f32 v118, v115, v118, v115
	v_mul_f32_e32 v118, 0xbfcc422a, v118
	v_mul_f32_e32 v118, 0x3fb8aa3b, v118
	v_exp_f32_e32 v145, v118
	s_nop 0
	v_pk_add_f32 v[118:119], v[144:145], 1.0 op_sel_hi:[1,0]
	s_nop 0
	s_nop 0
	v_rcp_f32_e32 v129, v119
	s_nop 0
	v_mul_f32_e32 v129, v115, v129
	s_nop 0
	v_rcp_f32_e32 v115, v118
	s_nop 0
	v_mul_f32_e32 v143, v114, v115
	v_mul_f32_e32 v115, 0x3d372713, v116
	v_mul_f32_e32 v115, v116, v115
	v_fma_f32 v115, v116, v115, v116
	v_mul_f32_e32 v115, 0xbfcc422a, v115
	v_mul_f32_e32 v115, 0x3fb8aa3b, v115
	v_mul_f32_e32 v114, 0x3d372713, v120
	v_exp_f32_e32 v118, v115
	v_mul_f32_e32 v115, 0x3d372713, v121
	v_mul_f32_e32 v114, v120, v114
	v_mul_f32_e32 v115, v121, v115
	v_fma_f32 v114, v120, v114, v120
	v_fma_f32 v115, v121, v115, v121
	v_mul_f32_e32 v114, 0xbfcc422a, v114
	v_mul_f32_e32 v115, 0xbfcc422a, v115
	v_mul_f32_e32 v114, 0x3fb8aa3b, v114
	v_mul_f32_e32 v115, 0x3fb8aa3b, v115
	v_exp_f32_e32 v114, v114
	v_exp_f32_e32 v115, v115
	s_nop 0
	v_pk_add_f32 v[114:115], v[114:115], 1.0 op_sel_hi:[1,0]
	s_nop 0
	s_nop 0
	v_rcp_f32_e32 v119, v115
	s_nop 0
	v_mul_f32_e32 v121, v121, v119
	s_nop 0
	v_rcp_f32_e32 v115, v114
	s_nop 0
	v_mul_f32_e32 v120, v120, v115
	v_mul_f32_e32 v114, 0x3d372713, v117
	v_mul_f32_e32 v114, v117, v114
	v_fma_f32 v114, v117, v114, v117
	v_mul_f32_e32 v114, 0xbfcc422a, v114
	v_mul_f32_e32 v114, 0x3fb8aa3b, v114
	v_exp_f32_e32 v119, v114
	s_nop 0
	v_pk_add_f32 v[114:115], v[118:119], 1.0 op_sel_hi:[1,0]
	s_nop 0
	s_nop 0
	v_rcp_f32_e32 v118, v115
	s_nop 0
	v_mul_f32_e32 v115, v117, v118
	s_nop 0
	v_rcp_f32_e32 v117, v114
	s_nop 0
	v_mul_f32_e32 v119, v116, v117
	v_or_b32_e32 v114, 8, v126
	v_cvt_pk_bf16_f32 v119, v119, v115
	v_ashrrev_i32_e32 v115, 31, v114
	v_lshlrev_b64 v[114:115], 9, v[114:115]
	v_cvt_pk_bf16_f32 v117, v120, v121
	v_lshl_add_u64 v[120:121], v[122:123], 0, v[114:115]
	v_lshl_add_u64 v[120:121], v[120:121], 0, s[10:11]
	v_cvt_pk_bf16_f32 v116, v128, v127
	v_cvt_pk_bf16_f32 v118, v143, v129
	v_lshl_add_u64 v[120:121], v[120:121], 0, v[48:49]
	global_store_dwordx4 v[120:121], v[116:119], off
	s_nop 1
	v_mul_f32_e32 v119, 0x3d372713, v106
	v_mul_f32_e32 v119, v106, v119
	v_fma_f32 v119, v106, v119, v106
	v_mul_f32_e32 v119, 0xbfcc422a, v119
	v_mul_f32_e32 v119, 0x3fb8aa3b, v119
	v_mul_f32_e32 v118, 0x3d372713, v110
	v_exp_f32_e32 v120, v119
	v_mul_f32_e32 v119, 0x3d372713, v111
	v_mul_f32_e32 v118, v110, v118
	v_mul_f32_e32 v119, v111, v119
	v_fma_f32 v118, v110, v118, v110
	v_fma_f32 v119, v111, v119, v111
	v_mul_f32_e32 v118, 0xbfcc422a, v118
	v_mul_f32_e32 v119, 0xbfcc422a, v119
	v_mul_f32_e32 v118, 0x3fb8aa3b, v118
	v_mul_f32_e32 v119, 0x3fb8aa3b, v119
	v_exp_f32_e32 v118, v118
	v_exp_f32_e32 v119, v119
	v_or_b32_e32 v116, 16, v142
	v_ashrrev_i32_e32 v117, 31, v116
	v_lshlrev_b64 v[116:117], 14, v[116:117]
	v_pk_add_f32 v[118:119], v[118:119], 1.0 op_sel_hi:[1,0]
	s_nop 0
	s_nop 0
	v_rcp_f32_e32 v121, v119
	s_nop 0
	v_mul_f32_e32 v119, v111, v121
	s_nop 0
	v_rcp_f32_e32 v111, v118
	s_nop 0
	v_mul_f32_e32 v118, v110, v111
	v_mul_f32_e32 v110, 0x3d372713, v107
	v_mul_f32_e32 v110, v107, v110
	v_fma_f32 v110, v107, v110, v107
	v_mul_f32_e32 v110, 0xbfcc422a, v110
	v_mul_f32_e32 v110, 0x3fb8aa3b, v110
	v_exp_f32_e32 v121, v110
	s_nop 0
	v_pk_add_f32 v[110:111], v[120:121], 1.0 op_sel_hi:[1,0]
	s_nop 0
	s_nop 0
	v_rcp_f32_e32 v120, v111
	s_nop 0
	v_mul_f32_e32 v120, v107, v120
	s_nop 0
	v_rcp_f32_e32 v107, v110
	s_nop 0
	v_mul_f32_e32 v121, v106, v107
	v_mul_f32_e32 v107, 0x3d372713, v108
	v_mul_f32_e32 v107, v108, v107
	v_fma_f32 v107, v108, v107, v108
	v_mul_f32_e32 v107, 0xbfcc422a, v107
	v_mul_f32_e32 v107, 0x3fb8aa3b, v107
	v_mul_f32_e32 v106, 0x3d372713, v112
	v_exp_f32_e32 v110, v107
	v_mul_f32_e32 v107, 0x3d372713, v113
	v_mul_f32_e32 v106, v112, v106
	v_mul_f32_e32 v107, v113, v107
	v_fma_f32 v106, v112, v106, v112
	v_fma_f32 v107, v113, v107, v113
	v_mul_f32_e32 v106, 0xbfcc422a, v106
	v_mul_f32_e32 v107, 0xbfcc422a, v107
	v_mul_f32_e32 v106, 0x3fb8aa3b, v106
	v_mul_f32_e32 v107, 0x3fb8aa3b, v107
	v_exp_f32_e32 v106, v106
	v_exp_f32_e32 v107, v107
	s_nop 0
	v_pk_add_f32 v[106:107], v[106:107], 1.0 op_sel_hi:[1,0]
	s_nop 0
	s_nop 0
	v_rcp_f32_e32 v111, v107
	s_nop 0
	v_mul_f32_e32 v113, v113, v111
	s_nop 0
	v_rcp_f32_e32 v107, v106
	s_nop 0
	v_mul_f32_e32 v112, v112, v107
	v_mul_f32_e32 v106, 0x3d372713, v109
	v_mul_f32_e32 v106, v109, v106
	v_fma_f32 v106, v109, v106, v109
	v_mul_f32_e32 v106, 0xbfcc422a, v106
	v_mul_f32_e32 v106, 0x3fb8aa3b, v106
	v_exp_f32_e32 v111, v106
	s_nop 0
	v_pk_add_f32 v[106:107], v[110:111], 1.0 op_sel_hi:[1,0]
	s_nop 0
	s_nop 0
	v_rcp_f32_e32 v110, v107
	s_nop 0
	v_mul_f32_e32 v107, v109, v110
	s_nop 0
	v_rcp_f32_e32 v109, v106
	s_nop 0
	v_mul_f32_e32 v106, v108, v109
	v_cvt_pk_bf16_f32 v111, v106, v107
	v_lshl_add_u64 v[106:107], s[0:1], 0, v[116:117]
	v_cvt_pk_bf16_f32 v109, v112, v113
	v_lshl_add_u64 v[112:113], v[106:107], 0, v[124:125]
	v_lshl_add_u64 v[112:113], v[112:113], 0, s[10:11]
	v_cvt_pk_bf16_f32 v108, v118, v119
	v_cvt_pk_bf16_f32 v110, v121, v120
	v_lshl_add_u64 v[112:113], v[112:113], 0, v[48:49]
	global_store_dwordx4 v[112:113], v[108:111], off
	s_nop 1
	v_mul_f32_e32 v109, 0x3d372713, v98
	v_mul_f32_e32 v109, v98, v109
	v_fma_f32 v109, v98, v109, v98
	v_mul_f32_e32 v109, 0xbfcc422a, v109
	v_mul_f32_e32 v109, 0x3fb8aa3b, v109
	v_mul_f32_e32 v108, 0x3d372713, v102
	v_exp_f32_e32 v110, v109
	v_mul_f32_e32 v109, 0x3d372713, v103
	v_mul_f32_e32 v108, v102, v108
	v_mul_f32_e32 v109, v103, v109
	v_fma_f32 v108, v102, v108, v102
	v_fma_f32 v109, v103, v109, v103
	v_mul_f32_e32 v108, 0xbfcc422a, v108
	v_mul_f32_e32 v109, 0xbfcc422a, v109
	v_mul_f32_e32 v108, 0x3fb8aa3b, v108
	v_mul_f32_e32 v109, 0x3fb8aa3b, v109
	v_exp_f32_e32 v108, v108
	v_exp_f32_e32 v109, v109
	s_nop 0
	v_pk_add_f32 v[108:109], v[108:109], 1.0 op_sel_hi:[1,0]
	s_nop 0
	s_nop 0
	v_rcp_f32_e32 v111, v109
	s_nop 0
	v_mul_f32_e32 v109, v103, v111
	s_nop 0
	v_rcp_f32_e32 v103, v108
	s_nop 0
	v_mul_f32_e32 v108, v102, v103
	v_mul_f32_e32 v102, 0x3d372713, v99
	v_mul_f32_e32 v102, v99, v102
	v_fma_f32 v102, v99, v102, v99
	v_mul_f32_e32 v102, 0xbfcc422a, v102
	v_mul_f32_e32 v102, 0x3fb8aa3b, v102
	v_exp_f32_e32 v111, v102
	s_nop 0
	v_pk_add_f32 v[102:103], v[110:111], 1.0 op_sel_hi:[1,0]
	s_nop 0
	s_nop 0
	v_rcp_f32_e32 v110, v103
	s_nop 0
	v_mul_f32_e32 v110, v99, v110
	s_nop 0
	v_rcp_f32_e32 v99, v102
	s_nop 0
	v_mul_f32_e32 v111, v98, v99
	v_mul_f32_e32 v99, 0x3d372713, v100
	v_mul_f32_e32 v99, v100, v99
	v_fma_f32 v99, v100, v99, v100
	v_mul_f32_e32 v99, 0xbfcc422a, v99
	v_mul_f32_e32 v99, 0x3fb8aa3b, v99
	v_mul_f32_e32 v98, 0x3d372713, v104
	v_exp_f32_e32 v102, v99
	v_mul_f32_e32 v99, 0x3d372713, v105
	v_mul_f32_e32 v98, v104, v98
	v_mul_f32_e32 v99, v105, v99
	v_fma_f32 v98, v104, v98, v104
	v_fma_f32 v99, v105, v99, v105
	v_mul_f32_e32 v98, 0xbfcc422a, v98
	v_mul_f32_e32 v99, 0xbfcc422a, v99
	v_mul_f32_e32 v98, 0x3fb8aa3b, v98
	v_mul_f32_e32 v99, 0x3fb8aa3b, v99
	v_exp_f32_e32 v98, v98
	v_exp_f32_e32 v99, v99
	s_nop 0
	v_pk_add_f32 v[98:99], v[98:99], 1.0 op_sel_hi:[1,0]
	s_nop 0
	s_nop 0
	v_rcp_f32_e32 v103, v99
	s_nop 0
	v_mul_f32_e32 v105, v105, v103
	s_nop 0
	v_rcp_f32_e32 v99, v98
	s_nop 0
	v_mul_f32_e32 v104, v104, v99
	v_mul_f32_e32 v98, 0x3d372713, v101
	v_mul_f32_e32 v98, v101, v98
	v_fma_f32 v98, v101, v98, v101
	v_mul_f32_e32 v98, 0xbfcc422a, v98
	v_mul_f32_e32 v98, 0x3fb8aa3b, v98
	v_exp_f32_e32 v103, v98
	s_nop 0
	v_pk_add_f32 v[98:99], v[102:103], 1.0 op_sel_hi:[1,0]
	s_nop 0
	s_nop 0
	v_rcp_f32_e32 v102, v99
	s_nop 0
	v_mul_f32_e32 v101, v101, v102
	s_nop 0
	v_rcp_f32_e32 v99, v98
	s_nop 0
	v_mul_f32_e32 v102, v100, v99
	v_cvt_pk_bf16_f32 v101, v102, v101
	v_lshl_add_u64 v[102:103], v[106:107], 0, v[114:115]
	v_lshl_add_u64 v[102:103], v[102:103], 0, s[10:11]
	v_cvt_pk_bf16_f32 v98, v108, v109
	v_cvt_pk_bf16_f32 v99, v104, v105
	v_cvt_pk_bf16_f32 v100, v111, v110
	v_lshl_add_u64 v[102:103], v[102:103], 0, v[48:49]
	global_store_dwordx4 v[102:103], v[98:101], off
	s_nop 1
	v_mul_f32_e32 v101, 0x3d372713, v90
	v_mul_f32_e32 v101, v90, v101
	v_fma_f32 v101, v90, v101, v90
	v_mul_f32_e32 v101, 0xbfcc422a, v101
	v_mul_f32_e32 v101, 0x3fb8aa3b, v101
	v_mul_f32_e32 v100, 0x3d372713, v94
	v_exp_f32_e32 v102, v101
	v_mul_f32_e32 v101, 0x3d372713, v95
	v_mul_f32_e32 v100, v94, v100
	v_mul_f32_e32 v101, v95, v101
	v_fma_f32 v100, v94, v100, v94
	v_fma_f32 v101, v95, v101, v95
	v_mul_f32_e32 v100, 0xbfcc422a, v100
	v_mul_f32_e32 v101, 0xbfcc422a, v101
	v_mul_f32_e32 v100, 0x3fb8aa3b, v100
	v_mul_f32_e32 v101, 0x3fb8aa3b, v101
	v_exp_f32_e32 v100, v100
	v_exp_f32_e32 v101, v101
	v_or_b32_e32 v98, 32, v142
	v_ashrrev_i32_e32 v99, 31, v98
	v_lshlrev_b64 v[98:99], 14, v[98:99]
	v_pk_add_f32 v[100:101], v[100:101], 1.0 op_sel_hi:[1,0]
	s_nop 0
	s_nop 0
	v_rcp_f32_e32 v103, v101
	s_nop 0
	v_mul_f32_e32 v101, v95, v103
	s_nop 0
	v_rcp_f32_e32 v95, v100
	s_nop 0
	v_mul_f32_e32 v100, v94, v95
	v_mul_f32_e32 v94, 0x3d372713, v91
	v_mul_f32_e32 v94, v91, v94
	v_fma_f32 v94, v91, v94, v91
	v_mul_f32_e32 v94, 0xbfcc422a, v94
	v_mul_f32_e32 v94, 0x3fb8aa3b, v94
	v_exp_f32_e32 v103, v94
	s_nop 0
	v_pk_add_f32 v[94:95], v[102:103], 1.0 op_sel_hi:[1,0]
	s_nop 0
	s_nop 0
	v_rcp_f32_e32 v102, v95
	s_nop 0
	v_mul_f32_e32 v102, v91, v102
	s_nop 0
	v_rcp_f32_e32 v91, v94
	s_nop 0
	v_mul_f32_e32 v103, v90, v91
	v_mul_f32_e32 v91, 0x3d372713, v92
	v_mul_f32_e32 v91, v92, v91
	v_fma_f32 v91, v92, v91, v92
	v_mul_f32_e32 v91, 0xbfcc422a, v91
	v_mul_f32_e32 v91, 0x3fb8aa3b, v91
	v_mul_f32_e32 v90, 0x3d372713, v96
	v_exp_f32_e32 v94, v91
	v_mul_f32_e32 v91, 0x3d372713, v97
	v_mul_f32_e32 v90, v96, v90
	v_mul_f32_e32 v91, v97, v91
	v_fma_f32 v90, v96, v90, v96
	v_fma_f32 v91, v97, v91, v97
	v_mul_f32_e32 v90, 0xbfcc422a, v90
	v_mul_f32_e32 v91, 0xbfcc422a, v91
	v_mul_f32_e32 v90, 0x3fb8aa3b, v90
	v_mul_f32_e32 v91, 0x3fb8aa3b, v91
	v_exp_f32_e32 v90, v90
	v_exp_f32_e32 v91, v91
	s_nop 0
	v_pk_add_f32 v[90:91], v[90:91], 1.0 op_sel_hi:[1,0]
	s_nop 0
	s_nop 0
	v_rcp_f32_e32 v95, v91
	s_nop 0
	v_mul_f32_e32 v97, v97, v95
	s_nop 0
	v_rcp_f32_e32 v91, v90
	s_nop 0
	v_mul_f32_e32 v96, v96, v91
	v_mul_f32_e32 v90, 0x3d372713, v93
	v_mul_f32_e32 v90, v93, v90
	v_fma_f32 v90, v93, v90, v93
	v_mul_f32_e32 v90, 0xbfcc422a, v90
	v_mul_f32_e32 v90, 0x3fb8aa3b, v90
	v_exp_f32_e32 v95, v90
	s_nop 0
	v_pk_add_f32 v[90:91], v[94:95], 1.0 op_sel_hi:[1,0]
	s_nop 0
	s_nop 0
	v_rcp_f32_e32 v94, v91
	s_nop 0
	v_mul_f32_e32 v91, v93, v94
	s_nop 0
	v_rcp_f32_e32 v93, v90
	s_nop 0
	v_mul_f32_e32 v90, v92, v93
	v_cvt_pk_bf16_f32 v95, v90, v91
	v_lshl_add_u64 v[90:91], s[0:1], 0, v[98:99]
	v_cvt_pk_bf16_f32 v93, v96, v97
	v_lshl_add_u64 v[96:97], v[90:91], 0, v[124:125]
	v_lshl_add_u64 v[96:97], v[96:97], 0, s[10:11]
	v_cvt_pk_bf16_f32 v92, v100, v101
	v_cvt_pk_bf16_f32 v94, v103, v102
	v_lshl_add_u64 v[96:97], v[96:97], 0, v[48:49]
	global_store_dwordx4 v[96:97], v[92:95], off
	s_nop 1
	v_mul_f32_e32 v93, 0x3d372713, v82
	v_mul_f32_e32 v93, v82, v93
	v_fma_f32 v93, v82, v93, v82
	v_mul_f32_e32 v93, 0xbfcc422a, v93
	v_mul_f32_e32 v93, 0x3fb8aa3b, v93
	v_mul_f32_e32 v92, 0x3d372713, v86
	v_exp_f32_e32 v94, v93
	v_mul_f32_e32 v93, 0x3d372713, v87
	v_mul_f32_e32 v92, v86, v92
	v_mul_f32_e32 v93, v87, v93
	v_fma_f32 v92, v86, v92, v86
	v_fma_f32 v93, v87, v93, v87
	v_mul_f32_e32 v92, 0xbfcc422a, v92
	v_mul_f32_e32 v93, 0xbfcc422a, v93
	v_mul_f32_e32 v92, 0x3fb8aa3b, v92
	v_mul_f32_e32 v93, 0x3fb8aa3b, v93
	v_exp_f32_e32 v92, v92
	v_exp_f32_e32 v93, v93
	s_nop 0
	v_pk_add_f32 v[92:93], v[92:93], 1.0 op_sel_hi:[1,0]
	s_nop 0
	s_nop 0
	v_rcp_f32_e32 v95, v93
	s_nop 0
	v_mul_f32_e32 v93, v87, v95
	s_nop 0
	v_rcp_f32_e32 v87, v92
	s_nop 0
	v_mul_f32_e32 v92, v86, v87
	v_mul_f32_e32 v86, 0x3d372713, v83
	v_mul_f32_e32 v86, v83, v86
	v_fma_f32 v86, v83, v86, v83
	v_mul_f32_e32 v86, 0xbfcc422a, v86
	v_mul_f32_e32 v86, 0x3fb8aa3b, v86
	v_exp_f32_e32 v95, v86
	s_nop 0
	v_pk_add_f32 v[86:87], v[94:95], 1.0 op_sel_hi:[1,0]
	s_nop 0
	s_nop 0
	v_rcp_f32_e32 v94, v87
	s_nop 0
	v_mul_f32_e32 v94, v83, v94
	s_nop 0
	v_rcp_f32_e32 v83, v86
	s_nop 0
	v_mul_f32_e32 v95, v82, v83
	v_mul_f32_e32 v83, 0x3d372713, v84
	v_mul_f32_e32 v83, v84, v83
	v_fma_f32 v83, v84, v83, v84
	v_mul_f32_e32 v83, 0xbfcc422a, v83
	v_mul_f32_e32 v83, 0x3fb8aa3b, v83
	v_mul_f32_e32 v82, 0x3d372713, v88
	v_exp_f32_e32 v86, v83
	v_mul_f32_e32 v83, 0x3d372713, v89
	v_mul_f32_e32 v82, v88, v82
	v_mul_f32_e32 v83, v89, v83
	v_fma_f32 v82, v88, v82, v88
	v_fma_f32 v83, v89, v83, v89
	v_mul_f32_e32 v82, 0xbfcc422a, v82
	v_mul_f32_e32 v83, 0xbfcc422a, v83
	v_mul_f32_e32 v82, 0x3fb8aa3b, v82
	v_mul_f32_e32 v83, 0x3fb8aa3b, v83
	v_exp_f32_e32 v82, v82
	v_exp_f32_e32 v83, v83
	s_nop 0
	v_pk_add_f32 v[82:83], v[82:83], 1.0 op_sel_hi:[1,0]
	s_nop 0
	s_nop 0
	v_rcp_f32_e32 v87, v83
	s_nop 0
	v_mul_f32_e32 v89, v89, v87
	s_nop 0
	v_rcp_f32_e32 v83, v82
	s_nop 0
	v_mul_f32_e32 v88, v88, v83
	v_mul_f32_e32 v82, 0x3d372713, v85
	v_mul_f32_e32 v82, v85, v82
	v_fma_f32 v82, v85, v82, v85
	v_mul_f32_e32 v82, 0xbfcc422a, v82
	v_mul_f32_e32 v82, 0x3fb8aa3b, v82
	v_exp_f32_e32 v87, v82
	s_nop 0
	v_pk_add_f32 v[82:83], v[86:87], 1.0 op_sel_hi:[1,0]
	s_nop 0
	s_nop 0
	v_rcp_f32_e32 v86, v83
	s_nop 0
	v_mul_f32_e32 v85, v85, v86
	s_nop 0
	v_rcp_f32_e32 v83, v82
	s_nop 0
	v_mul_f32_e32 v86, v84, v83
	v_cvt_pk_bf16_f32 v85, v86, v85
	v_lshl_add_u64 v[86:87], v[90:91], 0, v[114:115]
	v_lshl_add_u64 v[86:87], v[86:87], 0, s[10:11]
	v_cvt_pk_bf16_f32 v82, v92, v93
	v_cvt_pk_bf16_f32 v83, v88, v89
	v_cvt_pk_bf16_f32 v84, v95, v94
	v_lshl_add_u64 v[86:87], v[86:87], 0, v[48:49]
	global_store_dwordx4 v[86:87], v[82:85], off
	s_nop 1
	v_mul_f32_e32 v85, 0x3d372713, v74
	v_mul_f32_e32 v85, v74, v85
	v_fma_f32 v85, v74, v85, v74
	v_mul_f32_e32 v85, 0xbfcc422a, v85
	v_mul_f32_e32 v85, 0x3fb8aa3b, v85
	v_mul_f32_e32 v84, 0x3d372713, v78
	v_exp_f32_e32 v86, v85
	v_mul_f32_e32 v85, 0x3d372713, v79
	v_mul_f32_e32 v84, v78, v84
	v_mul_f32_e32 v85, v79, v85
	v_fma_f32 v84, v78, v84, v78
	v_fma_f32 v85, v79, v85, v79
	v_mul_f32_e32 v84, 0xbfcc422a, v84
	v_mul_f32_e32 v85, 0xbfcc422a, v85
	v_mul_f32_e32 v84, 0x3fb8aa3b, v84
	v_mul_f32_e32 v85, 0x3fb8aa3b, v85
	v_exp_f32_e32 v84, v84
	v_exp_f32_e32 v85, v85
	v_or_b32_e32 v82, 48, v142
	v_ashrrev_i32_e32 v83, 31, v82
	v_lshlrev_b64 v[82:83], 14, v[82:83]
	v_pk_add_f32 v[84:85], v[84:85], 1.0 op_sel_hi:[1,0]
	s_nop 0
	s_nop 0
	v_rcp_f32_e32 v87, v85
	s_nop 0
	v_mul_f32_e32 v85, v79, v87
	s_nop 0
	v_rcp_f32_e32 v79, v84
	s_nop 0
	v_mul_f32_e32 v84, v78, v79
	v_mul_f32_e32 v78, 0x3d372713, v75
	v_mul_f32_e32 v78, v75, v78
	v_fma_f32 v78, v75, v78, v75
	v_mul_f32_e32 v78, 0xbfcc422a, v78
	v_mul_f32_e32 v78, 0x3fb8aa3b, v78
	v_exp_f32_e32 v87, v78
	s_nop 0
	v_pk_add_f32 v[78:79], v[86:87], 1.0 op_sel_hi:[1,0]
	s_nop 0
	s_nop 0
	v_rcp_f32_e32 v86, v79
	s_nop 0
	v_mul_f32_e32 v86, v75, v86
	s_nop 0
	v_rcp_f32_e32 v75, v78
	s_nop 0
	v_mul_f32_e32 v87, v74, v75
	v_mul_f32_e32 v75, 0x3d372713, v76
	v_mul_f32_e32 v75, v76, v75
	v_fma_f32 v75, v76, v75, v76
	v_mul_f32_e32 v75, 0xbfcc422a, v75
	v_mul_f32_e32 v75, 0x3fb8aa3b, v75
	v_mul_f32_e32 v74, 0x3d372713, v80
	v_exp_f32_e32 v78, v75
	v_mul_f32_e32 v75, 0x3d372713, v81
	v_mul_f32_e32 v74, v80, v74
	v_mul_f32_e32 v75, v81, v75
	v_fma_f32 v74, v80, v74, v80
	v_fma_f32 v75, v81, v75, v81
	v_mul_f32_e32 v74, 0xbfcc422a, v74
	v_mul_f32_e32 v75, 0xbfcc422a, v75
	v_mul_f32_e32 v74, 0x3fb8aa3b, v74
	v_mul_f32_e32 v75, 0x3fb8aa3b, v75
	v_exp_f32_e32 v74, v74
	v_exp_f32_e32 v75, v75
	s_nop 0
	v_pk_add_f32 v[74:75], v[74:75], 1.0 op_sel_hi:[1,0]
	s_nop 0
	s_nop 0
	v_rcp_f32_e32 v79, v75
	s_nop 0
	v_mul_f32_e32 v81, v81, v79
	s_nop 0
	v_rcp_f32_e32 v75, v74
	s_nop 0
	v_mul_f32_e32 v80, v80, v75
	v_mul_f32_e32 v74, 0x3d372713, v77
	v_mul_f32_e32 v74, v77, v74
	v_fma_f32 v74, v77, v74, v77
	v_mul_f32_e32 v74, 0xbfcc422a, v74
	v_mul_f32_e32 v74, 0x3fb8aa3b, v74
	v_exp_f32_e32 v79, v74
	s_nop 0
	v_pk_add_f32 v[74:75], v[78:79], 1.0 op_sel_hi:[1,0]
	s_nop 0
	s_nop 0
	v_rcp_f32_e32 v78, v75
	s_nop 0
	v_mul_f32_e32 v75, v77, v78
	s_nop 0
	v_rcp_f32_e32 v77, v74
	s_nop 0
	v_mul_f32_e32 v74, v76, v77
	v_cvt_pk_bf16_f32 v79, v74, v75
	v_lshl_add_u64 v[74:75], s[0:1], 0, v[82:83]
	v_cvt_pk_bf16_f32 v77, v80, v81
	v_lshl_add_u64 v[80:81], v[74:75], 0, v[124:125]
	v_lshl_add_u64 v[80:81], v[80:81], 0, s[10:11]
	v_cvt_pk_bf16_f32 v76, v84, v85
	v_cvt_pk_bf16_f32 v78, v87, v86
	v_lshl_add_u64 v[80:81], v[80:81], 0, v[48:49]
	global_store_dwordx4 v[80:81], v[76:79], off
	s_nop 1
	v_mul_f32_e32 v77, 0x3d372713, v66
	v_mul_f32_e32 v77, v66, v77
	v_fma_f32 v77, v66, v77, v66
	v_mul_f32_e32 v77, 0xbfcc422a, v77
	v_mul_f32_e32 v77, 0x3fb8aa3b, v77
	v_mul_f32_e32 v76, 0x3d372713, v70
	v_exp_f32_e32 v78, v77
	v_mul_f32_e32 v77, 0x3d372713, v71
	v_mul_f32_e32 v76, v70, v76
	v_mul_f32_e32 v77, v71, v77
	v_fma_f32 v76, v70, v76, v70
	v_fma_f32 v77, v71, v77, v71
	v_mul_f32_e32 v76, 0xbfcc422a, v76
	v_mul_f32_e32 v77, 0xbfcc422a, v77
	v_mul_f32_e32 v76, 0x3fb8aa3b, v76
	v_mul_f32_e32 v77, 0x3fb8aa3b, v77
	v_exp_f32_e32 v76, v76
	v_exp_f32_e32 v77, v77
	s_nop 0
	v_pk_add_f32 v[76:77], v[76:77], 1.0 op_sel_hi:[1,0]
	s_nop 0
	s_nop 0
	v_rcp_f32_e32 v79, v77
	s_nop 0
	v_mul_f32_e32 v77, v71, v79
	s_nop 0
	v_rcp_f32_e32 v71, v76
	s_nop 0
	v_mul_f32_e32 v76, v70, v71
	v_mul_f32_e32 v70, 0x3d372713, v67
	v_mul_f32_e32 v70, v67, v70
	v_fma_f32 v70, v67, v70, v67
	v_mul_f32_e32 v70, 0xbfcc422a, v70
	v_mul_f32_e32 v70, 0x3fb8aa3b, v70
	v_exp_f32_e32 v79, v70
	s_nop 0
	v_pk_add_f32 v[70:71], v[78:79], 1.0 op_sel_hi:[1,0]
	s_nop 0
	s_nop 0
	v_rcp_f32_e32 v78, v71
	s_nop 0
	v_mul_f32_e32 v78, v67, v78
	s_nop 0
	v_rcp_f32_e32 v67, v70
	s_nop 0
	v_mul_f32_e32 v79, v66, v67
	v_mul_f32_e32 v67, 0x3d372713, v68
	v_mul_f32_e32 v67, v68, v67
	v_fma_f32 v67, v68, v67, v68
	v_mul_f32_e32 v67, 0xbfcc422a, v67
	v_mul_f32_e32 v67, 0x3fb8aa3b, v67
	v_mul_f32_e32 v66, 0x3d372713, v72
	v_exp_f32_e32 v70, v67
	v_mul_f32_e32 v67, 0x3d372713, v73
	v_mul_f32_e32 v66, v72, v66
	v_mul_f32_e32 v67, v73, v67
	v_fma_f32 v66, v72, v66, v72
	v_fma_f32 v67, v73, v67, v73
	v_mul_f32_e32 v66, 0xbfcc422a, v66
	v_mul_f32_e32 v67, 0xbfcc422a, v67
	v_mul_f32_e32 v66, 0x3fb8aa3b, v66
	v_mul_f32_e32 v67, 0x3fb8aa3b, v67
	v_exp_f32_e32 v66, v66
	v_exp_f32_e32 v67, v67
	s_nop 0
	v_pk_add_f32 v[66:67], v[66:67], 1.0 op_sel_hi:[1,0]
	s_nop 0
	s_nop 0
	v_rcp_f32_e32 v71, v67
	s_nop 0
	v_mul_f32_e32 v73, v73, v71
	s_nop 0
	v_rcp_f32_e32 v67, v66
	s_nop 0
	v_mul_f32_e32 v72, v72, v67
	v_mul_f32_e32 v66, 0x3d372713, v69
	v_mul_f32_e32 v66, v69, v66
	v_fma_f32 v66, v69, v66, v69
	v_mul_f32_e32 v66, 0xbfcc422a, v66
	v_mul_f32_e32 v66, 0x3fb8aa3b, v66
	v_exp_f32_e32 v71, v66
	s_nop 0
	v_pk_add_f32 v[66:67], v[70:71], 1.0 op_sel_hi:[1,0]
	s_nop 0
	s_nop 0
	v_rcp_f32_e32 v70, v67
	s_nop 0
	v_mul_f32_e32 v69, v69, v70
	s_nop 0
	v_rcp_f32_e32 v67, v66
	s_nop 0
	v_mul_f32_e32 v70, v68, v67
	v_cvt_pk_bf16_f32 v69, v70, v69
	v_lshl_add_u64 v[70:71], v[74:75], 0, v[114:115]
	v_lshl_add_u64 v[70:71], v[70:71], 0, s[10:11]
	v_cvt_pk_bf16_f32 v66, v76, v77
	v_cvt_pk_bf16_f32 v67, v72, v73
	v_cvt_pk_bf16_f32 v68, v79, v78
	v_lshl_add_u64 v[70:71], v[70:71], 0, v[48:49]
	global_store_dwordx4 v[70:71], v[66:69], off
	s_nop 1
	v_mul_f32_e32 v67, 0x3d372713, v58
	v_mul_f32_e32 v67, v58, v67
	v_fma_f32 v67, v58, v67, v58
	v_mul_f32_e32 v67, 0xbfcc422a, v67
	v_mul_f32_e32 v67, 0x3fb8aa3b, v67
	v_mul_f32_e32 v66, 0x3d372713, v62
	v_exp_f32_e32 v68, v67
	v_mul_f32_e32 v67, 0x3d372713, v63
	v_mul_f32_e32 v66, v62, v66
	v_mul_f32_e32 v67, v63, v67
	v_fma_f32 v66, v62, v66, v62
	v_fma_f32 v67, v63, v67, v63
	v_mul_f32_e32 v66, 0xbfcc422a, v66
	v_mul_f32_e32 v67, 0xbfcc422a, v67
	v_mul_f32_e32 v66, 0x3fb8aa3b, v66
	v_mul_f32_e32 v67, 0x3fb8aa3b, v67
	v_exp_f32_e32 v66, v66
	v_exp_f32_e32 v67, v67
	s_nop 0
	v_pk_add_f32 v[66:67], v[66:67], 1.0 op_sel_hi:[1,0]
	s_nop 0
	s_nop 0
	v_rcp_f32_e32 v69, v67
	s_nop 0
	v_mul_f32_e32 v67, v63, v69
	s_nop 0
	v_rcp_f32_e32 v63, v66
	s_nop 0
	v_mul_f32_e32 v66, v62, v63
	v_mul_f32_e32 v62, 0x3d372713, v59
	v_mul_f32_e32 v62, v59, v62
	v_fma_f32 v62, v59, v62, v59
	v_mul_f32_e32 v62, 0xbfcc422a, v62
	v_mul_f32_e32 v62, 0x3fb8aa3b, v62
	v_exp_f32_e32 v69, v62
	s_nop 0
	v_pk_add_f32 v[62:63], v[68:69], 1.0 op_sel_hi:[1,0]
	s_nop 0
	s_nop 0
	v_rcp_f32_e32 v68, v63
	s_nop 0
	v_mul_f32_e32 v68, v59, v68
	s_nop 0
	v_rcp_f32_e32 v59, v62
	s_nop 0
	v_mul_f32_e32 v69, v58, v59
	v_mul_f32_e32 v59, 0x3d372713, v60
	v_mul_f32_e32 v59, v60, v59
	v_fma_f32 v59, v60, v59, v60
	v_mul_f32_e32 v59, 0xbfcc422a, v59
	v_mul_f32_e32 v59, 0x3fb8aa3b, v59
	v_mul_f32_e32 v58, 0x3d372713, v64
	v_exp_f32_e32 v62, v59
	v_mul_f32_e32 v59, 0x3d372713, v65
	v_mul_f32_e32 v58, v64, v58
	v_mul_f32_e32 v59, v65, v59
	v_fma_f32 v58, v64, v58, v64
	v_fma_f32 v59, v65, v59, v65
	v_mul_f32_e32 v58, 0xbfcc422a, v58
	v_mul_f32_e32 v59, 0xbfcc422a, v59
	v_mul_f32_e32 v58, 0x3fb8aa3b, v58
	v_mul_f32_e32 v59, 0x3fb8aa3b, v59
	v_exp_f32_e32 v58, v58
	v_exp_f32_e32 v59, v59
	s_nop 0
	v_pk_add_f32 v[58:59], v[58:59], 1.0 op_sel_hi:[1,0]
	s_nop 0
	s_nop 0
	v_rcp_f32_e32 v63, v59
	s_nop 0
	v_mul_f32_e32 v65, v65, v63
	s_nop 0
	v_rcp_f32_e32 v59, v58
	s_nop 0
	v_mul_f32_e32 v64, v64, v59
	v_mul_f32_e32 v58, 0x3d372713, v61
	v_mul_f32_e32 v58, v61, v58
	v_fma_f32 v58, v61, v58, v61
	v_mul_f32_e32 v58, 0xbfcc422a, v58
	v_mul_f32_e32 v58, 0x3fb8aa3b, v58
	v_exp_f32_e32 v63, v58
	s_nop 0
	v_pk_add_f32 v[58:59], v[62:63], 1.0 op_sel_hi:[1,0]
	s_nop 0
	s_nop 0
	v_rcp_f32_e32 v62, v59
	s_nop 0
	v_mul_f32_e32 v59, v61, v62
	s_mov_b64 s[12:13], 0x200000
	v_rcp_f32_e32 v61, v58
	s_nop 0
	v_mul_f32_e32 v58, v60, v61
	v_cvt_pk_bf16_f32 v63, v58, v59
	v_lshl_add_u64 v[58:59], v[122:123], 0, s[12:13]
	v_cvt_pk_bf16_f32 v61, v64, v65
	v_lshl_add_u64 v[64:65], v[58:59], 0, v[124:125]
	v_lshl_add_u64 v[64:65], v[64:65], 0, s[10:11]
	v_cvt_pk_bf16_f32 v60, v66, v67
	v_cvt_pk_bf16_f32 v62, v69, v68
	v_lshl_add_u64 v[64:65], v[64:65], 0, v[48:49]
	global_store_dwordx4 v[64:65], v[60:63], off
	s_nop 1
	v_mul_f32_e32 v61, 0x3d372713, v50
	v_mul_f32_e32 v61, v50, v61
	v_fma_f32 v61, v50, v61, v50
	v_mul_f32_e32 v61, 0xbfcc422a, v61
	v_mul_f32_e32 v61, 0x3fb8aa3b, v61
	v_mul_f32_e32 v60, 0x3d372713, v54
	v_exp_f32_e32 v62, v61
	v_mul_f32_e32 v61, 0x3d372713, v55
	v_mul_f32_e32 v60, v54, v60
	v_mul_f32_e32 v61, v55, v61
	v_fma_f32 v60, v54, v60, v54
	v_fma_f32 v61, v55, v61, v55
	v_mul_f32_e32 v60, 0xbfcc422a, v60
	v_mul_f32_e32 v61, 0xbfcc422a, v61
	v_mul_f32_e32 v60, 0x3fb8aa3b, v60
	v_mul_f32_e32 v61, 0x3fb8aa3b, v61
	v_exp_f32_e32 v60, v60
	v_exp_f32_e32 v61, v61
	s_nop 0
	v_pk_add_f32 v[60:61], v[60:61], 1.0 op_sel_hi:[1,0]
	s_nop 0
	s_nop 0
	v_rcp_f32_e32 v63, v61
	s_nop 0
	v_mul_f32_e32 v61, v55, v63
	s_nop 0
	v_rcp_f32_e32 v55, v60
	s_nop 0
	v_mul_f32_e32 v60, v54, v55
	v_mul_f32_e32 v54, 0x3d372713, v51
	v_mul_f32_e32 v54, v51, v54
	v_fma_f32 v54, v51, v54, v51
	v_mul_f32_e32 v54, 0xbfcc422a, v54
	v_mul_f32_e32 v54, 0x3fb8aa3b, v54
	v_exp_f32_e32 v63, v54
	s_nop 0
	v_pk_add_f32 v[54:55], v[62:63], 1.0 op_sel_hi:[1,0]
	s_nop 0
	s_nop 0
	v_rcp_f32_e32 v62, v55
	s_nop 0
	v_mul_f32_e32 v62, v51, v62
	s_nop 0
	v_rcp_f32_e32 v51, v54
	s_nop 0
	v_mul_f32_e32 v63, v50, v51
	v_mul_f32_e32 v51, 0x3d372713, v52
	v_mul_f32_e32 v51, v52, v51
	v_fma_f32 v51, v52, v51, v52
	v_mul_f32_e32 v51, 0xbfcc422a, v51
	v_mul_f32_e32 v51, 0x3fb8aa3b, v51
	v_mul_f32_e32 v50, 0x3d372713, v56
	v_exp_f32_e32 v54, v51
	v_mul_f32_e32 v51, 0x3d372713, v57
	v_mul_f32_e32 v50, v56, v50
	v_mul_f32_e32 v51, v57, v51
	v_fma_f32 v50, v56, v50, v56
	v_fma_f32 v51, v57, v51, v57
	v_mul_f32_e32 v50, 0xbfcc422a, v50
	v_mul_f32_e32 v51, 0xbfcc422a, v51
	v_mul_f32_e32 v50, 0x3fb8aa3b, v50
	v_mul_f32_e32 v51, 0x3fb8aa3b, v51
	v_exp_f32_e32 v50, v50
	v_exp_f32_e32 v51, v51
	s_nop 0
	v_pk_add_f32 v[50:51], v[50:51], 1.0 op_sel_hi:[1,0]
	s_nop 0
	s_nop 0
	v_rcp_f32_e32 v55, v51
	s_nop 0
	v_mul_f32_e32 v57, v57, v55
	s_nop 0
	v_rcp_f32_e32 v51, v50
	s_nop 0
	v_mul_f32_e32 v56, v56, v51
	v_mul_f32_e32 v50, 0x3d372713, v53
	v_mul_f32_e32 v50, v53, v50
	v_fma_f32 v50, v53, v50, v53
	v_mul_f32_e32 v50, 0xbfcc422a, v50
	v_mul_f32_e32 v50, 0x3fb8aa3b, v50
	v_exp_f32_e32 v55, v50
	s_nop 0
	v_pk_add_f32 v[50:51], v[54:55], 1.0 op_sel_hi:[1,0]
	s_nop 0
	s_nop 0
	v_rcp_f32_e32 v54, v51
	s_nop 0
	v_mul_f32_e32 v53, v53, v54
	s_nop 0
	v_rcp_f32_e32 v51, v50
	s_nop 0
	v_mul_f32_e32 v54, v52, v51
	v_cvt_pk_bf16_f32 v53, v54, v53
	v_lshl_add_u64 v[54:55], v[58:59], 0, v[114:115]
	v_lshl_add_u64 v[54:55], v[54:55], 0, s[10:11]
	v_cvt_pk_bf16_f32 v50, v60, v61
	v_cvt_pk_bf16_f32 v51, v56, v57
	v_cvt_pk_bf16_f32 v52, v63, v62
	v_lshl_add_u64 v[54:55], v[54:55], 0, v[48:49]
	global_store_dwordx4 v[54:55], v[50:53], off
	s_nop 1
	v_mul_f32_e32 v51, 0x3d372713, v40
	v_mul_f32_e32 v51, v40, v51
	v_fma_f32 v51, v40, v51, v40
	v_mul_f32_e32 v51, 0xbfcc422a, v51
	v_mul_f32_e32 v51, 0x3fb8aa3b, v51
	v_mul_f32_e32 v50, 0x3d372713, v44
	v_exp_f32_e32 v52, v51
	v_mul_f32_e32 v51, 0x3d372713, v45
	v_mul_f32_e32 v50, v44, v50
	v_mul_f32_e32 v51, v45, v51
	v_fma_f32 v50, v44, v50, v44
	v_fma_f32 v51, v45, v51, v45
	v_mul_f32_e32 v50, 0xbfcc422a, v50
	v_mul_f32_e32 v51, 0xbfcc422a, v51
	v_mul_f32_e32 v50, 0x3fb8aa3b, v50
	v_mul_f32_e32 v51, 0x3fb8aa3b, v51
	v_exp_f32_e32 v50, v50
	v_exp_f32_e32 v51, v51
	s_nop 0
	v_pk_add_f32 v[50:51], v[50:51], 1.0 op_sel_hi:[1,0]
	s_nop 0
	s_nop 0
	v_rcp_f32_e32 v53, v51
	s_nop 0
	v_mul_f32_e32 v51, v45, v53
	s_nop 0
	v_rcp_f32_e32 v45, v50
	s_nop 0
	v_mul_f32_e32 v50, v44, v45
	v_mul_f32_e32 v44, 0x3d372713, v41
	v_mul_f32_e32 v44, v41, v44
	v_fma_f32 v44, v41, v44, v41
	v_mul_f32_e32 v44, 0xbfcc422a, v44
	v_mul_f32_e32 v44, 0x3fb8aa3b, v44
	v_exp_f32_e32 v53, v44
	s_nop 0
	v_pk_add_f32 v[44:45], v[52:53], 1.0 op_sel_hi:[1,0]
	s_nop 0
	s_nop 0
	v_rcp_f32_e32 v52, v45
	s_nop 0
	v_mul_f32_e32 v52, v41, v52
	s_nop 0
	v_rcp_f32_e32 v41, v44
	s_nop 0
	v_mul_f32_e32 v53, v40, v41
	v_mul_f32_e32 v41, 0x3d372713, v42
	v_mul_f32_e32 v41, v42, v41
	v_fma_f32 v41, v42, v41, v42
	v_mul_f32_e32 v41, 0xbfcc422a, v41
	v_mul_f32_e32 v41, 0x3fb8aa3b, v41
	v_mul_f32_e32 v40, 0x3d372713, v46
	v_exp_f32_e32 v44, v41
	v_mul_f32_e32 v41, 0x3d372713, v47
	v_mul_f32_e32 v40, v46, v40
	v_mul_f32_e32 v41, v47, v41
	v_fma_f32 v40, v46, v40, v46
	v_fma_f32 v41, v47, v41, v47
	v_mul_f32_e32 v40, 0xbfcc422a, v40
	v_mul_f32_e32 v41, 0xbfcc422a, v41
	v_mul_f32_e32 v40, 0x3fb8aa3b, v40
	v_mul_f32_e32 v41, 0x3fb8aa3b, v41
	v_exp_f32_e32 v40, v40
	v_exp_f32_e32 v41, v41
	s_nop 0
	v_pk_add_f32 v[40:41], v[40:41], 1.0 op_sel_hi:[1,0]
	s_nop 0
	s_nop 0
	v_rcp_f32_e32 v45, v41
	s_nop 0
	v_mul_f32_e32 v47, v47, v45
	s_nop 0
	v_rcp_f32_e32 v41, v40
	s_nop 0
	v_mul_f32_e32 v46, v46, v41
	v_mul_f32_e32 v40, 0x3d372713, v43
	v_mul_f32_e32 v40, v43, v40
	v_fma_f32 v40, v43, v40, v43
	v_mul_f32_e32 v40, 0xbfcc422a, v40
	v_mul_f32_e32 v40, 0x3fb8aa3b, v40
	v_exp_f32_e32 v45, v40
	s_nop 0
	v_pk_add_f32 v[40:41], v[44:45], 1.0 op_sel_hi:[1,0]
	s_nop 0
	s_nop 0
	v_rcp_f32_e32 v44, v41
	s_nop 0
	v_mul_f32_e32 v41, v43, v44
	s_mov_b64 s[12:13], 0x240000
	v_rcp_f32_e32 v43, v40
	s_nop 0
	v_mul_f32_e32 v40, v42, v43
	v_cvt_pk_bf16_f32 v45, v40, v41
	v_lshl_add_u64 v[40:41], v[122:123], 0, s[12:13]
	v_cvt_pk_bf16_f32 v43, v46, v47
	v_lshl_add_u64 v[46:47], v[40:41], 0, v[124:125]
	v_lshl_add_u64 v[46:47], v[46:47], 0, s[10:11]
	v_cvt_pk_bf16_f32 v42, v50, v51
	v_cvt_pk_bf16_f32 v44, v53, v52
	v_lshl_add_u64 v[46:47], v[46:47], 0, v[48:49]
	global_store_dwordx4 v[46:47], v[42:45], off
	s_nop 1
	v_mul_f32_e32 v43, 0x3d372713, v32
	v_mul_f32_e32 v43, v32, v43
	v_fma_f32 v43, v32, v43, v32
	v_mul_f32_e32 v43, 0xbfcc422a, v43
	v_mul_f32_e32 v43, 0x3fb8aa3b, v43
	v_mul_f32_e32 v42, 0x3d372713, v36
	v_exp_f32_e32 v44, v43
	v_mul_f32_e32 v43, 0x3d372713, v37
	v_mul_f32_e32 v42, v36, v42
	v_mul_f32_e32 v43, v37, v43
	v_fma_f32 v42, v36, v42, v36
	v_fma_f32 v43, v37, v43, v37
	v_mul_f32_e32 v42, 0xbfcc422a, v42
	v_mul_f32_e32 v43, 0xbfcc422a, v43
	v_mul_f32_e32 v42, 0x3fb8aa3b, v42
	v_mul_f32_e32 v43, 0x3fb8aa3b, v43
	v_exp_f32_e32 v42, v42
	v_exp_f32_e32 v43, v43
	s_nop 0
	v_pk_add_f32 v[42:43], v[42:43], 1.0 op_sel_hi:[1,0]
	s_nop 0
	s_nop 0
	v_rcp_f32_e32 v45, v43
	s_nop 0
	v_mul_f32_e32 v43, v37, v45
	s_nop 0
	v_rcp_f32_e32 v37, v42
	s_nop 0
	v_mul_f32_e32 v42, v36, v37
	v_mul_f32_e32 v36, 0x3d372713, v33
	v_mul_f32_e32 v36, v33, v36
	v_fma_f32 v36, v33, v36, v33
	v_mul_f32_e32 v36, 0xbfcc422a, v36
	v_mul_f32_e32 v36, 0x3fb8aa3b, v36
	v_exp_f32_e32 v45, v36
	s_nop 0
	v_pk_add_f32 v[36:37], v[44:45], 1.0 op_sel_hi:[1,0]
	s_nop 0
	s_nop 0
	v_rcp_f32_e32 v44, v37
	s_nop 0
	v_mul_f32_e32 v44, v33, v44
	s_nop 0
	v_rcp_f32_e32 v33, v36
	s_nop 0
	v_mul_f32_e32 v45, v32, v33
	v_mul_f32_e32 v33, 0x3d372713, v34
	v_mul_f32_e32 v33, v34, v33
	v_fma_f32 v33, v34, v33, v34
	v_mul_f32_e32 v33, 0xbfcc422a, v33
	v_mul_f32_e32 v33, 0x3fb8aa3b, v33
	v_mul_f32_e32 v32, 0x3d372713, v38
	v_exp_f32_e32 v36, v33
	v_mul_f32_e32 v33, 0x3d372713, v39
	v_mul_f32_e32 v32, v38, v32
	v_mul_f32_e32 v33, v39, v33
	v_fma_f32 v32, v38, v32, v38
	v_fma_f32 v33, v39, v33, v39
	v_mul_f32_e32 v32, 0xbfcc422a, v32
	v_mul_f32_e32 v33, 0xbfcc422a, v33
	v_mul_f32_e32 v32, 0x3fb8aa3b, v32
	v_mul_f32_e32 v33, 0x3fb8aa3b, v33
	v_exp_f32_e32 v32, v32
	v_exp_f32_e32 v33, v33
	s_nop 0
	v_pk_add_f32 v[32:33], v[32:33], 1.0 op_sel_hi:[1,0]
	s_nop 0
	s_nop 0
	v_rcp_f32_e32 v37, v33
	s_nop 0
	v_mul_f32_e32 v39, v39, v37
	s_nop 0
	v_rcp_f32_e32 v33, v32
	s_nop 0
	v_mul_f32_e32 v38, v38, v33
	v_mul_f32_e32 v32, 0x3d372713, v35
	v_mul_f32_e32 v32, v35, v32
	v_fma_f32 v32, v35, v32, v35
	v_mul_f32_e32 v32, 0xbfcc422a, v32
	v_mul_f32_e32 v32, 0x3fb8aa3b, v32
	v_exp_f32_e32 v37, v32
	s_nop 0
	v_pk_add_f32 v[32:33], v[36:37], 1.0 op_sel_hi:[1,0]
	s_nop 0
	s_nop 0
	v_rcp_f32_e32 v36, v33
	s_nop 0
	v_mul_f32_e32 v35, v35, v36
	s_nop 0
	v_rcp_f32_e32 v33, v32
	s_nop 0
	v_mul_f32_e32 v36, v34, v33
	v_cvt_pk_bf16_f32 v35, v36, v35
	v_lshl_add_u64 v[36:37], v[40:41], 0, v[114:115]
	v_lshl_add_u64 v[36:37], v[36:37], 0, s[10:11]
	v_cvt_pk_bf16_f32 v32, v42, v43
	v_cvt_pk_bf16_f32 v33, v38, v39
	v_cvt_pk_bf16_f32 v34, v45, v44
	v_lshl_add_u64 v[36:37], v[36:37], 0, v[48:49]
	global_store_dwordx4 v[36:37], v[32:35], off
	s_nop 1
	v_mul_f32_e32 v33, 0x3d372713, v24
	v_mul_f32_e32 v33, v24, v33
	v_fma_f32 v33, v24, v33, v24
	v_mul_f32_e32 v33, 0xbfcc422a, v33
	v_mul_f32_e32 v33, 0x3fb8aa3b, v33
	v_mul_f32_e32 v32, 0x3d372713, v28
	v_exp_f32_e32 v34, v33
	v_mul_f32_e32 v33, 0x3d372713, v29
	v_mul_f32_e32 v32, v28, v32
	v_mul_f32_e32 v33, v29, v33
	v_fma_f32 v32, v28, v32, v28
	v_fma_f32 v33, v29, v33, v29
	v_mul_f32_e32 v32, 0xbfcc422a, v32
	v_mul_f32_e32 v33, 0xbfcc422a, v33
	v_mul_f32_e32 v32, 0x3fb8aa3b, v32
	v_mul_f32_e32 v33, 0x3fb8aa3b, v33
	v_exp_f32_e32 v32, v32
	v_exp_f32_e32 v33, v33
	s_nop 0
	v_pk_add_f32 v[32:33], v[32:33], 1.0 op_sel_hi:[1,0]
	s_nop 0
	s_nop 0
	v_rcp_f32_e32 v35, v33
	s_nop 0
	v_mul_f32_e32 v33, v29, v35
	s_nop 0
	v_rcp_f32_e32 v29, v32
	s_nop 0
	v_mul_f32_e32 v32, v28, v29
	v_mul_f32_e32 v28, 0x3d372713, v25
	v_mul_f32_e32 v28, v25, v28
	v_fma_f32 v28, v25, v28, v25
	v_mul_f32_e32 v28, 0xbfcc422a, v28
	v_mul_f32_e32 v28, 0x3fb8aa3b, v28
	v_exp_f32_e32 v35, v28
	s_nop 0
	v_pk_add_f32 v[28:29], v[34:35], 1.0 op_sel_hi:[1,0]
	s_nop 0
	s_nop 0
	v_rcp_f32_e32 v34, v29
	s_nop 0
	v_mul_f32_e32 v34, v25, v34
	s_nop 0
	v_rcp_f32_e32 v25, v28
	s_nop 0
	v_mul_f32_e32 v35, v24, v25
	v_mul_f32_e32 v25, 0x3d372713, v26
	v_mul_f32_e32 v25, v26, v25
	v_fma_f32 v25, v26, v25, v26
	v_mul_f32_e32 v25, 0xbfcc422a, v25
	v_mul_f32_e32 v25, 0x3fb8aa3b, v25
	v_mul_f32_e32 v24, 0x3d372713, v30
	v_exp_f32_e32 v28, v25
	v_mul_f32_e32 v25, 0x3d372713, v31
	v_mul_f32_e32 v24, v30, v24
	v_mul_f32_e32 v25, v31, v25
	v_fma_f32 v24, v30, v24, v30
	v_fma_f32 v25, v31, v25, v31
	v_mul_f32_e32 v24, 0xbfcc422a, v24
	v_mul_f32_e32 v25, 0xbfcc422a, v25
	v_mul_f32_e32 v24, 0x3fb8aa3b, v24
	v_mul_f32_e32 v25, 0x3fb8aa3b, v25
	v_exp_f32_e32 v24, v24
	v_exp_f32_e32 v25, v25
	s_nop 0
	v_pk_add_f32 v[24:25], v[24:25], 1.0 op_sel_hi:[1,0]
	s_nop 0
	s_nop 0
	v_rcp_f32_e32 v29, v25
	s_nop 0
	v_mul_f32_e32 v31, v31, v29
	s_nop 0
	v_rcp_f32_e32 v25, v24
	s_nop 0
	v_mul_f32_e32 v30, v30, v25
	v_mul_f32_e32 v24, 0x3d372713, v27
	v_mul_f32_e32 v24, v27, v24
	v_fma_f32 v24, v27, v24, v27
	v_mul_f32_e32 v24, 0xbfcc422a, v24
	v_mul_f32_e32 v24, 0x3fb8aa3b, v24
	v_exp_f32_e32 v29, v24
	s_nop 0
	v_pk_add_f32 v[24:25], v[28:29], 1.0 op_sel_hi:[1,0]
	s_nop 0
	s_nop 0
	v_rcp_f32_e32 v28, v25
	s_nop 0
	v_mul_f32_e32 v25, v27, v28
	s_mov_b64 s[12:13], 0x280000
	v_rcp_f32_e32 v27, v24
	s_nop 0
	v_mul_f32_e32 v24, v26, v27
	v_cvt_pk_bf16_f32 v29, v24, v25
	v_lshl_add_u64 v[24:25], v[122:123], 0, s[12:13]
	v_cvt_pk_bf16_f32 v27, v30, v31
	v_lshl_add_u64 v[30:31], v[24:25], 0, v[124:125]
	v_lshl_add_u64 v[30:31], v[30:31], 0, s[10:11]
	v_cvt_pk_bf16_f32 v26, v32, v33
	v_cvt_pk_bf16_f32 v28, v35, v34
	v_lshl_add_u64 v[30:31], v[30:31], 0, v[48:49]
	global_store_dwordx4 v[30:31], v[26:29], off
	s_nop 1
	v_mul_f32_e32 v27, 0x3d372713, v16
	v_mul_f32_e32 v27, v16, v27
	v_fma_f32 v27, v16, v27, v16
	v_mul_f32_e32 v27, 0xbfcc422a, v27
	v_mul_f32_e32 v27, 0x3fb8aa3b, v27
	v_mul_f32_e32 v26, 0x3d372713, v20
	v_exp_f32_e32 v28, v27
	v_mul_f32_e32 v27, 0x3d372713, v21
	v_mul_f32_e32 v26, v20, v26
	v_mul_f32_e32 v27, v21, v27
	v_fma_f32 v26, v20, v26, v20
	v_fma_f32 v27, v21, v27, v21
	v_mul_f32_e32 v26, 0xbfcc422a, v26
	v_mul_f32_e32 v27, 0xbfcc422a, v27
	v_mul_f32_e32 v26, 0x3fb8aa3b, v26
	v_mul_f32_e32 v27, 0x3fb8aa3b, v27
	v_exp_f32_e32 v26, v26
	v_exp_f32_e32 v27, v27
	s_nop 0
	v_pk_add_f32 v[26:27], v[26:27], 1.0 op_sel_hi:[1,0]
	s_nop 0
	s_nop 0
	v_rcp_f32_e32 v29, v27
	s_nop 0
	v_mul_f32_e32 v27, v21, v29
	s_nop 0
	v_rcp_f32_e32 v21, v26
	s_nop 0
	v_mul_f32_e32 v26, v20, v21
	v_mul_f32_e32 v20, 0x3d372713, v17
	v_mul_f32_e32 v20, v17, v20
	v_fma_f32 v20, v17, v20, v17
	v_mul_f32_e32 v20, 0xbfcc422a, v20
	v_mul_f32_e32 v20, 0x3fb8aa3b, v20
	v_exp_f32_e32 v29, v20
	s_nop 0
	v_pk_add_f32 v[20:21], v[28:29], 1.0 op_sel_hi:[1,0]
	s_nop 0
	s_nop 0
	v_rcp_f32_e32 v28, v21
	s_nop 0
	v_mul_f32_e32 v28, v17, v28
	s_nop 0
	v_rcp_f32_e32 v17, v20
	s_nop 0
	v_mul_f32_e32 v29, v16, v17
	v_mul_f32_e32 v17, 0x3d372713, v18
	v_mul_f32_e32 v17, v18, v17
	v_fma_f32 v17, v18, v17, v18
	v_mul_f32_e32 v17, 0xbfcc422a, v17
	v_mul_f32_e32 v17, 0x3fb8aa3b, v17
	v_mul_f32_e32 v16, 0x3d372713, v22
	v_exp_f32_e32 v20, v17
	v_mul_f32_e32 v17, 0x3d372713, v23
	v_mul_f32_e32 v16, v22, v16
	v_mul_f32_e32 v17, v23, v17
	v_fma_f32 v16, v22, v16, v22
	v_fma_f32 v17, v23, v17, v23
	v_mul_f32_e32 v16, 0xbfcc422a, v16
	v_mul_f32_e32 v17, 0xbfcc422a, v17
	v_mul_f32_e32 v16, 0x3fb8aa3b, v16
	v_mul_f32_e32 v17, 0x3fb8aa3b, v17
	v_exp_f32_e32 v16, v16
	v_exp_f32_e32 v17, v17
	s_nop 0
	v_pk_add_f32 v[16:17], v[16:17], 1.0 op_sel_hi:[1,0]
	s_nop 0
	s_nop 0
	v_rcp_f32_e32 v21, v17
	s_nop 0
	v_mul_f32_e32 v23, v23, v21
	s_nop 0
	v_rcp_f32_e32 v17, v16
	s_nop 0
	v_mul_f32_e32 v22, v22, v17
	v_mul_f32_e32 v16, 0x3d372713, v19
	v_mul_f32_e32 v16, v19, v16
	v_fma_f32 v16, v19, v16, v19
	v_mul_f32_e32 v16, 0xbfcc422a, v16
	v_mul_f32_e32 v16, 0x3fb8aa3b, v16
	v_exp_f32_e32 v21, v16
	s_nop 0
	v_pk_add_f32 v[16:17], v[20:21], 1.0 op_sel_hi:[1,0]
	s_nop 0
	s_nop 0
	v_rcp_f32_e32 v20, v17
	s_nop 0
	v_mul_f32_e32 v19, v19, v20
	s_nop 0
	v_rcp_f32_e32 v17, v16
	s_nop 0
	v_mul_f32_e32 v20, v18, v17
	v_cvt_pk_bf16_f32 v19, v20, v19
	v_lshl_add_u64 v[20:21], v[24:25], 0, v[114:115]
	v_lshl_add_u64 v[20:21], v[20:21], 0, s[10:11]
	v_cvt_pk_bf16_f32 v16, v26, v27
	v_cvt_pk_bf16_f32 v17, v22, v23
	v_cvt_pk_bf16_f32 v18, v29, v28
	v_lshl_add_u64 v[20:21], v[20:21], 0, v[48:49]
	global_store_dwordx4 v[20:21], v[16:19], off
	s_nop 1
	v_mul_f32_e32 v17, 0x3d372713, v8
	v_mul_f32_e32 v17, v8, v17
	v_fma_f32 v17, v8, v17, v8
	v_mul_f32_e32 v17, 0xbfcc422a, v17
	v_mul_f32_e32 v17, 0x3fb8aa3b, v17
	v_mul_f32_e32 v16, 0x3d372713, v12
	v_exp_f32_e32 v18, v17
	v_mul_f32_e32 v17, 0x3d372713, v13
	v_mul_f32_e32 v16, v12, v16
	v_mul_f32_e32 v17, v13, v17
	v_fma_f32 v16, v12, v16, v12
	v_fma_f32 v17, v13, v17, v13
	v_mul_f32_e32 v16, 0xbfcc422a, v16
	v_mul_f32_e32 v17, 0xbfcc422a, v17
	v_mul_f32_e32 v16, 0x3fb8aa3b, v16
	v_mul_f32_e32 v17, 0x3fb8aa3b, v17
	v_exp_f32_e32 v16, v16
	v_exp_f32_e32 v17, v17
	s_nop 0
	v_pk_add_f32 v[16:17], v[16:17], 1.0 op_sel_hi:[1,0]
	s_nop 0
	s_nop 0
	v_rcp_f32_e32 v19, v17
	s_nop 0
	v_mul_f32_e32 v17, v13, v19
	s_nop 0
	v_rcp_f32_e32 v13, v16
	s_nop 0
	v_mul_f32_e32 v16, v12, v13
	v_mul_f32_e32 v12, 0x3d372713, v9
	v_mul_f32_e32 v12, v9, v12
	v_fma_f32 v12, v9, v12, v9
	v_mul_f32_e32 v12, 0xbfcc422a, v12
	v_mul_f32_e32 v12, 0x3fb8aa3b, v12
	v_exp_f32_e32 v19, v12
	s_nop 0
	v_pk_add_f32 v[12:13], v[18:19], 1.0 op_sel_hi:[1,0]
	s_nop 0
	s_nop 0
	v_rcp_f32_e32 v18, v13
	s_nop 0
	v_mul_f32_e32 v18, v9, v18
	s_nop 0
	v_rcp_f32_e32 v9, v12
	s_nop 0
	v_mul_f32_e32 v19, v8, v9
	v_mul_f32_e32 v9, 0x3d372713, v10
	v_mul_f32_e32 v9, v10, v9
	v_fma_f32 v9, v10, v9, v10
	v_mul_f32_e32 v9, 0xbfcc422a, v9
	v_mul_f32_e32 v9, 0x3fb8aa3b, v9
	v_mul_f32_e32 v8, 0x3d372713, v14
	v_exp_f32_e32 v12, v9
	v_mul_f32_e32 v9, 0x3d372713, v15
	v_mul_f32_e32 v8, v14, v8
	v_mul_f32_e32 v9, v15, v9
	v_fma_f32 v8, v14, v8, v14
	v_fma_f32 v9, v15, v9, v15
	v_mul_f32_e32 v8, 0xbfcc422a, v8
	v_mul_f32_e32 v9, 0xbfcc422a, v9
	v_mul_f32_e32 v8, 0x3fb8aa3b, v8
	v_mul_f32_e32 v9, 0x3fb8aa3b, v9
	v_exp_f32_e32 v8, v8
	v_exp_f32_e32 v9, v9
	s_nop 0
	v_pk_add_f32 v[8:9], v[8:9], 1.0 op_sel_hi:[1,0]
	s_nop 0
	s_nop 0
	v_rcp_f32_e32 v13, v9
	s_nop 0
	v_mul_f32_e32 v15, v15, v13
	s_nop 0
	v_rcp_f32_e32 v9, v8
	s_nop 0
	v_mul_f32_e32 v14, v14, v9
	v_mul_f32_e32 v8, 0x3d372713, v11
	v_mul_f32_e32 v8, v11, v8
	v_fma_f32 v8, v11, v8, v11
	v_mul_f32_e32 v8, 0xbfcc422a, v8
	v_mul_f32_e32 v8, 0x3fb8aa3b, v8
	v_exp_f32_e32 v13, v8
	s_nop 0
	v_pk_add_f32 v[8:9], v[12:13], 1.0 op_sel_hi:[1,0]
	s_nop 0
	s_nop 0
	v_rcp_f32_e32 v12, v9
	s_nop 0
	v_mul_f32_e32 v9, v11, v12
	s_mov_b64 s[12:13], 0x2c0000
	v_rcp_f32_e32 v11, v8
	s_nop 0
	v_mul_f32_e32 v8, v10, v11
	v_cvt_pk_bf16_f32 v13, v8, v9
	v_lshl_add_u64 v[8:9], v[122:123], 0, s[12:13]
	v_cvt_pk_bf16_f32 v11, v14, v15
	v_lshl_add_u64 v[14:15], v[8:9], 0, v[124:125]
	v_lshl_add_u64 v[14:15], v[14:15], 0, s[10:11]
	v_cvt_pk_bf16_f32 v10, v16, v17
	v_cvt_pk_bf16_f32 v12, v19, v18
	v_lshl_add_u64 v[14:15], v[14:15], 0, v[48:49]
	global_store_dwordx4 v[14:15], v[10:13], off
	s_nop 1
	v_mul_f32_e32 v11, 0x3d372713, v0
	v_mul_f32_e32 v11, v0, v11
	v_fma_f32 v11, v0, v11, v0
	v_mul_f32_e32 v11, 0xbfcc422a, v11
	v_mul_f32_e32 v11, 0x3fb8aa3b, v11
	v_mul_f32_e32 v10, 0x3d372713, v4
	v_exp_f32_e32 v12, v11
	v_mul_f32_e32 v11, 0x3d372713, v5
	v_mul_f32_e32 v10, v4, v10
	v_mul_f32_e32 v11, v5, v11
	v_fma_f32 v10, v4, v10, v4
	v_fma_f32 v11, v5, v11, v5
	v_mul_f32_e32 v10, 0xbfcc422a, v10
	v_mul_f32_e32 v11, 0xbfcc422a, v11
	v_mul_f32_e32 v10, 0x3fb8aa3b, v10
	v_mul_f32_e32 v11, 0x3fb8aa3b, v11
	v_exp_f32_e32 v10, v10
	v_exp_f32_e32 v11, v11
	s_nop 0
	v_pk_add_f32 v[10:11], v[10:11], 1.0 op_sel_hi:[1,0]
	s_nop 0
	s_nop 0
	v_rcp_f32_e32 v13, v11
	s_nop 0
	v_mul_f32_e32 v11, v5, v13
	s_nop 0
	v_rcp_f32_e32 v5, v10
	s_nop 0
	v_mul_f32_e32 v10, v4, v5
	v_mul_f32_e32 v4, 0x3d372713, v1
	v_mul_f32_e32 v4, v1, v4
	v_fma_f32 v4, v1, v4, v1
	v_mul_f32_e32 v4, 0xbfcc422a, v4
	v_mul_f32_e32 v4, 0x3fb8aa3b, v4
	v_exp_f32_e32 v13, v4
	s_nop 0
	v_pk_add_f32 v[4:5], v[12:13], 1.0 op_sel_hi:[1,0]
	s_nop 0
	s_nop 0
	v_rcp_f32_e32 v12, v5
	s_nop 0
	v_mul_f32_e32 v12, v1, v12
	s_nop 0
	v_rcp_f32_e32 v1, v4
	s_nop 0
	v_mul_f32_e32 v13, v0, v1
	v_mul_f32_e32 v1, 0x3d372713, v2
	v_mul_f32_e32 v1, v2, v1
	v_fma_f32 v1, v2, v1, v2
	v_mul_f32_e32 v1, 0xbfcc422a, v1
	v_mul_f32_e32 v1, 0x3fb8aa3b, v1
	v_mul_f32_e32 v0, 0x3d372713, v6
	v_exp_f32_e32 v4, v1
	v_mul_f32_e32 v1, 0x3d372713, v7
	v_mul_f32_e32 v0, v6, v0
	v_mul_f32_e32 v1, v7, v1
	v_fma_f32 v0, v6, v0, v6
	v_fma_f32 v1, v7, v1, v7
	v_mul_f32_e32 v0, 0xbfcc422a, v0
	v_mul_f32_e32 v1, 0xbfcc422a, v1
	v_mul_f32_e32 v0, 0x3fb8aa3b, v0
	v_mul_f32_e32 v1, 0x3fb8aa3b, v1
	v_exp_f32_e32 v0, v0
	v_exp_f32_e32 v1, v1
	s_nop 0
	v_pk_add_f32 v[0:1], v[0:1], 1.0 op_sel_hi:[1,0]
	s_nop 0
	s_nop 0
	v_rcp_f32_e32 v5, v1
	s_nop 0
	v_mul_f32_e32 v7, v7, v5
	s_nop 0
	v_rcp_f32_e32 v1, v0
	s_nop 0
	v_mul_f32_e32 v6, v6, v1
	v_mul_f32_e32 v0, 0x3d372713, v3
	v_mul_f32_e32 v0, v3, v0
	v_fma_f32 v0, v3, v0, v3
	v_mul_f32_e32 v0, 0xbfcc422a, v0
	v_mul_f32_e32 v0, 0x3fb8aa3b, v0
	v_exp_f32_e32 v5, v0
	s_nop 0
	v_pk_add_f32 v[0:1], v[4:5], 1.0 op_sel_hi:[1,0]
	s_nop 0
	s_nop 0
	v_rcp_f32_e32 v4, v1
	s_nop 0
	v_mul_f32_e32 v3, v3, v4
	s_mov_b64 s[12:13], s[6:7]
	v_rcp_f32_e32 v1, v0
	s_nop 0
	v_mul_f32_e32 v4, v2, v1
	v_cvt_pk_bf16_f32 v3, v4, v3
	v_lshl_add_u64 v[4:5], v[8:9], 0, v[114:115]
	v_lshl_add_u64 v[4:5], v[4:5], 0, s[10:11]
	v_cvt_pk_bf16_f32 v0, v10, v11
	v_cvt_pk_bf16_f32 v1, v6, v7
	v_cvt_pk_bf16_f32 v2, v13, v12
	v_lshl_add_u64 v[4:5], v[4:5], 0, v[48:49]
	s_and_b64 vcc, exec, s[8:9]
	s_mov_b64 s[10:11], s[4:5]
	global_store_dwordx4 v[4:5], v[0:3], off
	s_cbranch_vccz .LBB0_819
	s_waitcnt vmcnt(0)
	s_cmpk_gt_u32 s18, 0xff
	s_cbranch_scc1 .LBB0_826
	s_barrier

.LBB0_1056:
	s_add_i32 s56, s28, 2
	s_add_u32 s29, s24, 0xfffc0080
	s_addc_u32 s30, s25, -1
	s_add_i32 s57, 0, 0x10000
	ds_read_b128 v[130:133], v203
	ds_read_b128 v[134:137], v203 offset:1024
	ds_read_b128 v[138:141], v203 offset:2048
	ds_read_b128 v[142:145], v203 offset:3072
	s_cmp_eq_u32 s17, s28
	s_cselect_b32 s28, s22, s19
	s_cselect_b32 s31, s21, s30
	s_cselect_b32 s30, s20, s29
	s_cselect_b32 s29, s23, s27
	s_add_i32 m0, s39, 0xc000
	ds_read_b128 v[146:149], v217
	ds_read_b128 v[150:153], v217 offset:1024
	ds_read_b128 v[154:157], v217 offset:2048
	ds_read_b128 v[158:161], v217 offset:3072
	ds_read_b128 v[162:165], v217 offset:4096
	ds_read_b128 v[166:169], v217 offset:5120
	ds_read_b128 v[170:173], v217 offset:6144
	ds_read_b128 v[174:177], v217 offset:7168
	global_load_lds_dwordx4 v204, s[24:25]
	s_add_i32 m0, s39, 0xe000
	s_nop 0
	global_load_lds_dwordx4 v206, s[24:25]
	s_waitcnt lgkmcnt(8)
	s_barrier
	s_waitcnt lgkmcnt(0)
	s_setprio 1
	s_waitcnt lgkmcnt(0)
	v_mfma_f32_16x16x32_bf16 v[126:129], v[130:133], v[146:149], v[126:129]
	v_mfma_f32_16x16x32_bf16 v[122:125], v[138:141], v[146:149], v[122:125]
	v_mfma_f32_16x16x32_bf16 v[118:121], v[130:133], v[154:157], v[118:121]
	v_mfma_f32_16x16x32_bf16 v[114:117], v[138:141], v[154:157], v[114:117]
	v_mfma_f32_16x16x32_bf16 v[102:105], v[130:133], v[162:165], v[102:105]
	v_mfma_f32_16x16x32_bf16 v[98:101], v[138:141], v[162:165], v[98:101]
	v_mfma_f32_16x16x32_bf16 v[86:89], v[130:133], v[170:173], v[86:89]
	v_mfma_f32_16x16x32_bf16 v[82:85], v[138:141], v[170:173], v[82:85]
	v_mfma_f32_16x16x32_bf16 v[126:129], v[134:137], v[150:153], v[126:129]
	v_mfma_f32_16x16x32_bf16 v[122:125], v[142:145], v[150:153], v[122:125]
	v_mfma_f32_16x16x32_bf16 v[118:121], v[134:137], v[158:161], v[118:121]
	v_mfma_f32_16x16x32_bf16 v[114:117], v[142:145], v[158:161], v[114:117]
	v_mfma_f32_16x16x32_bf16 v[102:105], v[134:137], v[166:169], v[102:105]
	v_mfma_f32_16x16x32_bf16 v[98:101], v[142:145], v[166:169], v[98:101]
	v_mfma_f32_16x16x32_bf16 v[86:89], v[134:137], v[174:177], v[86:89]
	v_mfma_f32_16x16x32_bf16 v[82:85], v[142:145], v[174:177], v[82:85]
	s_setprio 0
	s_barrier
	s_add_i32 s60, 0, 0x14000
	s_add_i32 s57, s57, s38
	s_mov_b32 m0, s57
	ds_read_b128 v[178:181], v203 offset:16384
	ds_read_b128 v[182:185], v203 offset:17408
	ds_read_b128 v[186:189], v203 offset:18432
	ds_read_b128 v[190:193], v203 offset:19456
	global_load_lds_dwordx4 v48, s[28:29]
	s_add_i32 m0, s57, 0x2000
	s_nop 0
	global_load_lds_dwordx4 v202, s[28:29]
	s_barrier
	s_waitcnt lgkmcnt(0)
	s_setprio 1
	s_waitcnt lgkmcnt(0)
	v_mfma_f32_16x16x32_bf16 v[110:113], v[178:181], v[146:149], v[110:113]
	v_mfma_f32_16x16x32_bf16 v[106:109], v[186:189], v[146:149], v[106:109]
	v_mfma_f32_16x16x32_bf16 v[94:97], v[178:181], v[154:157], v[94:97]
	v_mfma_f32_16x16x32_bf16 v[90:93], v[186:189], v[154:157], v[90:93]
	v_mfma_f32_16x16x32_bf16 v[78:81], v[178:181], v[162:165], v[78:81]
	v_mfma_f32_16x16x32_bf16 v[74:77], v[186:189], v[162:165], v[74:77]
	v_mfma_f32_16x16x32_bf16 v[70:73], v[178:181], v[170:173], v[70:73]
	v_mfma_f32_16x16x32_bf16 v[66:69], v[186:189], v[170:173], v[66:69]
	v_mfma_f32_16x16x32_bf16 v[110:113], v[182:185], v[150:153], v[110:113]
	v_mfma_f32_16x16x32_bf16 v[106:109], v[190:193], v[150:153], v[106:109]
	v_mfma_f32_16x16x32_bf16 v[94:97], v[182:185], v[158:161], v[94:97]
	v_mfma_f32_16x16x32_bf16 v[90:93], v[190:193], v[158:161], v[90:93]
	v_mfma_f32_16x16x32_bf16 v[78:81], v[182:185], v[166:169], v[78:81]
	v_mfma_f32_16x16x32_bf16 v[74:77], v[190:193], v[166:169], v[74:77]
	v_mfma_f32_16x16x32_bf16 v[70:73], v[182:185], v[174:177], v[70:73]
	v_mfma_f32_16x16x32_bf16 v[66:69], v[190:193], v[174:177], v[66:69]
	s_setprio 0
	s_mov_b32 m0, s39
	v_lshl_add_u64 v[212:213], s[30:31], 0, v[198:199]
	s_barrier
	ds_read_b128 v[146:149], v217 offset:16384
	ds_read_b128 v[150:153], v217 offset:17408
	ds_read_b128 v[154:157], v217 offset:18432
	ds_read_b128 v[158:161], v217 offset:19456
	ds_read_b128 v[162:165], v217 offset:20480
	ds_read_b128 v[166:169], v217 offset:21504
	ds_read_b128 v[170:173], v217 offset:22528
	ds_read_b128 v[174:177], v217 offset:23552
	global_load_lds_dwordx4 v[212:213], off
	v_lshl_add_u64 v[218:219], s[30:31], 0, v[200:201]
	s_mov_b32 m0, s40
	s_nop 0
	global_load_lds_dwordx4 v[218:219], off
	s_barrier
	s_waitcnt lgkmcnt(0)
	s_setprio 1
	s_waitcnt lgkmcnt(0)
	v_mfma_f32_16x16x32_bf16 v[62:65], v[130:133], v[146:149], v[62:65]
	v_mfma_f32_16x16x32_bf16 v[58:61], v[138:141], v[146:149], v[58:61]
	v_mfma_f32_16x16x32_bf16 v[54:57], v[130:133], v[154:157], v[54:57]
	v_mfma_f32_16x16x32_bf16 v[50:53], v[138:141], v[154:157], v[50:53]
	v_mfma_f32_16x16x32_bf16 v[36:39], v[130:133], v[162:165], v[36:39]
	v_mfma_f32_16x16x32_bf16 v[32:35], v[138:141], v[162:165], v[32:35]
	v_mfma_f32_16x16x32_bf16 v[20:23], v[130:133], v[170:173], v[20:23]
	v_mfma_f32_16x16x32_bf16 v[16:19], v[138:141], v[170:173], v[16:19]
	v_mfma_f32_16x16x32_bf16 v[62:65], v[134:137], v[150:153], v[62:65]
	v_mfma_f32_16x16x32_bf16 v[58:61], v[142:145], v[150:153], v[58:61]
	v_mfma_f32_16x16x32_bf16 v[54:57], v[134:137], v[158:161], v[54:57]
	v_mfma_f32_16x16x32_bf16 v[50:53], v[142:145], v[158:161], v[50:53]
	v_mfma_f32_16x16x32_bf16 v[36:39], v[134:137], v[166:169], v[36:39]
	v_mfma_f32_16x16x32_bf16 v[32:35], v[142:145], v[166:169], v[32:35]
	v_mfma_f32_16x16x32_bf16 v[20:23], v[134:137], v[174:177], v[20:23]
	v_mfma_f32_16x16x32_bf16 v[16:19], v[142:145], v[174:177], v[16:19]
	s_setprio 0
	s_barrier
	s_add_u32 s58, s28, 0x40000
	s_addc_u32 s59, s29, 0
	s_add_i32 s57, s60, s38
	s_mov_b32 m0, s57
	s_nop 0
	global_load_lds_dwordx4 v48, s[58:59]
	s_add_i32 m0, s57, 0x2000
	s_nop 0
	global_load_lds_dwordx4 v202, s[58:59]
	s_waitcnt vmcnt(6)
	s_barrier
	s_setprio 1
	v_mfma_f32_16x16x32_bf16 v[44:47], v[178:181], v[146:149], v[44:47]
	v_mfma_f32_16x16x32_bf16 v[40:43], v[186:189], v[146:149], v[40:43]
	v_mfma_f32_16x16x32_bf16 v[28:31], v[178:181], v[154:157], v[28:31]
	v_mfma_f32_16x16x32_bf16 v[24:27], v[186:189], v[154:157], v[24:27]
	v_mfma_f32_16x16x32_bf16 v[12:15], v[178:181], v[162:165], v[12:15]
	v_mfma_f32_16x16x32_bf16 v[8:11], v[186:189], v[162:165], v[8:11]
	v_mfma_f32_16x16x32_bf16 v[4:7], v[178:181], v[170:173], v[4:7]
	v_mfma_f32_16x16x32_bf16 v[0:3], v[186:189], v[170:173], v[0:3]
	v_mfma_f32_16x16x32_bf16 v[44:47], v[182:185], v[150:153], v[44:47]
	v_mfma_f32_16x16x32_bf16 v[40:43], v[190:193], v[150:153], v[40:43]
	v_mfma_f32_16x16x32_bf16 v[28:31], v[182:185], v[158:161], v[28:31]
	v_mfma_f32_16x16x32_bf16 v[24:27], v[190:193], v[158:161], v[24:27]
	v_mfma_f32_16x16x32_bf16 v[12:15], v[182:185], v[166:169], v[12:15]
	v_mfma_f32_16x16x32_bf16 v[8:11], v[190:193], v[166:169], v[8:11]
	v_mfma_f32_16x16x32_bf16 v[4:7], v[182:185], v[174:177], v[4:7]
	v_mfma_f32_16x16x32_bf16 v[0:3], v[190:193], v[174:177], v[0:3]
	s_setprio 0
	s_add_i32 s57, 0, 0x18000
	s_barrier
	ds_read_b128 v[130:133], v203 offset:32768
	ds_read_b128 v[134:137], v203 offset:33792
	ds_read_b128 v[138:141], v203 offset:34816
	ds_read_b128 v[142:145], v203 offset:35840
	s_add_u32 s30, s30, 0x40000
	s_addc_u32 s31, s31, 0
	s_mov_b32 m0, s41
	ds_read_b128 v[146:149], v217 offset:32768
	ds_read_b128 v[150:153], v217 offset:33792
	ds_read_b128 v[154:157], v217 offset:34816
	ds_read_b128 v[158:161], v217 offset:35840
	ds_read_b128 v[162:165], v217 offset:36864
	ds_read_b128 v[166:169], v217 offset:37888
	ds_read_b128 v[170:173], v217 offset:38912
	ds_read_b128 v[174:177], v217 offset:39936
	global_load_lds_dwordx4 v198, s[30:31]
	s_mov_b32 m0, s42
	s_nop 0
	global_load_lds_dwordx4 v200, s[30:31]
	s_waitcnt lgkmcnt(8)
	s_barrier
	s_waitcnt lgkmcnt(0)
	s_setprio 1
	s_waitcnt lgkmcnt(0)
	v_mfma_f32_16x16x32_bf16 v[126:129], v[130:133], v[146:149], v[126:129]
	v_mfma_f32_16x16x32_bf16 v[122:125], v[138:141], v[146:149], v[122:125]
	v_mfma_f32_16x16x32_bf16 v[118:121], v[130:133], v[154:157], v[118:121]
	v_mfma_f32_16x16x32_bf16 v[114:117], v[138:141], v[154:157], v[114:117]
	v_mfma_f32_16x16x32_bf16 v[102:105], v[130:133], v[162:165], v[102:105]
	v_mfma_f32_16x16x32_bf16 v[98:101], v[138:141], v[162:165], v[98:101]
	v_mfma_f32_16x16x32_bf16 v[86:89], v[130:133], v[170:173], v[86:89]
	v_mfma_f32_16x16x32_bf16 v[82:85], v[138:141], v[170:173], v[82:85]
	v_mfma_f32_16x16x32_bf16 v[126:129], v[134:137], v[150:153], v[126:129]
	v_mfma_f32_16x16x32_bf16 v[122:125], v[142:145], v[150:153], v[122:125]
	v_mfma_f32_16x16x32_bf16 v[118:121], v[134:137], v[158:161], v[118:121]
	v_mfma_f32_16x16x32_bf16 v[114:117], v[142:145], v[158:161], v[114:117]
	v_mfma_f32_16x16x32_bf16 v[102:105], v[134:137], v[166:169], v[102:105]
	v_mfma_f32_16x16x32_bf16 v[98:101], v[142:145], v[166:169], v[98:101]
	v_mfma_f32_16x16x32_bf16 v[86:89], v[134:137], v[174:177], v[86:89]
	v_mfma_f32_16x16x32_bf16 v[82:85], v[142:145], v[174:177], v[82:85]
	s_setprio 0
	s_barrier
	s_add_i32 s30, 0, 0x1c000
	s_add_i32 s31, s57, s38
	s_add_u32 s58, s28, s66
	s_addc_u32 s59, s29, s67
	s_mov_b32 m0, s31
	ds_read_b128 v[178:181], v203 offset:49152
	ds_read_b128 v[182:185], v203 offset:50176
	ds_read_b128 v[186:189], v203 offset:51200
	ds_read_b128 v[190:193], v203 offset:52224
	global_load_lds_dwordx4 v48, s[58:59]
	s_add_i32 m0, s31, 0x2000
	s_nop 0
	global_load_lds_dwordx4 v202, s[58:59]
	s_barrier
	s_waitcnt lgkmcnt(0)
	s_setprio 1
	s_waitcnt lgkmcnt(0)
	v_mfma_f32_16x16x32_bf16 v[110:113], v[178:181], v[146:149], v[110:113]
	v_mfma_f32_16x16x32_bf16 v[106:109], v[186:189], v[146:149], v[106:109]
	v_mfma_f32_16x16x32_bf16 v[94:97], v[178:181], v[154:157], v[94:97]
	v_mfma_f32_16x16x32_bf16 v[90:93], v[186:189], v[154:157], v[90:93]
	v_mfma_f32_16x16x32_bf16 v[78:81], v[178:181], v[162:165], v[78:81]
	v_mfma_f32_16x16x32_bf16 v[74:77], v[186:189], v[162:165], v[74:77]
	v_mfma_f32_16x16x32_bf16 v[70:73], v[178:181], v[170:173], v[70:73]
	v_mfma_f32_16x16x32_bf16 v[66:69], v[186:189], v[170:173], v[66:69]
	v_mfma_f32_16x16x32_bf16 v[110:113], v[182:185], v[150:153], v[110:113]
	v_mfma_f32_16x16x32_bf16 v[106:109], v[190:193], v[150:153], v[106:109]
	v_mfma_f32_16x16x32_bf16 v[94:97], v[182:185], v[158:161], v[94:97]
	v_mfma_f32_16x16x32_bf16 v[90:93], v[190:193], v[158:161], v[90:93]
	v_mfma_f32_16x16x32_bf16 v[78:81], v[182:185], v[166:169], v[78:81]
	v_mfma_f32_16x16x32_bf16 v[74:77], v[190:193], v[166:169], v[74:77]
	v_mfma_f32_16x16x32_bf16 v[70:73], v[182:185], v[174:177], v[70:73]
	v_mfma_f32_16x16x32_bf16 v[66:69], v[190:193], v[174:177], v[66:69]
	s_setprio 0
	s_mov_b32 m0, s49
	v_lshl_add_u64 v[208:209], v[212:213], 0, s[66:67]
	s_barrier
	ds_read_b128 v[146:149], v217 offset:49152
	ds_read_b128 v[150:153], v217 offset:50176
	ds_read_b128 v[154:157], v217 offset:51200
	ds_read_b128 v[158:161], v217 offset:52224
	ds_read_b128 v[162:165], v217 offset:53248
	ds_read_b128 v[166:169], v217 offset:54272
	ds_read_b128 v[170:173], v217 offset:55296
	ds_read_b128 v[174:177], v217 offset:56320
	global_load_lds_dwordx4 v[208:209], off
	v_lshl_add_u64 v[208:209], v[218:219], 0, s[66:67]
	s_mov_b32 m0, s50
	s_nop 0
	global_load_lds_dwordx4 v[208:209], off
	s_barrier
	s_waitcnt lgkmcnt(0)
	s_setprio 1
	s_waitcnt lgkmcnt(0)
	v_mfma_f32_16x16x32_bf16 v[62:65], v[130:133], v[146:149], v[62:65]
	v_mfma_f32_16x16x32_bf16 v[58:61], v[138:141], v[146:149], v[58:61]
	v_mfma_f32_16x16x32_bf16 v[54:57], v[130:133], v[154:157], v[54:57]
	v_mfma_f32_16x16x32_bf16 v[50:53], v[138:141], v[154:157], v[50:53]
	v_mfma_f32_16x16x32_bf16 v[36:39], v[130:133], v[162:165], v[36:39]
	v_mfma_f32_16x16x32_bf16 v[32:35], v[138:141], v[162:165], v[32:35]
	v_mfma_f32_16x16x32_bf16 v[20:23], v[130:133], v[170:173], v[20:23]
	v_mfma_f32_16x16x32_bf16 v[16:19], v[138:141], v[170:173], v[16:19]
	v_mfma_f32_16x16x32_bf16 v[62:65], v[134:137], v[150:153], v[62:65]
	v_mfma_f32_16x16x32_bf16 v[58:61], v[142:145], v[150:153], v[58:61]
	v_mfma_f32_16x16x32_bf16 v[54:57], v[134:137], v[158:161], v[54:57]
	v_mfma_f32_16x16x32_bf16 v[50:53], v[142:145], v[158:161], v[50:53]
	v_mfma_f32_16x16x32_bf16 v[36:39], v[134:137], v[166:169], v[36:39]
	v_mfma_f32_16x16x32_bf16 v[32:35], v[142:145], v[166:169], v[32:35]
	v_mfma_f32_16x16x32_bf16 v[20:23], v[134:137], v[174:177], v[20:23]
	v_mfma_f32_16x16x32_bf16 v[16:19], v[142:145], v[174:177], v[16:19]
	s_setprio 0
	s_barrier
	s_add_u32 s28, s28, 0x40080
	s_addc_u32 s29, s29, 0
	s_add_i32 s30, s30, s38
	s_mov_b32 m0, s30
	s_nop 0
	global_load_lds_dwordx4 v48, s[28:29]
	s_add_i32 m0, s30, 0x2000
	s_nop 0
	global_load_lds_dwordx4 v202, s[28:29]
	s_waitcnt vmcnt(6)
	s_barrier
	s_setprio 1
	v_mfma_f32_16x16x32_bf16 v[44:47], v[178:181], v[146:149], v[44:47]
	v_mfma_f32_16x16x32_bf16 v[40:43], v[186:189], v[146:149], v[40:43]
	v_mfma_f32_16x16x32_bf16 v[28:31], v[178:181], v[154:157], v[28:31]
	v_mfma_f32_16x16x32_bf16 v[24:27], v[186:189], v[154:157], v[24:27]
	v_mfma_f32_16x16x32_bf16 v[12:15], v[178:181], v[162:165], v[12:15]
	v_mfma_f32_16x16x32_bf16 v[8:11], v[186:189], v[162:165], v[8:11]
	v_mfma_f32_16x16x32_bf16 v[4:7], v[178:181], v[170:173], v[4:7]
	v_mfma_f32_16x16x32_bf16 v[0:3], v[186:189], v[170:173], v[0:3]
	v_mfma_f32_16x16x32_bf16 v[44:47], v[182:185], v[150:153], v[44:47]
	v_mfma_f32_16x16x32_bf16 v[40:43], v[190:193], v[150:153], v[40:43]
	v_mfma_f32_16x16x32_bf16 v[28:31], v[182:185], v[158:161], v[28:31]
	v_mfma_f32_16x16x32_bf16 v[24:27], v[190:193], v[158:161], v[24:27]
	v_mfma_f32_16x16x32_bf16 v[12:15], v[182:185], v[166:169], v[12:15]
	v_mfma_f32_16x16x32_bf16 v[8:11], v[190:193], v[166:169], v[8:11]
	v_mfma_f32_16x16x32_bf16 v[4:7], v[182:185], v[174:177], v[4:7]
	v_mfma_f32_16x16x32_bf16 v[0:3], v[190:193], v[174:177], v[0:3]
	s_setprio 0
	s_add_u32 s24, s24, 0x100
	s_addc_u32 s25, s25, 0
	s_add_u32 s19, s19, 0x100
	s_addc_u32 s27, s27, 0
	s_cmp_ge_i32 s56, s1
	s_mov_b32 s28, s56
	s_barrier
	s_cbranch_scc0 .LBB0_1056
	v_mov_b32_e32 v130, v214
	v_mov_b32_e32 v131, v215
	s_bitcmp1_b32 s55, 0
	v_add_u32_e32 v134, s47, v130
	v_lshlrev_b32_e32 v130, 8, v134
	v_lshl_add_u32 v132, v131, 3, s48
	v_ashrrev_i32_e32 v131, 31, v130
	v_lshl_add_u64 v[130:131], v[130:131], 1, s[12:13]
	v_ashrrev_i32_e32 v133, 31, v132
	s_cselect_b64 s[28:29], -1, 0
	v_lshlrev_b32_e32 v208, 9, v215
	v_lshl_add_u32 v208, v214, 4, v208
	v_lshl_add_u32 v208, s47, 9, v208
	v_lshl_add_u32 v208, s48, 6, v208
	v_mov_b32_e32 v209, 0
	v_lshl_add_u64 v[208:209], v[208:209], 0, s[12:13]
	s_mov_b64 s[24:25], -1
	s_and_b64 vcc, exec, s[28:29]
	s_mov_b32 s57, s81
	s_cbranch_vccz .LBB0_1093
	s_mov_b64 s[24:25], 0x20000
	v_lshl_add_u64 v[130:131], v[208:209], 0, s[24:25]
	s_and_b32 s1, s55, -2
	s_mov_b64 s[24:25], 0x100
	s_cmp_lg_u32 s1, 4
	v_mov_b64_e32 v[210:211], v[130:131]
	s_cbranch_scc1 .LBB0_1060
	v_lshl_add_u32 v134, s26, 8, v134
	v_ashrrev_i32_e32 v135, 31, v134
	v_lshlrev_b64 v[134:135], 11, v[134:135]
	s_lshl_b32 s0, s0, 8
	v_lshl_add_u64 v[134:135], s[14:15], 0, v[134:135]
	s_ashr_i32 s1, s0, 31
	v_lshl_add_u64 v[134:135], s[0:1], 1, v[134:135]
	v_lshl_add_u64 v[210:211], v[132:133], 1, v[134:135]
	s_mov_b64 s[24:25], 0x400

.LBB0_1219:
	s_add_u32 s26, s24, 0xfffc0080
	s_addc_u32 s27, s25, -1
	s_add_i32 s31, 0, 0x10000
	ds_read_b128 v[130:133], v201
	ds_read_b128 v[134:137], v201 offset:1024
	ds_read_b128 v[138:141], v201 offset:2048
	ds_read_b128 v[142:145], v201 offset:3072
	s_cmp_eq_u32 s30, 12
	s_cselect_b32 s29, s19, s27
	s_cselect_b32 s28, s18, s26
	s_cselect_b32 s27, s21, s17
	s_cselect_b32 s26, s20, s15
	s_add_i32 m0, s41, 0xc000
	ds_read_b128 v[146:149], v210
	ds_read_b128 v[150:153], v210 offset:1024
	ds_read_b128 v[154:157], v210 offset:2048
	ds_read_b128 v[158:161], v210 offset:3072
	ds_read_b128 v[162:165], v210 offset:4096
	ds_read_b128 v[166:169], v210 offset:5120
	ds_read_b128 v[170:173], v210 offset:6144
	ds_read_b128 v[174:177], v210 offset:7168
	global_load_lds_dwordx4 v200, s[24:25]
	s_add_i32 m0, s41, 0xe000
	s_nop 0
	global_load_lds_dwordx4 v202, s[24:25]
	s_waitcnt lgkmcnt(8)
	s_barrier
	s_waitcnt lgkmcnt(0)
	s_setprio 1
	s_waitcnt lgkmcnt(0)
	v_mfma_f32_16x16x32_bf16 v[126:129], v[130:133], v[146:149], v[126:129]
	v_mfma_f32_16x16x32_bf16 v[122:125], v[138:141], v[146:149], v[122:125]
	v_mfma_f32_16x16x32_bf16 v[118:121], v[130:133], v[154:157], v[118:121]
	v_mfma_f32_16x16x32_bf16 v[106:109], v[138:141], v[154:157], v[106:109]
	v_mfma_f32_16x16x32_bf16 v[94:97], v[130:133], v[162:165], v[94:97]
	v_mfma_f32_16x16x32_bf16 v[90:93], v[138:141], v[162:165], v[90:93]
	v_mfma_f32_16x16x32_bf16 v[86:89], v[130:133], v[170:173], v[86:89]
	v_mfma_f32_16x16x32_bf16 v[74:77], v[138:141], v[170:173], v[74:77]
	v_mfma_f32_16x16x32_bf16 v[126:129], v[134:137], v[150:153], v[126:129]
	v_mfma_f32_16x16x32_bf16 v[122:125], v[142:145], v[150:153], v[122:125]
	v_mfma_f32_16x16x32_bf16 v[118:121], v[134:137], v[158:161], v[118:121]
	v_mfma_f32_16x16x32_bf16 v[106:109], v[142:145], v[158:161], v[106:109]
	v_mfma_f32_16x16x32_bf16 v[94:97], v[134:137], v[166:169], v[94:97]
	v_mfma_f32_16x16x32_bf16 v[90:93], v[142:145], v[166:169], v[90:93]
	v_mfma_f32_16x16x32_bf16 v[86:89], v[134:137], v[174:177], v[86:89]
	v_mfma_f32_16x16x32_bf16 v[74:77], v[142:145], v[174:177], v[74:77]
	s_setprio 0
	s_barrier
	s_add_i32 s50, 0, 0x14000
	s_add_i32 s31, s31, s40
	s_mov_b32 m0, s31
	ds_read_b128 v[178:181], v201 offset:16384
	ds_read_b128 v[182:185], v201 offset:17408
	ds_read_b128 v[186:189], v201 offset:18432
	ds_read_b128 v[204:207], v201 offset:19456
	global_load_lds_dwordx4 v48, s[26:27]
	s_add_i32 m0, s31, 0x2000
	s_nop 0
	global_load_lds_dwordx4 v190, s[26:27]
	s_barrier
	s_waitcnt lgkmcnt(0)
	s_setprio 1
	s_waitcnt lgkmcnt(0)
	v_mfma_f32_16x16x32_bf16 v[114:117], v[178:181], v[146:149], v[114:117]
	v_mfma_f32_16x16x32_bf16 v[110:113], v[186:189], v[146:149], v[110:113]
	v_mfma_f32_16x16x32_bf16 v[102:105], v[178:181], v[154:157], v[102:105]
	v_mfma_f32_16x16x32_bf16 v[98:101], v[186:189], v[154:157], v[98:101]
	v_mfma_f32_16x16x32_bf16 v[82:85], v[178:181], v[162:165], v[82:85]
	v_mfma_f32_16x16x32_bf16 v[78:81], v[186:189], v[162:165], v[78:81]
	v_mfma_f32_16x16x32_bf16 v[70:73], v[178:181], v[170:173], v[70:73]
	v_mfma_f32_16x16x32_bf16 v[66:69], v[186:189], v[170:173], v[66:69]
	v_mfma_f32_16x16x32_bf16 v[114:117], v[182:185], v[150:153], v[114:117]
	v_mfma_f32_16x16x32_bf16 v[110:113], v[204:207], v[150:153], v[110:113]
	v_mfma_f32_16x16x32_bf16 v[102:105], v[182:185], v[158:161], v[102:105]
	v_mfma_f32_16x16x32_bf16 v[98:101], v[204:207], v[158:161], v[98:101]
	v_mfma_f32_16x16x32_bf16 v[82:85], v[182:185], v[166:169], v[82:85]
	v_mfma_f32_16x16x32_bf16 v[78:81], v[204:207], v[166:169], v[78:81]
	v_mfma_f32_16x16x32_bf16 v[70:73], v[182:185], v[174:177], v[70:73]
	v_mfma_f32_16x16x32_bf16 v[66:69], v[204:207], v[174:177], v[66:69]
	s_setprio 0
	s_mov_b32 m0, s41
	v_lshl_add_u64 v[216:217], s[28:29], 0, v[48:49]
	s_barrier
	ds_read_b128 v[146:149], v210 offset:16384
	ds_read_b128 v[150:153], v210 offset:17408
	ds_read_b128 v[154:157], v210 offset:18432
	ds_read_b128 v[158:161], v210 offset:19456
	ds_read_b128 v[162:165], v210 offset:20480
	ds_read_b128 v[166:169], v210 offset:21504
	ds_read_b128 v[170:173], v210 offset:22528
	ds_read_b128 v[174:177], v210 offset:23552
	global_load_lds_dwordx4 v[216:217], off
	v_lshl_add_u64 v[218:219], s[28:29], 0, v[190:191]
	s_mov_b32 m0, s42
	s_nop 0
	global_load_lds_dwordx4 v[218:219], off
	s_barrier
	s_waitcnt lgkmcnt(0)
	s_setprio 1
	s_waitcnt lgkmcnt(0)
	v_mfma_f32_16x16x32_bf16 v[62:65], v[130:133], v[146:149], v[62:65]
	v_mfma_f32_16x16x32_bf16 v[58:61], v[138:141], v[146:149], v[58:61]
	v_mfma_f32_16x16x32_bf16 v[54:57], v[130:133], v[154:157], v[54:57]
	v_mfma_f32_16x16x32_bf16 v[40:43], v[138:141], v[154:157], v[40:43]
	v_mfma_f32_16x16x32_bf16 v[36:39], v[130:133], v[162:165], v[36:39]
	v_mfma_f32_16x16x32_bf16 v[24:27], v[138:141], v[162:165], v[24:27]
	v_mfma_f32_16x16x32_bf16 v[20:23], v[130:133], v[170:173], v[20:23]
	v_mfma_f32_16x16x32_bf16 v[8:11], v[138:141], v[170:173], v[8:11]
	v_mfma_f32_16x16x32_bf16 v[62:65], v[134:137], v[150:153], v[62:65]
	v_mfma_f32_16x16x32_bf16 v[58:61], v[142:145], v[150:153], v[58:61]
	v_mfma_f32_16x16x32_bf16 v[54:57], v[134:137], v[158:161], v[54:57]
	v_mfma_f32_16x16x32_bf16 v[40:43], v[142:145], v[158:161], v[40:43]
	v_mfma_f32_16x16x32_bf16 v[36:39], v[134:137], v[166:169], v[36:39]
	v_mfma_f32_16x16x32_bf16 v[24:27], v[142:145], v[166:169], v[24:27]
	v_mfma_f32_16x16x32_bf16 v[20:23], v[134:137], v[174:177], v[20:23]
	v_mfma_f32_16x16x32_bf16 v[8:11], v[142:145], v[174:177], v[8:11]
	s_setprio 0
	s_barrier
	s_add_u32 s34, s26, 0x40000
	s_addc_u32 s35, s27, 0
	s_add_i32 s31, s50, s40
	s_mov_b32 m0, s31
	s_nop 0
	global_load_lds_dwordx4 v48, s[34:35]
	s_add_i32 m0, s31, 0x2000
	s_nop 0
	global_load_lds_dwordx4 v190, s[34:35]
	s_waitcnt vmcnt(6)
	s_barrier
	s_setprio 1
	v_mfma_f32_16x16x32_bf16 v[50:53], v[178:181], v[146:149], v[50:53]
	v_mfma_f32_16x16x32_bf16 v[44:47], v[186:189], v[146:149], v[44:47]
	v_mfma_f32_16x16x32_bf16 v[32:35], v[178:181], v[154:157], v[32:35]
	v_mfma_f32_16x16x32_bf16 v[28:31], v[186:189], v[154:157], v[28:31]
	v_mfma_f32_16x16x32_bf16 v[16:19], v[178:181], v[162:165], v[16:19]
	v_mfma_f32_16x16x32_bf16 v[12:15], v[186:189], v[162:165], v[12:15]
	v_mfma_f32_16x16x32_bf16 v[4:7], v[178:181], v[170:173], v[4:7]
	v_mfma_f32_16x16x32_bf16 v[0:3], v[186:189], v[170:173], v[0:3]
	v_mfma_f32_16x16x32_bf16 v[50:53], v[182:185], v[150:153], v[50:53]
	v_mfma_f32_16x16x32_bf16 v[44:47], v[204:207], v[150:153], v[44:47]
	v_mfma_f32_16x16x32_bf16 v[32:35], v[182:185], v[158:161], v[32:35]
	v_mfma_f32_16x16x32_bf16 v[28:31], v[204:207], v[158:161], v[28:31]
	v_mfma_f32_16x16x32_bf16 v[16:19], v[182:185], v[166:169], v[16:19]
	v_mfma_f32_16x16x32_bf16 v[12:15], v[204:207], v[166:169], v[12:15]
	v_mfma_f32_16x16x32_bf16 v[4:7], v[182:185], v[174:177], v[4:7]
	v_mfma_f32_16x16x32_bf16 v[0:3], v[204:207], v[174:177], v[0:3]
	s_setprio 0
	s_add_i32 s31, 0, 0x18000
	s_barrier
	ds_read_b128 v[130:133], v201 offset:32768
	ds_read_b128 v[134:137], v201 offset:33792
	ds_read_b128 v[138:141], v201 offset:34816
	ds_read_b128 v[142:145], v201 offset:35840
	s_add_u32 s28, s28, 0x40000
	s_addc_u32 s29, s29, 0
	s_mov_b32 m0, s43
	ds_read_b128 v[146:149], v210 offset:32768
	ds_read_b128 v[150:153], v210 offset:33792
	ds_read_b128 v[154:157], v210 offset:34816
	ds_read_b128 v[158:161], v210 offset:35840
	ds_read_b128 v[162:165], v210 offset:36864
	ds_read_b128 v[166:169], v210 offset:37888
	ds_read_b128 v[170:173], v210 offset:38912
	ds_read_b128 v[174:177], v210 offset:39936
	global_load_lds_dwordx4 v48, s[28:29]
	s_mov_b32 m0, s44
	s_nop 0
	global_load_lds_dwordx4 v190, s[28:29]
	s_waitcnt lgkmcnt(8)
	s_barrier
	s_waitcnt lgkmcnt(0)
	s_setprio 1
	s_waitcnt lgkmcnt(0)
	v_mfma_f32_16x16x32_bf16 v[126:129], v[130:133], v[146:149], v[126:129]
	v_mfma_f32_16x16x32_bf16 v[122:125], v[138:141], v[146:149], v[122:125]
	v_mfma_f32_16x16x32_bf16 v[118:121], v[130:133], v[154:157], v[118:121]
	v_mfma_f32_16x16x32_bf16 v[106:109], v[138:141], v[154:157], v[106:109]
	v_mfma_f32_16x16x32_bf16 v[94:97], v[130:133], v[162:165], v[94:97]
	v_mfma_f32_16x16x32_bf16 v[90:93], v[138:141], v[162:165], v[90:93]
	v_mfma_f32_16x16x32_bf16 v[86:89], v[130:133], v[170:173], v[86:89]
	v_mfma_f32_16x16x32_bf16 v[74:77], v[138:141], v[170:173], v[74:77]
	v_mfma_f32_16x16x32_bf16 v[126:129], v[134:137], v[150:153], v[126:129]
	v_mfma_f32_16x16x32_bf16 v[122:125], v[142:145], v[150:153], v[122:125]
	v_mfma_f32_16x16x32_bf16 v[118:121], v[134:137], v[158:161], v[118:121]
	v_mfma_f32_16x16x32_bf16 v[106:109], v[142:145], v[158:161], v[106:109]
	v_mfma_f32_16x16x32_bf16 v[94:97], v[134:137], v[166:169], v[94:97]
	v_mfma_f32_16x16x32_bf16 v[90:93], v[142:145], v[166:169], v[90:93]
	v_mfma_f32_16x16x32_bf16 v[86:89], v[134:137], v[174:177], v[86:89]
	v_mfma_f32_16x16x32_bf16 v[74:77], v[142:145], v[174:177], v[74:77]
	s_setprio 0
	s_barrier
	s_add_i32 s28, 0, 0x1c000
	s_add_i32 s29, s31, s40
	s_add_u32 s52, s26, s66
	s_addc_u32 s53, s27, s67
	s_mov_b32 m0, s29
	ds_read_b128 v[178:181], v201 offset:49152
	ds_read_b128 v[182:185], v201 offset:50176
	ds_read_b128 v[186:189], v201 offset:51200
	ds_read_b128 v[204:207], v201 offset:52224
	global_load_lds_dwordx4 v48, s[52:53]
	s_add_i32 m0, s29, 0x2000
	s_nop 0
	global_load_lds_dwordx4 v190, s[52:53]
	s_barrier
	s_waitcnt lgkmcnt(0)
	s_setprio 1
	s_waitcnt lgkmcnt(0)
	v_mfma_f32_16x16x32_bf16 v[114:117], v[178:181], v[146:149], v[114:117]
	v_mfma_f32_16x16x32_bf16 v[110:113], v[186:189], v[146:149], v[110:113]
	v_mfma_f32_16x16x32_bf16 v[102:105], v[178:181], v[154:157], v[102:105]
	v_mfma_f32_16x16x32_bf16 v[98:101], v[186:189], v[154:157], v[98:101]
	v_mfma_f32_16x16x32_bf16 v[82:85], v[178:181], v[162:165], v[82:85]
	v_mfma_f32_16x16x32_bf16 v[78:81], v[186:189], v[162:165], v[78:81]
	v_mfma_f32_16x16x32_bf16 v[70:73], v[178:181], v[170:173], v[70:73]
	v_mfma_f32_16x16x32_bf16 v[66:69], v[186:189], v[170:173], v[66:69]
	v_mfma_f32_16x16x32_bf16 v[114:117], v[182:185], v[150:153], v[114:117]
	v_mfma_f32_16x16x32_bf16 v[110:113], v[204:207], v[150:153], v[110:113]
	v_mfma_f32_16x16x32_bf16 v[102:105], v[182:185], v[158:161], v[102:105]
	v_mfma_f32_16x16x32_bf16 v[98:101], v[204:207], v[158:161], v[98:101]
	v_mfma_f32_16x16x32_bf16 v[82:85], v[182:185], v[166:169], v[82:85]
	v_mfma_f32_16x16x32_bf16 v[78:81], v[204:207], v[166:169], v[78:81]
	v_mfma_f32_16x16x32_bf16 v[70:73], v[182:185], v[174:177], v[70:73]
	v_mfma_f32_16x16x32_bf16 v[66:69], v[204:207], v[174:177], v[66:69]
	s_setprio 0
	s_mov_b32 m0, s47
	v_lshl_add_u64 v[212:213], v[216:217], 0, s[66:67]
	s_barrier
	ds_read_b128 v[146:149], v210 offset:49152
	ds_read_b128 v[150:153], v210 offset:50176
	ds_read_b128 v[154:157], v210 offset:51200
	ds_read_b128 v[158:161], v210 offset:52224
	ds_read_b128 v[162:165], v210 offset:53248
	ds_read_b128 v[166:169], v210 offset:54272
	ds_read_b128 v[170:173], v210 offset:55296
	ds_read_b128 v[174:177], v210 offset:56320
	global_load_lds_dwordx4 v[212:213], off
	v_lshl_add_u64 v[212:213], v[218:219], 0, s[66:67]
	s_mov_b32 m0, s48
	s_nop 0
	global_load_lds_dwordx4 v[212:213], off
	s_barrier
	s_waitcnt lgkmcnt(0)
	s_setprio 1
	s_waitcnt lgkmcnt(0)
	v_mfma_f32_16x16x32_bf16 v[62:65], v[130:133], v[146:149], v[62:65]
	v_mfma_f32_16x16x32_bf16 v[58:61], v[138:141], v[146:149], v[58:61]
	v_mfma_f32_16x16x32_bf16 v[54:57], v[130:133], v[154:157], v[54:57]
	v_mfma_f32_16x16x32_bf16 v[40:43], v[138:141], v[154:157], v[40:43]
	v_mfma_f32_16x16x32_bf16 v[36:39], v[130:133], v[162:165], v[36:39]
	v_mfma_f32_16x16x32_bf16 v[24:27], v[138:141], v[162:165], v[24:27]
	v_mfma_f32_16x16x32_bf16 v[20:23], v[130:133], v[170:173], v[20:23]
	v_mfma_f32_16x16x32_bf16 v[8:11], v[138:141], v[170:173], v[8:11]
	v_mfma_f32_16x16x32_bf16 v[62:65], v[134:137], v[150:153], v[62:65]
	v_mfma_f32_16x16x32_bf16 v[58:61], v[142:145], v[150:153], v[58:61]
	v_mfma_f32_16x16x32_bf16 v[54:57], v[134:137], v[158:161], v[54:57]
	v_mfma_f32_16x16x32_bf16 v[40:43], v[142:145], v[158:161], v[40:43]
	v_mfma_f32_16x16x32_bf16 v[36:39], v[134:137], v[166:169], v[36:39]
	v_mfma_f32_16x16x32_bf16 v[24:27], v[142:145], v[166:169], v[24:27]
	v_mfma_f32_16x16x32_bf16 v[20:23], v[134:137], v[174:177], v[20:23]
	v_mfma_f32_16x16x32_bf16 v[8:11], v[142:145], v[174:177], v[8:11]
	s_setprio 0
	s_barrier
	s_add_u32 s26, s26, 0x40080
	s_addc_u32 s27, s27, 0
	s_add_i32 s28, s28, s40
	s_mov_b32 m0, s28
	s_nop 0
	global_load_lds_dwordx4 v48, s[26:27]
	s_add_i32 m0, s28, 0x2000
	s_nop 0
	global_load_lds_dwordx4 v190, s[26:27]
	s_waitcnt vmcnt(6)
	s_barrier
	s_setprio 1
	v_mfma_f32_16x16x32_bf16 v[50:53], v[178:181], v[146:149], v[50:53]
	v_mfma_f32_16x16x32_bf16 v[44:47], v[186:189], v[146:149], v[44:47]
	v_mfma_f32_16x16x32_bf16 v[32:35], v[178:181], v[154:157], v[32:35]
	v_mfma_f32_16x16x32_bf16 v[28:31], v[186:189], v[154:157], v[28:31]
	v_mfma_f32_16x16x32_bf16 v[16:19], v[178:181], v[162:165], v[16:19]
	v_mfma_f32_16x16x32_bf16 v[12:15], v[186:189], v[162:165], v[12:15]
	v_mfma_f32_16x16x32_bf16 v[4:7], v[178:181], v[170:173], v[4:7]
	v_mfma_f32_16x16x32_bf16 v[0:3], v[186:189], v[170:173], v[0:3]
	v_mfma_f32_16x16x32_bf16 v[50:53], v[182:185], v[150:153], v[50:53]
	v_mfma_f32_16x16x32_bf16 v[44:47], v[204:207], v[150:153], v[44:47]
	v_mfma_f32_16x16x32_bf16 v[32:35], v[182:185], v[158:161], v[32:35]
	v_mfma_f32_16x16x32_bf16 v[28:31], v[204:207], v[158:161], v[28:31]
	v_mfma_f32_16x16x32_bf16 v[16:19], v[182:185], v[166:169], v[16:19]
	v_mfma_f32_16x16x32_bf16 v[12:15], v[204:207], v[166:169], v[12:15]
	v_mfma_f32_16x16x32_bf16 v[4:7], v[182:185], v[174:177], v[4:7]
	v_mfma_f32_16x16x32_bf16 v[0:3], v[204:207], v[174:177], v[0:3]
	s_setprio 0
	s_add_i32 s30, s30, 2
	s_add_u32 s24, s24, 0x100
	s_addc_u32 s25, s25, 0
	s_add_u32 s15, s15, 0x100
	s_addc_u32 s17, s17, 0
	s_cmp_gt_u32 s30, 13
	s_barrier
	s_cbranch_scc0 .LBB0_1219
	s_mul_hi_i32 s15, s22, 0x38e38e39
	s_lshr_b32 s17, s15, 31
	s_ashr_i32 s15, s15, 1
	s_add_i32 s24, s15, s17
	s_mul_i32 s15, s24, -9
	s_add_i32 s28, s15, s22
	s_cmp_eq_u32 s28, 0
	s_cselect_b64 s[26:27], -1, 0
	s_ashr_i32 s25, s24, 31
	s_cmp_lg_u32 s28, 0
	s_cbranch_scc0 .LBB0_1222
	s_ashr_i32 s29, s28, 31
	s_lshl_b64 s[28:29], s[28:29], 18
	s_lshl_b64 s[30:31], s[24:25], 21
	s_add_u32 s15, s28, s30
	s_addc_u32 s17, s29, s31
	s_add_u32 s28, s15, 0xfffc0000
	s_addc_u32 s29, s17, -1
	s_mov_b64 s[30:31], s[6:7]
	s_cbranch_execnz .LBB0_1215
	s_branch .LBB0_1214

.LBB0_1356:
	s_add_u32 s28, s26, 0xfffc0080
	s_addc_u32 s29, s27, -1
	s_add_i32 s46, 0, 0x10000
	ds_read_b128 v[146:149], v137
	ds_read_b128 v[150:153], v137 offset:1024
	ds_read_b128 v[154:157], v137 offset:2048
	ds_read_b128 v[158:161], v137 offset:3072
	s_cmp_eq_u32 s45, 12
	s_cselect_b32 s31, s19, s29
	s_cselect_b32 s30, s18, s28
	s_cselect_b32 s29, s21, s17
	s_cselect_b32 s28, s20, s15
	s_add_i32 m0, s23, 0xc000
	ds_read_b128 v[162:165], v145
	ds_read_b128 v[166:169], v145 offset:1024
	ds_read_b128 v[170:173], v145 offset:2048
	ds_read_b128 v[174:177], v145 offset:3072
	ds_read_b128 v[178:181], v145 offset:4096
	ds_read_b128 v[182:185], v145 offset:5120
	ds_read_b128 v[186:189], v145 offset:6144
	ds_read_b128 v[190:193], v145 offset:7168
	global_load_lds_dwordx4 v136, s[26:27]
	s_add_i32 m0, s23, 0xe000
	s_nop 0
	global_load_lds_dwordx4 v138, s[26:27]
	s_waitcnt lgkmcnt(8)
	s_barrier
	s_waitcnt lgkmcnt(0)
	s_setprio 1
	s_waitcnt lgkmcnt(0)
	v_mfma_f32_16x16x32_bf16 v[126:129], v[146:149], v[162:165], v[126:129]
	v_mfma_f32_16x16x32_bf16 v[118:121], v[154:157], v[162:165], v[118:121]
	v_mfma_f32_16x16x32_bf16 v[110:113], v[146:149], v[170:173], v[110:113]
	v_mfma_f32_16x16x32_bf16 v[102:105], v[154:157], v[170:173], v[102:105]
	v_mfma_f32_16x16x32_bf16 v[94:97], v[146:149], v[178:181], v[94:97]
	v_mfma_f32_16x16x32_bf16 v[86:89], v[154:157], v[178:181], v[86:89]
	v_mfma_f32_16x16x32_bf16 v[78:81], v[146:149], v[186:189], v[78:81]
	v_mfma_f32_16x16x32_bf16 v[70:73], v[154:157], v[186:189], v[70:73]
	v_mfma_f32_16x16x32_bf16 v[126:129], v[150:153], v[166:169], v[126:129]
	v_mfma_f32_16x16x32_bf16 v[118:121], v[158:161], v[166:169], v[118:121]
	v_mfma_f32_16x16x32_bf16 v[110:113], v[150:153], v[174:177], v[110:113]
	v_mfma_f32_16x16x32_bf16 v[102:105], v[158:161], v[174:177], v[102:105]
	v_mfma_f32_16x16x32_bf16 v[94:97], v[150:153], v[182:185], v[94:97]
	v_mfma_f32_16x16x32_bf16 v[86:89], v[158:161], v[182:185], v[86:89]
	v_mfma_f32_16x16x32_bf16 v[78:81], v[150:153], v[190:193], v[78:81]
	v_mfma_f32_16x16x32_bf16 v[70:73], v[158:161], v[190:193], v[70:73]
	s_setprio 0
	s_barrier
	s_add_i32 s48, 0, 0x14000
	s_add_i32 s46, s46, s37
	ds_read_b128 v[198:201], v137 offset:16384
	ds_read_b128 v[202:205], v137 offset:17408
	ds_read_b128 v[206:209], v137 offset:18432
	ds_read_b128 v[210:213], v137 offset:19456
	s_mov_b32 m0, s46
	global_load_lds_dwordx4 v48, s[28:29]
	s_add_i32 m0, s46, 0x2000
	s_nop 0
	global_load_lds_dwordx4 v130, s[28:29]
	s_barrier
	s_waitcnt lgkmcnt(0)
	s_setprio 1
	s_waitcnt lgkmcnt(0)
	v_mfma_f32_16x16x32_bf16 v[122:125], v[198:201], v[162:165], v[122:125]
	v_mfma_f32_16x16x32_bf16 v[114:117], v[206:209], v[162:165], v[114:117]
	v_mfma_f32_16x16x32_bf16 v[106:109], v[198:201], v[170:173], v[106:109]
	v_mfma_f32_16x16x32_bf16 v[98:101], v[206:209], v[170:173], v[98:101]
	v_mfma_f32_16x16x32_bf16 v[90:93], v[198:201], v[178:181], v[90:93]
	v_mfma_f32_16x16x32_bf16 v[82:85], v[206:209], v[178:181], v[82:85]
	v_mfma_f32_16x16x32_bf16 v[74:77], v[198:201], v[186:189], v[74:77]
	v_mfma_f32_16x16x32_bf16 v[66:69], v[206:209], v[186:189], v[66:69]
	v_mfma_f32_16x16x32_bf16 v[122:125], v[202:205], v[166:169], v[122:125]
	v_mfma_f32_16x16x32_bf16 v[114:117], v[210:213], v[166:169], v[114:117]
	v_mfma_f32_16x16x32_bf16 v[106:109], v[202:205], v[174:177], v[106:109]
	v_mfma_f32_16x16x32_bf16 v[98:101], v[210:213], v[174:177], v[98:101]
	v_mfma_f32_16x16x32_bf16 v[90:93], v[202:205], v[182:185], v[90:93]
	v_mfma_f32_16x16x32_bf16 v[82:85], v[210:213], v[182:185], v[82:85]
	v_mfma_f32_16x16x32_bf16 v[74:77], v[202:205], v[190:193], v[74:77]
	v_mfma_f32_16x16x32_bf16 v[66:69], v[210:213], v[190:193], v[66:69]
	s_setprio 0
	s_mov_b32 m0, s23
	v_lshl_add_u64 v[216:217], s[30:31], 0, v[134:135]
	s_barrier
	ds_read_b128 v[162:165], v145 offset:16384
	ds_read_b128 v[166:169], v145 offset:17408
	ds_read_b128 v[170:173], v145 offset:18432
	ds_read_b128 v[174:177], v145 offset:19456
	ds_read_b128 v[178:181], v145 offset:20480
	ds_read_b128 v[182:185], v145 offset:21504
	ds_read_b128 v[186:189], v145 offset:22528
	ds_read_b128 v[190:193], v145 offset:23552
	global_load_lds_dwordx4 v[216:217], off
	v_lshl_add_u64 v[218:219], s[30:31], 0, v[132:133]
	s_mov_b32 m0, s25
	s_nop 0
	global_load_lds_dwordx4 v[218:219], off
	s_barrier
	s_waitcnt lgkmcnt(0)
	s_setprio 1
	s_waitcnt lgkmcnt(0)
	v_mfma_f32_16x16x32_bf16 v[62:65], v[146:149], v[162:165], v[62:65]
	v_mfma_f32_16x16x32_bf16 v[54:57], v[154:157], v[162:165], v[54:57]
	v_mfma_f32_16x16x32_bf16 v[44:47], v[146:149], v[170:173], v[44:47]
	v_mfma_f32_16x16x32_bf16 v[36:39], v[154:157], v[170:173], v[36:39]
	v_mfma_f32_16x16x32_bf16 v[28:31], v[146:149], v[178:181], v[28:31]
	v_mfma_f32_16x16x32_bf16 v[20:23], v[154:157], v[178:181], v[20:23]
	v_mfma_f32_16x16x32_bf16 v[12:15], v[146:149], v[186:189], v[12:15]
	v_mfma_f32_16x16x32_bf16 v[4:7], v[154:157], v[186:189], v[4:7]
	v_mfma_f32_16x16x32_bf16 v[62:65], v[150:153], v[166:169], v[62:65]
	v_mfma_f32_16x16x32_bf16 v[54:57], v[158:161], v[166:169], v[54:57]
	v_mfma_f32_16x16x32_bf16 v[44:47], v[150:153], v[174:177], v[44:47]
	v_mfma_f32_16x16x32_bf16 v[36:39], v[158:161], v[174:177], v[36:39]
	v_mfma_f32_16x16x32_bf16 v[28:31], v[150:153], v[182:185], v[28:31]
	v_mfma_f32_16x16x32_bf16 v[20:23], v[158:161], v[182:185], v[20:23]
	v_mfma_f32_16x16x32_bf16 v[12:15], v[150:153], v[190:193], v[12:15]
	v_mfma_f32_16x16x32_bf16 v[4:7], v[158:161], v[190:193], v[4:7]
	s_setprio 0
	s_barrier
	s_add_u32 s46, s28, 0x40000
	s_addc_u32 s47, s29, 0
	s_add_i32 s48, s48, s37
	s_mov_b32 m0, s48
	s_nop 0
	global_load_lds_dwordx4 v48, s[46:47]
	s_add_i32 m0, s48, 0x2000
	s_nop 0
	global_load_lds_dwordx4 v130, s[46:47]
	s_waitcnt vmcnt(6)
	s_barrier
	s_setprio 1
	v_mfma_f32_16x16x32_bf16 v[58:61], v[198:201], v[162:165], v[58:61]
	v_mfma_f32_16x16x32_bf16 v[50:53], v[206:209], v[162:165], v[50:53]
	v_mfma_f32_16x16x32_bf16 v[40:43], v[198:201], v[170:173], v[40:43]
	v_mfma_f32_16x16x32_bf16 v[32:35], v[206:209], v[170:173], v[32:35]
	v_mfma_f32_16x16x32_bf16 v[24:27], v[198:201], v[178:181], v[24:27]
	v_mfma_f32_16x16x32_bf16 v[16:19], v[206:209], v[178:181], v[16:19]
	v_mfma_f32_16x16x32_bf16 v[8:11], v[198:201], v[186:189], v[8:11]
	v_mfma_f32_16x16x32_bf16 v[0:3], v[206:209], v[186:189], v[0:3]
	v_mfma_f32_16x16x32_bf16 v[58:61], v[202:205], v[166:169], v[58:61]
	v_mfma_f32_16x16x32_bf16 v[50:53], v[210:213], v[166:169], v[50:53]
	v_mfma_f32_16x16x32_bf16 v[40:43], v[202:205], v[174:177], v[40:43]
	v_mfma_f32_16x16x32_bf16 v[32:35], v[210:213], v[174:177], v[32:35]
	v_mfma_f32_16x16x32_bf16 v[24:27], v[202:205], v[182:185], v[24:27]
	v_mfma_f32_16x16x32_bf16 v[16:19], v[210:213], v[182:185], v[16:19]
	v_mfma_f32_16x16x32_bf16 v[8:11], v[202:205], v[190:193], v[8:11]
	v_mfma_f32_16x16x32_bf16 v[0:3], v[210:213], v[190:193], v[0:3]
	s_setprio 0
	s_add_i32 s46, 0, 0x18000
	s_barrier
	ds_read_b128 v[146:149], v137 offset:32768
	ds_read_b128 v[150:153], v137 offset:33792
	ds_read_b128 v[154:157], v137 offset:34816
	ds_read_b128 v[158:161], v137 offset:35840
	s_add_u32 s30, s30, 0x40000
	s_addc_u32 s31, s31, 0
	s_mov_b32 m0, s40
	ds_read_b128 v[162:165], v145 offset:32768
	ds_read_b128 v[166:169], v145 offset:33792
	ds_read_b128 v[170:173], v145 offset:34816
	ds_read_b128 v[174:177], v145 offset:35840
	ds_read_b128 v[178:181], v145 offset:36864
	ds_read_b128 v[182:185], v145 offset:37888
	ds_read_b128 v[186:189], v145 offset:38912
	ds_read_b128 v[190:193], v145 offset:39936
	global_load_lds_dwordx4 v134, s[30:31]
	s_mov_b32 m0, s41
	s_nop 0
	global_load_lds_dwordx4 v132, s[30:31]
	s_waitcnt lgkmcnt(8)
	s_barrier
	s_waitcnt lgkmcnt(0)
	s_setprio 1
	s_waitcnt lgkmcnt(0)
	v_mfma_f32_16x16x32_bf16 v[126:129], v[146:149], v[162:165], v[126:129]
	v_mfma_f32_16x16x32_bf16 v[118:121], v[154:157], v[162:165], v[118:121]
	v_mfma_f32_16x16x32_bf16 v[110:113], v[146:149], v[170:173], v[110:113]
	v_mfma_f32_16x16x32_bf16 v[102:105], v[154:157], v[170:173], v[102:105]
	v_mfma_f32_16x16x32_bf16 v[94:97], v[146:149], v[178:181], v[94:97]
	v_mfma_f32_16x16x32_bf16 v[86:89], v[154:157], v[178:181], v[86:89]
	v_mfma_f32_16x16x32_bf16 v[78:81], v[146:149], v[186:189], v[78:81]
	v_mfma_f32_16x16x32_bf16 v[70:73], v[154:157], v[186:189], v[70:73]
	v_mfma_f32_16x16x32_bf16 v[126:129], v[150:153], v[166:169], v[126:129]
	v_mfma_f32_16x16x32_bf16 v[118:121], v[158:161], v[166:169], v[118:121]
	v_mfma_f32_16x16x32_bf16 v[110:113], v[150:153], v[174:177], v[110:113]
	v_mfma_f32_16x16x32_bf16 v[102:105], v[158:161], v[174:177], v[102:105]
	v_mfma_f32_16x16x32_bf16 v[94:97], v[150:153], v[182:185], v[94:97]
	v_mfma_f32_16x16x32_bf16 v[86:89], v[158:161], v[182:185], v[86:89]
	v_mfma_f32_16x16x32_bf16 v[78:81], v[150:153], v[190:193], v[78:81]
	v_mfma_f32_16x16x32_bf16 v[70:73], v[158:161], v[190:193], v[70:73]
	s_setprio 0
	s_barrier
	s_add_i32 s30, 0, 0x1c000
	s_add_i32 s31, s46, s37
	s_add_u32 s46, s28, s66
	s_addc_u32 s47, s29, s67
	s_mov_b32 m0, s31
	ds_read_b128 v[198:201], v137 offset:49152
	ds_read_b128 v[202:205], v137 offset:50176
	ds_read_b128 v[206:209], v137 offset:51200
	ds_read_b128 v[210:213], v137 offset:52224
	global_load_lds_dwordx4 v48, s[46:47]
	s_add_i32 m0, s31, 0x2000
	s_nop 0
	global_load_lds_dwordx4 v130, s[46:47]
	s_barrier
	s_waitcnt lgkmcnt(0)
	s_setprio 1
	s_waitcnt lgkmcnt(0)
	v_mfma_f32_16x16x32_bf16 v[122:125], v[198:201], v[162:165], v[122:125]
	v_mfma_f32_16x16x32_bf16 v[114:117], v[206:209], v[162:165], v[114:117]
	v_mfma_f32_16x16x32_bf16 v[106:109], v[198:201], v[170:173], v[106:109]
	v_mfma_f32_16x16x32_bf16 v[98:101], v[206:209], v[170:173], v[98:101]
	v_mfma_f32_16x16x32_bf16 v[90:93], v[198:201], v[178:181], v[90:93]
	v_mfma_f32_16x16x32_bf16 v[82:85], v[206:209], v[178:181], v[82:85]
	v_mfma_f32_16x16x32_bf16 v[74:77], v[198:201], v[186:189], v[74:77]
	v_mfma_f32_16x16x32_bf16 v[66:69], v[206:209], v[186:189], v[66:69]
	v_mfma_f32_16x16x32_bf16 v[122:125], v[202:205], v[166:169], v[122:125]
	v_mfma_f32_16x16x32_bf16 v[114:117], v[210:213], v[166:169], v[114:117]
	v_mfma_f32_16x16x32_bf16 v[106:109], v[202:205], v[174:177], v[106:109]
	v_mfma_f32_16x16x32_bf16 v[98:101], v[210:213], v[174:177], v[98:101]
	v_mfma_f32_16x16x32_bf16 v[90:93], v[202:205], v[182:185], v[90:93]
	v_mfma_f32_16x16x32_bf16 v[82:85], v[210:213], v[182:185], v[82:85]
	v_mfma_f32_16x16x32_bf16 v[74:77], v[202:205], v[190:193], v[74:77]
	v_mfma_f32_16x16x32_bf16 v[66:69], v[210:213], v[190:193], v[66:69]
	s_setprio 0
	s_mov_b32 m0, s42
	v_lshl_add_u64 v[140:141], v[216:217], 0, s[66:67]
	s_barrier
	ds_read_b128 v[162:165], v145 offset:49152
	ds_read_b128 v[166:169], v145 offset:50176
	ds_read_b128 v[170:173], v145 offset:51200
	ds_read_b128 v[174:177], v145 offset:52224
	ds_read_b128 v[178:181], v145 offset:53248
	ds_read_b128 v[182:185], v145 offset:54272
	ds_read_b128 v[186:189], v145 offset:55296
	ds_read_b128 v[190:193], v145 offset:56320
	global_load_lds_dwordx4 v[140:141], off
	v_lshl_add_u64 v[140:141], v[218:219], 0, s[66:67]
	s_mov_b32 m0, s43
	s_nop 0
	global_load_lds_dwordx4 v[140:141], off
	s_barrier
	s_waitcnt lgkmcnt(0)
	s_setprio 1
	s_waitcnt lgkmcnt(0)
	v_mfma_f32_16x16x32_bf16 v[62:65], v[146:149], v[162:165], v[62:65]
	v_mfma_f32_16x16x32_bf16 v[54:57], v[154:157], v[162:165], v[54:57]
	v_mfma_f32_16x16x32_bf16 v[44:47], v[146:149], v[170:173], v[44:47]
	v_mfma_f32_16x16x32_bf16 v[36:39], v[154:157], v[170:173], v[36:39]
	v_mfma_f32_16x16x32_bf16 v[28:31], v[146:149], v[178:181], v[28:31]
	v_mfma_f32_16x16x32_bf16 v[20:23], v[154:157], v[178:181], v[20:23]
	v_mfma_f32_16x16x32_bf16 v[12:15], v[146:149], v[186:189], v[12:15]
	v_mfma_f32_16x16x32_bf16 v[4:7], v[154:157], v[186:189], v[4:7]
	v_mfma_f32_16x16x32_bf16 v[62:65], v[150:153], v[166:169], v[62:65]
	v_mfma_f32_16x16x32_bf16 v[54:57], v[158:161], v[166:169], v[54:57]
	v_mfma_f32_16x16x32_bf16 v[44:47], v[150:153], v[174:177], v[44:47]
	v_mfma_f32_16x16x32_bf16 v[36:39], v[158:161], v[174:177], v[36:39]
	v_mfma_f32_16x16x32_bf16 v[28:31], v[150:153], v[182:185], v[28:31]
	v_mfma_f32_16x16x32_bf16 v[20:23], v[158:161], v[182:185], v[20:23]
	v_mfma_f32_16x16x32_bf16 v[12:15], v[150:153], v[190:193], v[12:15]
	v_mfma_f32_16x16x32_bf16 v[4:7], v[158:161], v[190:193], v[4:7]
	s_setprio 0
	s_barrier
	s_add_u32 s28, s28, 0x40080
	s_addc_u32 s29, s29, 0
	s_add_i32 s30, s30, s37
	s_mov_b32 m0, s30
	s_nop 0
	global_load_lds_dwordx4 v48, s[28:29]
	s_add_i32 m0, s30, 0x2000
	s_nop 0
	global_load_lds_dwordx4 v130, s[28:29]
	s_waitcnt vmcnt(6)
	s_barrier
	s_setprio 1
	v_mfma_f32_16x16x32_bf16 v[58:61], v[198:201], v[162:165], v[58:61]
	v_mfma_f32_16x16x32_bf16 v[50:53], v[206:209], v[162:165], v[50:53]
	v_mfma_f32_16x16x32_bf16 v[40:43], v[198:201], v[170:173], v[40:43]
	v_mfma_f32_16x16x32_bf16 v[32:35], v[206:209], v[170:173], v[32:35]
	v_mfma_f32_16x16x32_bf16 v[24:27], v[198:201], v[178:181], v[24:27]
	v_mfma_f32_16x16x32_bf16 v[16:19], v[206:209], v[178:181], v[16:19]
	v_mfma_f32_16x16x32_bf16 v[8:11], v[198:201], v[186:189], v[8:11]
	v_mfma_f32_16x16x32_bf16 v[0:3], v[206:209], v[186:189], v[0:3]
	v_mfma_f32_16x16x32_bf16 v[58:61], v[202:205], v[166:169], v[58:61]
	v_mfma_f32_16x16x32_bf16 v[50:53], v[210:213], v[166:169], v[50:53]
	v_mfma_f32_16x16x32_bf16 v[40:43], v[202:205], v[174:177], v[40:43]
	v_mfma_f32_16x16x32_bf16 v[32:35], v[210:213], v[174:177], v[32:35]
	v_mfma_f32_16x16x32_bf16 v[24:27], v[202:205], v[182:185], v[24:27]
	v_mfma_f32_16x16x32_bf16 v[16:19], v[210:213], v[182:185], v[16:19]
	v_mfma_f32_16x16x32_bf16 v[8:11], v[202:205], v[190:193], v[8:11]
	v_mfma_f32_16x16x32_bf16 v[0:3], v[210:213], v[190:193], v[0:3]
	s_setprio 0
	s_add_i32 s45, s45, 2
	s_add_u32 s26, s26, 0x100
	s_addc_u32 s27, s27, 0
	s_add_u32 s15, s15, 0x100
	s_addc_u32 s17, s17, 0
	s_cmp_gt_u32 s45, 13
	s_barrier
	s_cbranch_scc0 .LBB0_1356
	v_mul_f32_e32 v147, 0xbfb8aa3b, v126
	v_exp_f32_e32 v148, v147
	v_mul_f32_e32 v147, 0xbfb8aa3b, v118
	v_exp_f32_e32 v150, v147
	v_mul_f32_e32 v147, 0xbfb8aa3b, v127
	v_exp_f32_e32 v149, v147
	v_lshl_or_b32 v140, s22, 7, v144
	v_lshl_add_u32 v146, s24, 8, v142
	v_ashrrev_i32_e32 v141, 31, v140
	v_pk_add_f32 v[148:149], v[148:149], 1.0 op_sel_hi:[1,0]
	s_movk_i32 s15, 0x1600
	s_mov_b32 s22, s14
	s_mov_b32 s24, s16
	s_mov_b64 s[28:29], s[20:21]
	v_rcp_f32_e32 v147, v149
	s_nop 0
	v_mul_f32_e32 v127, v127, v147
	s_nop 0
	v_rcp_f32_e32 v147, v148
	s_nop 0
	v_mul_f32_e32 v126, v126, v147
	v_pk_mul_f32 v[122:123], v[122:123], v[126:127]
	v_mul_f32_e32 v126, 0xbfb8aa3b, v119
	v_exp_f32_e32 v151, v126
	s_nop 0
	v_pk_add_f32 v[126:127], v[150:151], 1.0 op_sel_hi:[1,0]
	s_nop 0
	s_nop 0
	v_rcp_f32_e32 v147, v127
	s_nop 0
	v_mul_f32_e32 v119, v119, v147
	s_nop 0
	v_rcp_f32_e32 v127, v126
	s_nop 0
	v_mul_f32_e32 v118, v118, v127
	v_pk_mul_f32 v[114:115], v[114:115], v[118:119]
	v_mul_f32_e32 v119, 0xbfb8aa3b, v120
	v_mul_f32_e32 v118, 0xbfb8aa3b, v128
	v_exp_f32_e32 v126, v119
	v_mul_f32_e32 v119, 0xbfb8aa3b, v129
	v_exp_f32_e32 v118, v118
	v_exp_f32_e32 v119, v119
	s_nop 0
	v_pk_add_f32 v[118:119], v[118:119], 1.0 op_sel_hi:[1,0]
	s_nop 0
	s_nop 0
	v_rcp_f32_e32 v127, v119
	s_nop 0
	v_mul_f32_e32 v119, v129, v127
	s_nop 0
	v_rcp_f32_e32 v127, v118
	s_nop 0
	v_mul_f32_e32 v118, v128, v127
	v_pk_mul_f32 v[124:125], v[124:125], v[118:119]
	v_mul_f32_e32 v118, 0xbfb8aa3b, v121
	v_exp_f32_e32 v127, v118
	s_nop 0
	v_pk_add_f32 v[118:119], v[126:127], 1.0 op_sel_hi:[1,0]
	s_nop 0
	s_nop 0
	v_rcp_f32_e32 v126, v119
	s_nop 0
	v_mul_f32_e32 v119, v121, v126
	s_nop 0
	v_rcp_f32_e32 v121, v118
	s_nop 0
	v_mul_f32_e32 v118, v120, v121
	v_pk_mul_f32 v[116:117], v[116:117], v[118:119]
	v_cvt_pk_bf16_f32 v120, v114, v115
	v_mov_b64_e32 v[114:115], s[12:13]
	v_cvt_pk_bf16_f32 v118, v122, v123
	v_cvt_pk_bf16_f32 v121, v116, v117
	v_mad_i64_i32 v[122:123], s[26:27], v146, s15, v[114:115]
	v_lshlrev_b64 v[116:117], 1, v[140:141]
	v_cvt_pk_bf16_f32 v119, v124, v125
	v_lshl_add_u64 v[122:123], v[122:123], 0, v[116:117]
	global_store_dwordx4 v[122:123], v[118:121], off
	s_nop 1
	v_mul_f32_e32 v119, 0xbfb8aa3b, v102
	v_mul_f32_e32 v118, 0xbfb8aa3b, v110
	v_exp_f32_e32 v120, v119
	v_mul_f32_e32 v119, 0xbfb8aa3b, v111
	v_exp_f32_e32 v118, v118
	v_exp_f32_e32 v119, v119
	s_nop 0
	v_pk_add_f32 v[118:119], v[118:119], 1.0 op_sel_hi:[1,0]
	s_nop 0
	s_nop 0
	v_rcp_f32_e32 v121, v119
	s_nop 0
	v_mul_f32_e32 v111, v111, v121
	s_nop 0
	v_rcp_f32_e32 v119, v118
	s_nop 0
	v_mul_f32_e32 v110, v110, v119
	v_pk_mul_f32 v[106:107], v[106:107], v[110:111]
	v_mul_f32_e32 v110, 0xbfb8aa3b, v103
	v_exp_f32_e32 v121, v110
	s_nop 0
	v_pk_add_f32 v[110:111], v[120:121], 1.0 op_sel_hi:[1,0]
	s_nop 0
	s_nop 0
	v_rcp_f32_e32 v118, v111
	s_nop 0
	v_mul_f32_e32 v103, v103, v118
	s_nop 0
	v_rcp_f32_e32 v111, v110
	s_nop 0
	v_mul_f32_e32 v102, v102, v111
	v_pk_mul_f32 v[102:103], v[98:99], v[102:103]
	v_mul_f32_e32 v99, 0xbfb8aa3b, v104
	v_mul_f32_e32 v98, 0xbfb8aa3b, v112
	v_exp_f32_e32 v110, v99
	v_mul_f32_e32 v99, 0xbfb8aa3b, v113
	v_exp_f32_e32 v98, v98
	v_exp_f32_e32 v99, v99
	s_nop 0
	v_pk_add_f32 v[98:99], v[98:99], 1.0 op_sel_hi:[1,0]
	s_nop 0
	s_nop 0
	v_rcp_f32_e32 v111, v99
	s_nop 0
	v_mul_f32_e32 v99, v113, v111
	s_nop 0
	v_rcp_f32_e32 v111, v98
	s_nop 0
	v_mul_f32_e32 v98, v112, v111
	v_pk_mul_f32 v[108:109], v[108:109], v[98:99]
	v_mul_f32_e32 v98, 0xbfb8aa3b, v105
	v_exp_f32_e32 v111, v98
	s_nop 0
	v_pk_add_f32 v[98:99], v[110:111], 1.0 op_sel_hi:[1,0]
	s_nop 0
	s_nop 0
	v_rcp_f32_e32 v110, v99
	s_nop 0
	v_mul_f32_e32 v99, v105, v110
	s_nop 0
	v_rcp_f32_e32 v105, v98
	s_nop 0
	v_mul_f32_e32 v98, v104, v105
	v_or_b32_e32 v110, 16, v146
	v_pk_mul_f32 v[104:105], v[100:101], v[98:99]
	v_cvt_pk_bf16_f32 v100, v102, v103
	v_mad_i64_i32 v[102:103], s[26:27], v110, s15, v[114:115]
	v_cvt_pk_bf16_f32 v98, v106, v107
	v_cvt_pk_bf16_f32 v99, v108, v109
	v_cvt_pk_bf16_f32 v101, v104, v105
	v_lshl_add_u64 v[102:103], v[102:103], 0, v[116:117]
	global_store_dwordx4 v[102:103], v[98:101], off
	s_nop 1
	v_mul_f32_e32 v99, 0xbfb8aa3b, v86
	v_mul_f32_e32 v98, 0xbfb8aa3b, v94
	v_exp_f32_e32 v100, v99
	v_mul_f32_e32 v99, 0xbfb8aa3b, v95
	v_exp_f32_e32 v98, v98
	v_exp_f32_e32 v99, v99
	s_nop 0
	v_pk_add_f32 v[98:99], v[98:99], 1.0 op_sel_hi:[1,0]
	s_nop 0
	s_nop 0
	v_rcp_f32_e32 v101, v99
	s_nop 0
	v_mul_f32_e32 v95, v95, v101
	s_nop 0
	v_rcp_f32_e32 v99, v98
	s_nop 0
	v_mul_f32_e32 v94, v94, v99
	v_pk_mul_f32 v[90:91], v[90:91], v[94:95]
	v_mul_f32_e32 v94, 0xbfb8aa3b, v87
	v_exp_f32_e32 v101, v94
	s_nop 0
	v_pk_add_f32 v[94:95], v[100:101], 1.0 op_sel_hi:[1,0]
	s_nop 0
	s_nop 0
	v_rcp_f32_e32 v98, v95
	s_nop 0
	v_mul_f32_e32 v87, v87, v98
	s_nop 0
	v_rcp_f32_e32 v95, v94
	s_nop 0
	v_mul_f32_e32 v86, v86, v95
	v_pk_mul_f32 v[86:87], v[82:83], v[86:87]
	v_mul_f32_e32 v83, 0xbfb8aa3b, v88
	v_mul_f32_e32 v82, 0xbfb8aa3b, v96
	v_exp_f32_e32 v94, v83
	v_mul_f32_e32 v83, 0xbfb8aa3b, v97
	v_exp_f32_e32 v82, v82
	v_exp_f32_e32 v83, v83
	s_nop 0
	v_pk_add_f32 v[82:83], v[82:83], 1.0 op_sel_hi:[1,0]
	s_nop 0
	s_nop 0
	v_rcp_f32_e32 v95, v83
	s_nop 0
	v_mul_f32_e32 v83, v97, v95
	s_nop 0
	v_rcp_f32_e32 v95, v82
	s_nop 0
	v_mul_f32_e32 v82, v96, v95
	v_pk_mul_f32 v[92:93], v[92:93], v[82:83]
	v_mul_f32_e32 v82, 0xbfb8aa3b, v89
	v_exp_f32_e32 v95, v82
	s_nop 0
	v_pk_add_f32 v[82:83], v[94:95], 1.0 op_sel_hi:[1,0]
	s_nop 0
	s_nop 0
	v_rcp_f32_e32 v94, v83
	s_nop 0
	v_mul_f32_e32 v83, v89, v94
	s_nop 0
	v_rcp_f32_e32 v89, v82
	s_nop 0
	v_mul_f32_e32 v82, v88, v89
	v_or_b32_e32 v94, 32, v146
	v_pk_mul_f32 v[88:89], v[84:85], v[82:83]
	v_cvt_pk_bf16_f32 v84, v86, v87
	v_mad_i64_i32 v[86:87], s[26:27], v94, s15, v[114:115]
	v_cvt_pk_bf16_f32 v82, v90, v91
	v_cvt_pk_bf16_f32 v83, v92, v93
	v_cvt_pk_bf16_f32 v85, v88, v89
	v_lshl_add_u64 v[86:87], v[86:87], 0, v[116:117]
	global_store_dwordx4 v[86:87], v[82:85], off
	s_nop 1
	v_mul_f32_e32 v83, 0xbfb8aa3b, v70
	v_mul_f32_e32 v82, 0xbfb8aa3b, v78
	v_exp_f32_e32 v84, v83
	v_mul_f32_e32 v83, 0xbfb8aa3b, v79
	v_exp_f32_e32 v82, v82
	v_exp_f32_e32 v83, v83
	s_nop 0
	v_pk_add_f32 v[82:83], v[82:83], 1.0 op_sel_hi:[1,0]
	s_nop 0
	s_nop 0
	v_rcp_f32_e32 v85, v83
	s_nop 0
	v_mul_f32_e32 v79, v79, v85
	s_nop 0
	v_rcp_f32_e32 v83, v82
	s_nop 0
	v_mul_f32_e32 v78, v78, v83
	v_pk_mul_f32 v[74:75], v[74:75], v[78:79]
	v_mul_f32_e32 v78, 0xbfb8aa3b, v71
	v_exp_f32_e32 v85, v78
	s_nop 0
	v_pk_add_f32 v[78:79], v[84:85], 1.0 op_sel_hi:[1,0]
	s_nop 0
	s_nop 0
	v_rcp_f32_e32 v82, v79
	s_nop 0
	v_mul_f32_e32 v71, v71, v82
	s_nop 0
	v_rcp_f32_e32 v79, v78
	s_nop 0
	v_mul_f32_e32 v70, v70, v79
	v_pk_mul_f32 v[70:71], v[66:67], v[70:71]
	v_mul_f32_e32 v67, 0xbfb8aa3b, v72
	v_mul_f32_e32 v66, 0xbfb8aa3b, v80
	v_exp_f32_e32 v78, v67
	v_mul_f32_e32 v67, 0xbfb8aa3b, v81
	v_exp_f32_e32 v66, v66
	v_exp_f32_e32 v67, v67
	s_nop 0
	v_pk_add_f32 v[66:67], v[66:67], 1.0 op_sel_hi:[1,0]
	s_nop 0
	s_nop 0
	v_rcp_f32_e32 v79, v67
	s_nop 0
	v_mul_f32_e32 v67, v81, v79
	s_nop 0
	v_rcp_f32_e32 v79, v66
	s_nop 0
	v_mul_f32_e32 v66, v80, v79
	v_pk_mul_f32 v[76:77], v[76:77], v[66:67]
	v_mul_f32_e32 v66, 0xbfb8aa3b, v73
	v_exp_f32_e32 v79, v66
	s_nop 0
	v_pk_add_f32 v[66:67], v[78:79], 1.0 op_sel_hi:[1,0]
	s_nop 0
	s_nop 0
	v_rcp_f32_e32 v78, v67
	s_nop 0
	v_mul_f32_e32 v67, v73, v78
	s_nop 0
	v_rcp_f32_e32 v73, v66
	s_nop 0
	v_mul_f32_e32 v66, v72, v73
	v_or_b32_e32 v78, 48, v146
	v_pk_mul_f32 v[72:73], v[68:69], v[66:67]
	v_cvt_pk_bf16_f32 v68, v70, v71
	v_mad_i64_i32 v[70:71], s[26:27], v78, s15, v[114:115]
	v_cvt_pk_bf16_f32 v66, v74, v75
	v_cvt_pk_bf16_f32 v67, v76, v77
	v_cvt_pk_bf16_f32 v69, v72, v73
	v_lshl_add_u64 v[70:71], v[70:71], 0, v[116:117]
	global_store_dwordx4 v[70:71], v[66:69], off
	v_add_u32_e32 v70, 0x80, v146
	s_nop 0
	v_mul_f32_e32 v67, 0xbfb8aa3b, v54
	v_mul_f32_e32 v66, 0xbfb8aa3b, v62
	v_exp_f32_e32 v68, v67
	v_mul_f32_e32 v67, 0xbfb8aa3b, v63
	v_exp_f32_e32 v66, v66
	v_exp_f32_e32 v67, v67
	s_nop 0
	v_pk_add_f32 v[66:67], v[66:67], 1.0 op_sel_hi:[1,0]
	s_nop 0
	s_nop 0
	v_rcp_f32_e32 v69, v67
	s_nop 0
	v_mul_f32_e32 v63, v63, v69
	s_nop 0
	v_rcp_f32_e32 v67, v66
	s_nop 0
	v_mul_f32_e32 v62, v62, v67
	v_pk_mul_f32 v[58:59], v[58:59], v[62:63]
	v_mul_f32_e32 v62, 0xbfb8aa3b, v55
	v_exp_f32_e32 v69, v62
	s_nop 0
	v_pk_add_f32 v[62:63], v[68:69], 1.0 op_sel_hi:[1,0]
	s_nop 0
	s_nop 0
	v_rcp_f32_e32 v66, v63
	s_nop 0
	v_mul_f32_e32 v55, v55, v66
	s_nop 0
	v_rcp_f32_e32 v63, v62
	s_nop 0
	v_mul_f32_e32 v54, v54, v63
	v_pk_mul_f32 v[54:55], v[50:51], v[54:55]
	v_mul_f32_e32 v51, 0xbfb8aa3b, v56
	v_mul_f32_e32 v50, 0xbfb8aa3b, v64
	v_exp_f32_e32 v62, v51
	v_mul_f32_e32 v51, 0xbfb8aa3b, v65
	v_exp_f32_e32 v50, v50
	v_exp_f32_e32 v51, v51
	s_nop 0
	v_pk_add_f32 v[50:51], v[50:51], 1.0 op_sel_hi:[1,0]
	s_nop 0
	s_nop 0
	v_rcp_f32_e32 v63, v51
	s_nop 0
	v_mul_f32_e32 v51, v65, v63
	s_nop 0
	v_rcp_f32_e32 v63, v50
	s_nop 0
	v_mul_f32_e32 v50, v64, v63
	v_pk_mul_f32 v[60:61], v[60:61], v[50:51]
	v_mul_f32_e32 v50, 0xbfb8aa3b, v57
	v_exp_f32_e32 v63, v50
	s_nop 0
	v_pk_add_f32 v[50:51], v[62:63], 1.0 op_sel_hi:[1,0]
	s_nop 0
	s_nop 0
	v_rcp_f32_e32 v62, v51
	s_nop 0
	v_mul_f32_e32 v51, v57, v62
	s_nop 0
	v_rcp_f32_e32 v57, v50
	s_nop 0
	v_mul_f32_e32 v50, v56, v57
	v_pk_mul_f32 v[56:57], v[52:53], v[50:51]
	v_cvt_pk_bf16_f32 v52, v54, v55
	v_mad_i64_i32 v[54:55], s[26:27], v70, s15, v[114:115]
	v_cvt_pk_bf16_f32 v50, v58, v59
	v_cvt_pk_bf16_f32 v51, v60, v61
	v_cvt_pk_bf16_f32 v53, v56, v57
	v_lshl_add_u64 v[54:55], v[54:55], 0, v[116:117]
	global_store_dwordx4 v[54:55], v[50:53], off
	s_nop 1
	v_mul_f32_e32 v51, 0xbfb8aa3b, v36
	v_mul_f32_e32 v50, 0xbfb8aa3b, v44
	v_exp_f32_e32 v52, v51
	v_mul_f32_e32 v51, 0xbfb8aa3b, v45
	v_exp_f32_e32 v50, v50
	v_exp_f32_e32 v51, v51
	s_nop 0
	v_pk_add_f32 v[50:51], v[50:51], 1.0 op_sel_hi:[1,0]
	s_nop 0
	s_nop 0
	v_rcp_f32_e32 v53, v51
	s_nop 0
	v_mul_f32_e32 v45, v45, v53
	s_nop 0
	v_rcp_f32_e32 v51, v50
	s_nop 0
	v_mul_f32_e32 v44, v44, v51
	v_pk_mul_f32 v[40:41], v[40:41], v[44:45]
	v_mul_f32_e32 v44, 0xbfb8aa3b, v37
	v_exp_f32_e32 v53, v44
	s_nop 0
	v_pk_add_f32 v[44:45], v[52:53], 1.0 op_sel_hi:[1,0]
	s_nop 0
	s_nop 0
	v_rcp_f32_e32 v50, v45
	s_nop 0
	v_mul_f32_e32 v37, v37, v50
	s_nop 0
	v_rcp_f32_e32 v45, v44
	s_nop 0
	v_mul_f32_e32 v36, v36, v45
	v_pk_mul_f32 v[36:37], v[32:33], v[36:37]
	v_mul_f32_e32 v33, 0xbfb8aa3b, v38
	v_mul_f32_e32 v32, 0xbfb8aa3b, v46
	v_exp_f32_e32 v44, v33
	v_mul_f32_e32 v33, 0xbfb8aa3b, v47
	v_exp_f32_e32 v32, v32
	v_exp_f32_e32 v33, v33
	s_nop 0
	v_pk_add_f32 v[32:33], v[32:33], 1.0 op_sel_hi:[1,0]
	s_nop 0
	s_nop 0
	v_rcp_f32_e32 v45, v33
	s_nop 0
	v_mul_f32_e32 v33, v47, v45
	s_nop 0
	v_rcp_f32_e32 v45, v32
	s_nop 0
	v_mul_f32_e32 v32, v46, v45
	v_pk_mul_f32 v[42:43], v[42:43], v[32:33]
	v_mul_f32_e32 v32, 0xbfb8aa3b, v39
	v_exp_f32_e32 v45, v32
	s_nop 0
	v_pk_add_f32 v[32:33], v[44:45], 1.0 op_sel_hi:[1,0]
	s_nop 0
	s_nop 0
	v_rcp_f32_e32 v44, v33
	s_nop 0
	v_mul_f32_e32 v33, v39, v44
	s_nop 0
	v_rcp_f32_e32 v39, v32
	s_nop 0
	v_mul_f32_e32 v32, v38, v39
	v_add_u32_e32 v44, 0x90, v146
	v_pk_mul_f32 v[38:39], v[34:35], v[32:33]
	v_cvt_pk_bf16_f32 v34, v36, v37
	v_mad_i64_i32 v[36:37], s[26:27], v44, s15, v[114:115]
	v_cvt_pk_bf16_f32 v32, v40, v41
	v_cvt_pk_bf16_f32 v33, v42, v43
	v_cvt_pk_bf16_f32 v35, v38, v39
	v_lshl_add_u64 v[36:37], v[36:37], 0, v[116:117]
	global_store_dwordx4 v[36:37], v[32:35], off
	s_nop 1
	v_mul_f32_e32 v33, 0xbfb8aa3b, v20
	v_mul_f32_e32 v32, 0xbfb8aa3b, v28
	v_exp_f32_e32 v34, v33
	v_mul_f32_e32 v33, 0xbfb8aa3b, v29
	v_exp_f32_e32 v32, v32
	v_exp_f32_e32 v33, v33
	s_nop 0
	v_pk_add_f32 v[32:33], v[32:33], 1.0 op_sel_hi:[1,0]
	s_nop 0
	s_nop 0
	v_rcp_f32_e32 v35, v33
	s_nop 0
	v_mul_f32_e32 v29, v29, v35
	s_nop 0
	v_rcp_f32_e32 v33, v32
	s_nop 0
	v_mul_f32_e32 v28, v28, v33
	v_pk_mul_f32 v[24:25], v[24:25], v[28:29]
	v_mul_f32_e32 v28, 0xbfb8aa3b, v21
	v_exp_f32_e32 v35, v28
	s_nop 0
	v_pk_add_f32 v[28:29], v[34:35], 1.0 op_sel_hi:[1,0]
	s_nop 0
	s_nop 0
	v_rcp_f32_e32 v32, v29
	s_nop 0
	v_mul_f32_e32 v21, v21, v32
	s_nop 0
	v_rcp_f32_e32 v29, v28
	s_nop 0
	v_mul_f32_e32 v20, v20, v29
	v_pk_mul_f32 v[20:21], v[16:17], v[20:21]
	v_mul_f32_e32 v17, 0xbfb8aa3b, v22
	v_mul_f32_e32 v16, 0xbfb8aa3b, v30
	v_exp_f32_e32 v28, v17
	v_mul_f32_e32 v17, 0xbfb8aa3b, v31
	v_exp_f32_e32 v16, v16
	v_exp_f32_e32 v17, v17
	s_nop 0
	v_pk_add_f32 v[16:17], v[16:17], 1.0 op_sel_hi:[1,0]
	s_nop 0
	s_nop 0
	v_rcp_f32_e32 v29, v17
	s_nop 0
	v_mul_f32_e32 v17, v31, v29
	s_nop 0
	v_rcp_f32_e32 v29, v16
	s_nop 0
	v_mul_f32_e32 v16, v30, v29
	v_pk_mul_f32 v[26:27], v[26:27], v[16:17]
	v_mul_f32_e32 v16, 0xbfb8aa3b, v23
	v_exp_f32_e32 v29, v16
	s_nop 0
	v_pk_add_f32 v[16:17], v[28:29], 1.0 op_sel_hi:[1,0]
	s_nop 0
	s_nop 0
	v_rcp_f32_e32 v28, v17
	s_nop 0
	v_mul_f32_e32 v17, v23, v28
	s_nop 0
	v_rcp_f32_e32 v23, v16
	s_nop 0
	v_mul_f32_e32 v16, v22, v23
	v_add_u32_e32 v28, 0xa0, v146
	v_pk_mul_f32 v[22:23], v[18:19], v[16:17]
	v_cvt_pk_bf16_f32 v18, v20, v21
	v_mad_i64_i32 v[20:21], s[26:27], v28, s15, v[114:115]
	v_cvt_pk_bf16_f32 v16, v24, v25
	v_cvt_pk_bf16_f32 v17, v26, v27
	v_cvt_pk_bf16_f32 v19, v22, v23
	v_lshl_add_u64 v[20:21], v[20:21], 0, v[116:117]
	global_store_dwordx4 v[20:21], v[16:19], off
	s_nop 1
	v_mul_f32_e32 v17, 0xbfb8aa3b, v4
	v_mul_f32_e32 v16, 0xbfb8aa3b, v12
	v_exp_f32_e32 v18, v17
	v_mul_f32_e32 v17, 0xbfb8aa3b, v13
	v_exp_f32_e32 v16, v16
	v_exp_f32_e32 v17, v17
	s_nop 0
	v_pk_add_f32 v[16:17], v[16:17], 1.0 op_sel_hi:[1,0]
	s_nop 0
	s_nop 0
	v_rcp_f32_e32 v19, v17
	s_nop 0
	v_mul_f32_e32 v13, v13, v19
	s_nop 0
	v_rcp_f32_e32 v17, v16
	s_nop 0
	v_mul_f32_e32 v12, v12, v17
	v_pk_mul_f32 v[8:9], v[8:9], v[12:13]
	v_mul_f32_e32 v12, 0xbfb8aa3b, v5
	v_exp_f32_e32 v19, v12
	s_nop 0
	v_pk_add_f32 v[12:13], v[18:19], 1.0 op_sel_hi:[1,0]
	s_nop 0
	s_nop 0
	v_rcp_f32_e32 v16, v13
	s_nop 0
	v_mul_f32_e32 v5, v5, v16
	s_nop 0
	v_rcp_f32_e32 v13, v12
	s_nop 0
	v_mul_f32_e32 v4, v4, v13
	v_pk_mul_f32 v[4:5], v[0:1], v[4:5]
	v_mul_f32_e32 v1, 0xbfb8aa3b, v6
	v_mul_f32_e32 v0, 0xbfb8aa3b, v14
	v_exp_f32_e32 v12, v1
	v_mul_f32_e32 v1, 0xbfb8aa3b, v15
	v_exp_f32_e32 v0, v0
	v_exp_f32_e32 v1, v1
	s_nop 0
	v_pk_add_f32 v[0:1], v[0:1], 1.0 op_sel_hi:[1,0]
	s_nop 0
	s_nop 0
	v_rcp_f32_e32 v13, v1
	s_nop 0
	v_mul_f32_e32 v1, v15, v13
	s_nop 0
	v_rcp_f32_e32 v13, v0
	s_nop 0
	v_mul_f32_e32 v0, v14, v13
	v_pk_mul_f32 v[10:11], v[10:11], v[0:1]
	v_mul_f32_e32 v0, 0xbfb8aa3b, v7
	v_exp_f32_e32 v13, v0
	s_nop 0
	v_pk_add_f32 v[0:1], v[12:13], 1.0 op_sel_hi:[1,0]
	s_nop 0
	s_nop 0
	v_rcp_f32_e32 v12, v1
	s_nop 0
	v_mul_f32_e32 v1, v7, v12
	s_nop 0
	v_rcp_f32_e32 v7, v0
	s_nop 0
	v_mul_f32_e32 v0, v6, v7
	v_add_u32_e32 v12, 0xb0, v146
	v_pk_mul_f32 v[6:7], v[2:3], v[0:1]
	v_cvt_pk_bf16_f32 v2, v4, v5
	v_mad_i64_i32 v[4:5], s[26:27], v12, s15, v[114:115]
	v_cvt_pk_bf16_f32 v0, v8, v9
	v_cvt_pk_bf16_f32 v1, v10, v11
	v_cvt_pk_bf16_f32 v3, v6, v7
	v_lshl_add_u64 v[4:5], v[4:5], 0, v[116:117]
	s_and_b64 vcc, exec, s[0:1]
	s_mov_b64 s[26:27], s[18:19]
	global_store_dwordx4 v[4:5], v[0:3], off
	s_cbranch_vccz .LBB0_1353
	s_waitcnt vmcnt(0)
	s_cmpk_gt_u32 s5, 0xff
	s_cbranch_scc1 .LBB0_1360
	s_barrier

.LBB0_1421:
	s_add_u32 s18, s16, 0x100
	s_addc_u32 s19, s17, 0
	s_add_i32 s47, 0, 0x10000
	ds_read_b128 v[130:133], v202
	ds_read_b128 v[134:137], v202 offset:1024
	ds_read_b128 v[138:141], v202 offset:2048
	ds_read_b128 v[142:145], v202 offset:3072
	s_cmp_eq_u32 s46, 40
	s_cselect_b32 s23, s11, s19
	s_cselect_b32 s22, s10, s18
	s_cselect_b32 s21, s13, s45
	s_cselect_b32 s20, s12, s44
	v_lshl_add_u64 v[188:189], s[16:17], 0, v[152:153]
	s_add_i32 m0, s31, 0xc000
	ds_read_b128 v[156:159], v206
	ds_read_b128 v[160:163], v206 offset:1024
	ds_read_b128 v[164:167], v206 offset:2048
	ds_read_b128 v[168:171], v206 offset:3072
	ds_read_b128 v[172:175], v206 offset:4096
	ds_read_b128 v[176:179], v206 offset:5120
	ds_read_b128 v[180:183], v206 offset:6144
	ds_read_b128 v[184:187], v206 offset:7168
	global_load_lds_dwordx4 v[188:189], off
	v_lshl_add_u64 v[188:189], s[16:17], 0, v[154:155]
	s_add_i32 m0, s31, 0xe000
	s_nop 0
	global_load_lds_dwordx4 v[188:189], off
	s_waitcnt lgkmcnt(8)
	s_barrier
	s_waitcnt lgkmcnt(0)
	s_setprio 1
	s_waitcnt lgkmcnt(0)
	v_mfma_f32_16x16x32_bf16 v[126:129], v[130:133], v[156:159], v[126:129]
	v_mfma_f32_16x16x32_bf16 v[122:125], v[138:141], v[156:159], v[122:125]
	v_mfma_f32_16x16x32_bf16 v[114:117], v[130:133], v[164:167], v[114:117]
	v_mfma_f32_16x16x32_bf16 v[106:109], v[138:141], v[164:167], v[106:109]
	v_mfma_f32_16x16x32_bf16 v[98:101], v[130:133], v[172:175], v[98:101]
	v_mfma_f32_16x16x32_bf16 v[90:93], v[138:141], v[172:175], v[90:93]
	v_mfma_f32_16x16x32_bf16 v[82:85], v[130:133], v[180:183], v[82:85]
	v_mfma_f32_16x16x32_bf16 v[74:77], v[138:141], v[180:183], v[74:77]
	v_mfma_f32_16x16x32_bf16 v[126:129], v[134:137], v[160:163], v[126:129]
	v_mfma_f32_16x16x32_bf16 v[122:125], v[142:145], v[160:163], v[122:125]
	v_mfma_f32_16x16x32_bf16 v[114:117], v[134:137], v[168:171], v[114:117]
	v_mfma_f32_16x16x32_bf16 v[106:109], v[142:145], v[168:171], v[106:109]
	v_mfma_f32_16x16x32_bf16 v[98:101], v[134:137], v[176:179], v[98:101]
	v_mfma_f32_16x16x32_bf16 v[90:93], v[142:145], v[176:179], v[90:93]
	v_mfma_f32_16x16x32_bf16 v[82:85], v[134:137], v[184:187], v[82:85]
	v_mfma_f32_16x16x32_bf16 v[74:77], v[142:145], v[184:187], v[74:77]
	s_setprio 0
	s_barrier
	s_add_i32 s48, 0, 0x14000
	s_add_i32 s16, s47, s25
	ds_read_b128 v[188:191], v202 offset:16384
	ds_read_b128 v[198:201], v202 offset:17408
	ds_read_b128 v[208:211], v202 offset:18432
	ds_read_b128 v[212:215], v202 offset:19456
	s_mov_b32 m0, s16
	global_load_lds_dwordx4 v48, s[20:21]
	s_add_i32 m0, s16, 0x2000
	s_nop 0
	global_load_lds_dwordx4 v146, s[20:21]
	s_barrier
	s_waitcnt lgkmcnt(0)
	s_setprio 1
	s_waitcnt lgkmcnt(0)
	v_mfma_f32_16x16x32_bf16 v[118:121], v[188:191], v[156:159], v[118:121]
	v_mfma_f32_16x16x32_bf16 v[110:113], v[208:211], v[156:159], v[110:113]
	v_mfma_f32_16x16x32_bf16 v[102:105], v[188:191], v[164:167], v[102:105]
	v_mfma_f32_16x16x32_bf16 v[94:97], v[208:211], v[164:167], v[94:97]
	v_mfma_f32_16x16x32_bf16 v[86:89], v[188:191], v[172:175], v[86:89]
	v_mfma_f32_16x16x32_bf16 v[78:81], v[208:211], v[172:175], v[78:81]
	v_mfma_f32_16x16x32_bf16 v[70:73], v[188:191], v[180:183], v[70:73]
	v_mfma_f32_16x16x32_bf16 v[66:69], v[208:211], v[180:183], v[66:69]
	v_mfma_f32_16x16x32_bf16 v[118:121], v[198:201], v[160:163], v[118:121]
	v_mfma_f32_16x16x32_bf16 v[110:113], v[212:215], v[160:163], v[110:113]
	v_mfma_f32_16x16x32_bf16 v[102:105], v[198:201], v[168:171], v[102:105]
	v_mfma_f32_16x16x32_bf16 v[94:97], v[212:215], v[168:171], v[94:97]
	v_mfma_f32_16x16x32_bf16 v[86:89], v[198:201], v[176:179], v[86:89]
	v_mfma_f32_16x16x32_bf16 v[78:81], v[212:215], v[176:179], v[78:81]
	v_mfma_f32_16x16x32_bf16 v[70:73], v[198:201], v[184:187], v[70:73]
	v_mfma_f32_16x16x32_bf16 v[66:69], v[212:215], v[184:187], v[66:69]
	s_setprio 0
	s_mov_b32 m0, s31
	v_lshl_add_u64 v[216:217], s[22:23], 0, v[48:49]
	s_barrier
	ds_read_b128 v[156:159], v206 offset:16384
	ds_read_b128 v[160:163], v206 offset:17408
	ds_read_b128 v[164:167], v206 offset:18432
	ds_read_b128 v[168:171], v206 offset:19456
	ds_read_b128 v[172:175], v206 offset:20480
	ds_read_b128 v[176:179], v206 offset:21504
	ds_read_b128 v[180:183], v206 offset:22528
	ds_read_b128 v[184:187], v206 offset:23552
	global_load_lds_dwordx4 v[216:217], off
	v_lshl_add_u64 v[218:219], s[22:23], 0, v[146:147]
	s_mov_b32 m0, s34
	s_nop 0
	global_load_lds_dwordx4 v[218:219], off
	s_barrier
	s_waitcnt lgkmcnt(0)
	s_setprio 1
	s_waitcnt lgkmcnt(0)
	v_mfma_f32_16x16x32_bf16 v[62:65], v[130:133], v[156:159], v[62:65]
	v_mfma_f32_16x16x32_bf16 v[58:61], v[138:141], v[156:159], v[58:61]
	v_mfma_f32_16x16x32_bf16 v[50:53], v[130:133], v[164:167], v[50:53]
	v_mfma_f32_16x16x32_bf16 v[40:43], v[138:141], v[164:167], v[40:43]
	v_mfma_f32_16x16x32_bf16 v[32:35], v[130:133], v[172:175], v[32:35]
	v_mfma_f32_16x16x32_bf16 v[24:27], v[138:141], v[172:175], v[24:27]
	v_mfma_f32_16x16x32_bf16 v[16:19], v[130:133], v[180:183], v[16:19]
	v_mfma_f32_16x16x32_bf16 v[8:11], v[138:141], v[180:183], v[8:11]
	v_mfma_f32_16x16x32_bf16 v[62:65], v[134:137], v[160:163], v[62:65]
	v_mfma_f32_16x16x32_bf16 v[58:61], v[142:145], v[160:163], v[58:61]
	v_mfma_f32_16x16x32_bf16 v[50:53], v[134:137], v[168:171], v[50:53]
	v_mfma_f32_16x16x32_bf16 v[40:43], v[142:145], v[168:171], v[40:43]
	v_mfma_f32_16x16x32_bf16 v[32:35], v[134:137], v[176:179], v[32:35]
	v_mfma_f32_16x16x32_bf16 v[24:27], v[142:145], v[176:179], v[24:27]
	v_mfma_f32_16x16x32_bf16 v[16:19], v[134:137], v[184:187], v[16:19]
	v_mfma_f32_16x16x32_bf16 v[8:11], v[142:145], v[184:187], v[8:11]
	s_setprio 0
	s_barrier
	s_add_u32 s16, s20, 0xb0000
	s_addc_u32 s17, s21, 0
	s_add_i32 s47, s48, s25
	s_mov_b32 m0, s47
	s_nop 0
	global_load_lds_dwordx4 v48, s[16:17]
	s_add_i32 m0, s47, 0x2000
	s_nop 0
	global_load_lds_dwordx4 v146, s[16:17]
	s_waitcnt vmcnt(6)
	s_barrier
	s_setprio 1
	v_mfma_f32_16x16x32_bf16 v[54:57], v[188:191], v[156:159], v[54:57]
	v_mfma_f32_16x16x32_bf16 v[44:47], v[208:211], v[156:159], v[44:47]
	v_mfma_f32_16x16x32_bf16 v[36:39], v[188:191], v[164:167], v[36:39]
	v_mfma_f32_16x16x32_bf16 v[28:31], v[208:211], v[164:167], v[28:31]
	v_mfma_f32_16x16x32_bf16 v[20:23], v[188:191], v[172:175], v[20:23]
	v_mfma_f32_16x16x32_bf16 v[12:15], v[208:211], v[172:175], v[12:15]
	v_mfma_f32_16x16x32_bf16 v[4:7], v[188:191], v[180:183], v[4:7]
	v_mfma_f32_16x16x32_bf16 v[0:3], v[208:211], v[180:183], v[0:3]
	v_mfma_f32_16x16x32_bf16 v[54:57], v[198:201], v[160:163], v[54:57]
	v_mfma_f32_16x16x32_bf16 v[44:47], v[212:215], v[160:163], v[44:47]
	v_mfma_f32_16x16x32_bf16 v[36:39], v[198:201], v[168:171], v[36:39]
	v_mfma_f32_16x16x32_bf16 v[28:31], v[212:215], v[168:171], v[28:31]
	v_mfma_f32_16x16x32_bf16 v[20:23], v[198:201], v[176:179], v[20:23]
	v_mfma_f32_16x16x32_bf16 v[12:15], v[212:215], v[176:179], v[12:15]
	v_mfma_f32_16x16x32_bf16 v[4:7], v[198:201], v[184:187], v[4:7]
	v_mfma_f32_16x16x32_bf16 v[0:3], v[212:215], v[184:187], v[0:3]
	s_setprio 0
	s_add_i32 s47, 0, 0x18000
	s_barrier
	ds_read_b128 v[130:133], v202 offset:32768
	ds_read_b128 v[134:137], v202 offset:33792
	ds_read_b128 v[138:141], v202 offset:34816
	ds_read_b128 v[142:145], v202 offset:35840
	s_add_u32 s16, s22, 0xb0000
	s_addc_u32 s17, s23, 0
	s_mov_b32 m0, s35
	ds_read_b128 v[156:159], v206 offset:32768
	ds_read_b128 v[160:163], v206 offset:33792
	ds_read_b128 v[164:167], v206 offset:34816
	ds_read_b128 v[168:171], v206 offset:35840
	ds_read_b128 v[172:175], v206 offset:36864
	ds_read_b128 v[176:179], v206 offset:37888
	ds_read_b128 v[180:183], v206 offset:38912
	ds_read_b128 v[184:187], v206 offset:39936
	global_load_lds_dwordx4 v48, s[16:17]
	s_mov_b32 m0, s36
	s_nop 0
	global_load_lds_dwordx4 v146, s[16:17]
	s_waitcnt lgkmcnt(8)
	s_barrier
	s_waitcnt lgkmcnt(0)
	s_setprio 1
	s_waitcnt lgkmcnt(0)
	v_mfma_f32_16x16x32_bf16 v[126:129], v[130:133], v[156:159], v[126:129]
	v_mfma_f32_16x16x32_bf16 v[122:125], v[138:141], v[156:159], v[122:125]
	v_mfma_f32_16x16x32_bf16 v[114:117], v[130:133], v[164:167], v[114:117]
	v_mfma_f32_16x16x32_bf16 v[106:109], v[138:141], v[164:167], v[106:109]
	v_mfma_f32_16x16x32_bf16 v[98:101], v[130:133], v[172:175], v[98:101]
	v_mfma_f32_16x16x32_bf16 v[90:93], v[138:141], v[172:175], v[90:93]
	v_mfma_f32_16x16x32_bf16 v[82:85], v[130:133], v[180:183], v[82:85]
	v_mfma_f32_16x16x32_bf16 v[74:77], v[138:141], v[180:183], v[74:77]
	v_mfma_f32_16x16x32_bf16 v[126:129], v[134:137], v[160:163], v[126:129]
	v_mfma_f32_16x16x32_bf16 v[122:125], v[142:145], v[160:163], v[122:125]
	v_mfma_f32_16x16x32_bf16 v[114:117], v[134:137], v[168:171], v[114:117]
	v_mfma_f32_16x16x32_bf16 v[106:109], v[142:145], v[168:171], v[106:109]
	v_mfma_f32_16x16x32_bf16 v[98:101], v[134:137], v[176:179], v[98:101]
	v_mfma_f32_16x16x32_bf16 v[90:93], v[142:145], v[176:179], v[90:93]
	v_mfma_f32_16x16x32_bf16 v[82:85], v[134:137], v[184:187], v[82:85]
	v_mfma_f32_16x16x32_bf16 v[74:77], v[142:145], v[184:187], v[74:77]
	s_setprio 0
	s_barrier
	s_add_i32 s22, 0, 0x1c000
	s_add_i32 s16, s47, s25
	s_add_u32 s52, s20, s66
	s_addc_u32 s53, s21, s67
	s_mov_b32 m0, s16
	ds_read_b128 v[188:191], v202 offset:49152
	ds_read_b128 v[198:201], v202 offset:50176
	ds_read_b128 v[208:211], v202 offset:51200
	ds_read_b128 v[212:215], v202 offset:52224
	global_load_lds_dwordx4 v48, s[52:53]
	s_add_i32 m0, s16, 0x2000
	s_nop 0
	global_load_lds_dwordx4 v146, s[52:53]
	s_barrier
	s_waitcnt lgkmcnt(0)
	s_setprio 1
	s_waitcnt lgkmcnt(0)
	v_mfma_f32_16x16x32_bf16 v[118:121], v[188:191], v[156:159], v[118:121]
	v_mfma_f32_16x16x32_bf16 v[110:113], v[208:211], v[156:159], v[110:113]
	v_mfma_f32_16x16x32_bf16 v[102:105], v[188:191], v[164:167], v[102:105]
	v_mfma_f32_16x16x32_bf16 v[94:97], v[208:211], v[164:167], v[94:97]
	v_mfma_f32_16x16x32_bf16 v[86:89], v[188:191], v[172:175], v[86:89]
	v_mfma_f32_16x16x32_bf16 v[78:81], v[208:211], v[172:175], v[78:81]
	v_mfma_f32_16x16x32_bf16 v[70:73], v[188:191], v[180:183], v[70:73]
	v_mfma_f32_16x16x32_bf16 v[66:69], v[208:211], v[180:183], v[66:69]
	v_mfma_f32_16x16x32_bf16 v[118:121], v[198:201], v[160:163], v[118:121]
	v_mfma_f32_16x16x32_bf16 v[110:113], v[212:215], v[160:163], v[110:113]
	v_mfma_f32_16x16x32_bf16 v[102:105], v[198:201], v[168:171], v[102:105]
	v_mfma_f32_16x16x32_bf16 v[94:97], v[212:215], v[168:171], v[94:97]
	v_mfma_f32_16x16x32_bf16 v[86:89], v[198:201], v[176:179], v[86:89]
	v_mfma_f32_16x16x32_bf16 v[78:81], v[212:215], v[176:179], v[78:81]
	v_mfma_f32_16x16x32_bf16 v[70:73], v[198:201], v[184:187], v[70:73]
	v_mfma_f32_16x16x32_bf16 v[66:69], v[212:215], v[184:187], v[66:69]
	s_setprio 0
	s_mov_b32 m0, s39
	v_lshl_add_u64 v[192:193], v[216:217], 0, s[66:67]
	s_barrier
	ds_read_b128 v[156:159], v206 offset:49152
	ds_read_b128 v[160:163], v206 offset:50176
	ds_read_b128 v[164:167], v206 offset:51200
	ds_read_b128 v[168:171], v206 offset:52224
	ds_read_b128 v[172:175], v206 offset:53248
	ds_read_b128 v[176:179], v206 offset:54272
	ds_read_b128 v[180:183], v206 offset:55296
	ds_read_b128 v[184:187], v206 offset:56320
	global_load_lds_dwordx4 v[192:193], off
	v_lshl_add_u64 v[192:193], v[218:219], 0, s[66:67]
	s_mov_b32 m0, s40
	s_nop 0
	global_load_lds_dwordx4 v[192:193], off
	s_barrier
	s_waitcnt lgkmcnt(0)
	s_setprio 1
	s_waitcnt lgkmcnt(0)
	v_mfma_f32_16x16x32_bf16 v[62:65], v[130:133], v[156:159], v[62:65]
	v_mfma_f32_16x16x32_bf16 v[58:61], v[138:141], v[156:159], v[58:61]
	v_mfma_f32_16x16x32_bf16 v[50:53], v[130:133], v[164:167], v[50:53]
	v_mfma_f32_16x16x32_bf16 v[40:43], v[138:141], v[164:167], v[40:43]
	v_mfma_f32_16x16x32_bf16 v[32:35], v[130:133], v[172:175], v[32:35]
	v_mfma_f32_16x16x32_bf16 v[24:27], v[138:141], v[172:175], v[24:27]
	v_mfma_f32_16x16x32_bf16 v[16:19], v[130:133], v[180:183], v[16:19]
	v_mfma_f32_16x16x32_bf16 v[8:11], v[138:141], v[180:183], v[8:11]
	v_mfma_f32_16x16x32_bf16 v[62:65], v[134:137], v[160:163], v[62:65]
	v_mfma_f32_16x16x32_bf16 v[58:61], v[142:145], v[160:163], v[58:61]
	v_mfma_f32_16x16x32_bf16 v[50:53], v[134:137], v[168:171], v[50:53]
	v_mfma_f32_16x16x32_bf16 v[40:43], v[142:145], v[168:171], v[40:43]
	v_mfma_f32_16x16x32_bf16 v[32:35], v[134:137], v[176:179], v[32:35]
	v_mfma_f32_16x16x32_bf16 v[24:27], v[142:145], v[176:179], v[24:27]
	v_mfma_f32_16x16x32_bf16 v[16:19], v[134:137], v[184:187], v[16:19]
	v_mfma_f32_16x16x32_bf16 v[8:11], v[142:145], v[184:187], v[8:11]
	s_setprio 0
	s_barrier
	s_add_u32 s16, s20, 0xb0080
	s_addc_u32 s17, s21, 0
	s_add_i32 s20, s22, s25
	s_mov_b32 m0, s20
	s_nop 0
	global_load_lds_dwordx4 v48, s[16:17]
	s_add_i32 m0, s20, 0x2000
	s_nop 0
	global_load_lds_dwordx4 v146, s[16:17]
	s_waitcnt vmcnt(6)
	s_barrier
	s_setprio 1
	v_mfma_f32_16x16x32_bf16 v[54:57], v[188:191], v[156:159], v[54:57]
	v_mfma_f32_16x16x32_bf16 v[44:47], v[208:211], v[156:159], v[44:47]
	v_mfma_f32_16x16x32_bf16 v[36:39], v[188:191], v[164:167], v[36:39]
	v_mfma_f32_16x16x32_bf16 v[28:31], v[208:211], v[164:167], v[28:31]
	v_mfma_f32_16x16x32_bf16 v[20:23], v[188:191], v[172:175], v[20:23]
	v_mfma_f32_16x16x32_bf16 v[12:15], v[208:211], v[172:175], v[12:15]
	v_mfma_f32_16x16x32_bf16 v[4:7], v[188:191], v[180:183], v[4:7]
	v_mfma_f32_16x16x32_bf16 v[0:3], v[208:211], v[180:183], v[0:3]
	v_mfma_f32_16x16x32_bf16 v[54:57], v[198:201], v[160:163], v[54:57]
	v_mfma_f32_16x16x32_bf16 v[44:47], v[212:215], v[160:163], v[44:47]
	v_mfma_f32_16x16x32_bf16 v[36:39], v[198:201], v[168:171], v[36:39]
	v_mfma_f32_16x16x32_bf16 v[28:31], v[212:215], v[168:171], v[28:31]
	v_mfma_f32_16x16x32_bf16 v[20:23], v[198:201], v[176:179], v[20:23]
	v_mfma_f32_16x16x32_bf16 v[12:15], v[212:215], v[176:179], v[12:15]
	v_mfma_f32_16x16x32_bf16 v[4:7], v[198:201], v[184:187], v[4:7]
	v_mfma_f32_16x16x32_bf16 v[0:3], v[212:215], v[184:187], v[0:3]
	s_setprio 0
	s_add_i32 s46, s46, 2
	s_add_u32 s44, s44, 0x100
	s_addc_u32 s45, s45, 0
	s_cmp_gt_u32 s46, 41
	s_mov_b64 s[16:17], s[18:19]
	s_barrier
	s_cbranch_scc0 .LBB0_1421
	s_mul_hi_i32 s16, s14, 0x38e38e39
	s_lshr_b32 s17, s16, 31
	s_ashr_i32 s16, s16, 1
	s_add_i32 s16, s16, s17
	s_mul_i32 s17, s16, -9
	v_lshl_or_b32 v156, s15, 8, v205
	s_ashr_i32 s15, s14, 31
	s_add_i32 s18, s17, s14
	s_lshl_b64 s[14:15], s[14:15], 19
	s_ashr_i32 s17, s16, 31
	v_lshl_add_u64 v[158:159], v[150:151], 0, s[14:15]
	v_sub_co_u32_e64 v130, s[14:15], s18, 1
	s_lshl_b64 s[18:19], s[16:17], 23
	s_and_b64 s[14:15], s[14:15], exec
	v_ashrrev_i32_e32 v131, 31, v130
	s_cselect_b32 s14, 32, s16
	v_lshlrev_b64 v[130:131], 20, v[130:131]
	s_mul_hi_i32 s15, s14, 0x6000
	s_mulk_i32 s14, 0x6000
	v_ashrrev_i32_e32 v157, 31, v156
	v_lshl_add_u64 v[130:131], s[6:7], 0, v[130:131]
	s_add_u32 s14, s37, s14
	v_lshl_add_u64 v[130:131], v[130:131], 0, s[18:19]
	s_addc_u32 s15, s38, s15
	v_lshlrev_b64 v[208:209], 2, v[156:157]
	v_lshl_add_u64 v[162:163], v[130:131], 0, v[148:149]
	v_lshl_add_u64 v[130:131], s[14:15], 0, v[208:209]
	v_lshl_add_u64 v[156:157], v[156:157], 1, v[158:159]
	global_load_dwordx4 v[142:145], v[130:131], off
	global_load_dwordx4 v[138:141], v[130:131], off offset:64
	global_load_dwordx4 v[134:137], v[130:131], off offset:512
	s_nop 0
	global_load_dwordx4 v[130:133], v[130:131], off offset:576
	s_nop 0
	s_mov_b32 s14, 0x40000
	s_nop 0
	v_lshl_add_u64 v[162:163], v[162:163], 0, v[208:209]
	s_nop 0
	s_mov_b32 s15, s42
	s_nop 0
	s_mov_b32 s14, 0x48000
	s_nop 0
	s_mov_b32 s14, 0x50000
	s_nop 0
	s_mov_b32 s14, 0x58000
	s_nop 0
	s_mov_b32 s14, 0x20000
	s_nop 0
	s_nop 0
	s_mov_b64 s[18:19], s[12:13]
	s_mov_b64 s[16:17], s[10:11]
	v_and_b32_e32 v202, 16, v224
	v_lshrrev_b32_e32 v203, 1, v202
	v_add_u32_e32 v202, v202, v203
	v_mov_b32_e32 v203, 0
	v_mov_b32_e32 v223, 0
	v_lshl_add_u64 v[246:247], v[156:157], 0, v[202:203]
	v_mov_b32_e32 v222, 0x0
	v_lshl_add_u64 v[190:191], v[246:247], 0, v[222:223]
	global_load_dwordx4 v[198:201], v[190:191], off
	global_load_dwordx4 v[218:221], v[190:191], off offset:256
	v_mov_b32_e32 v222, 0x8000
	v_lshl_add_u64 v[190:191], v[246:247], 0, v[222:223]
	global_load_dwordx4 v[242:245], v[190:191], off
	global_load_dwordx4 v[164:167], v[190:191], off offset:256
	v_mov_b32_e32 v222, 0x10000
	v_lshl_add_u64 v[190:191], v[246:247], 0, v[222:223]
	global_load_dwordx4 v[168:171], v[190:191], off
	global_load_dwordx4 v[172:175], v[190:191], off offset:256
	v_mov_b32_e32 v222, 0x18000
	v_lshl_add_u64 v[190:191], v[246:247], 0, v[222:223]
	global_load_dwordx4 v[176:179], v[190:191], off
	global_load_dwordx4 v[180:183], v[190:191], off offset:256
	v_mov_b32_e32 v222, 0x40000
	v_lshl_add_u64 v[190:191], v[246:247], 0, v[222:223]
	global_load_dwordx4 v[184:187], v[190:191], off
	s_waitcnt vmcnt(8)
	v_permlane16_swap_b32 v198, v200
	v_permlane16_swap_b32 v199, v201
	s_nop 1
	v_lshlrev_b32_e32 v210, 16, v198
	v_and_b32_e32 v211, 0xffff0000, v198
	v_lshlrev_b32_e32 v212, 16, v199
	v_and_b32_e32 v213, 0xffff0000, v199
	v_pk_fma_f32 v[126:127], v[126:127], v[142:143], v[210:211]
	v_pk_fma_f32 v[128:129], v[128:129], v[144:145], v[212:213]
	v_lshlrev_b32_e32 v214, 16, v200
	v_and_b32_e32 v215, 0xffff0000, v200
	v_lshlrev_b32_e32 v216, 16, v201
	v_and_b32_e32 v217, 0xffff0000, v201
	v_pk_fma_f32 v[122:123], v[122:123], v[138:139], v[214:215]
	v_pk_fma_f32 v[124:125], v[124:125], v[140:141], v[216:217]
	v_mov_b32_e32 v222, 0x0
	v_lshl_add_u64 v[192:193], v[162:163], 0, v[222:223]
	global_store_dwordx4 v[192:193], v[126:129], off
	global_store_dwordx4 v[192:193], v[122:125], off offset:64
	global_load_dwordx4 v[198:201], v[190:191], off offset:256
	s_waitcnt vmcnt(10)
	v_permlane16_swap_b32 v218, v220
	v_permlane16_swap_b32 v219, v221
	s_nop 1
	v_lshlrev_b32_e32 v210, 16, v218
	v_and_b32_e32 v211, 0xffff0000, v218
	v_lshlrev_b32_e32 v212, 16, v219
	v_and_b32_e32 v213, 0xffff0000, v219
	v_pk_fma_f32 v[118:119], v[118:119], v[134:135], v[210:211]
	v_pk_fma_f32 v[120:121], v[120:121], v[136:137], v[212:213]
	v_lshlrev_b32_e32 v214, 16, v220
	v_and_b32_e32 v215, 0xffff0000, v220
	v_lshlrev_b32_e32 v216, 16, v221
	v_and_b32_e32 v217, 0xffff0000, v221
	v_pk_fma_f32 v[110:111], v[110:111], v[130:131], v[214:215]
	v_pk_fma_f32 v[112:113], v[112:113], v[132:133], v[216:217]
	v_mov_b32_e32 v222, 0x0
	v_lshl_add_u64 v[192:193], v[162:163], 0, v[222:223]
	global_store_dwordx4 v[192:193], v[118:121], off offset:512
	global_store_dwordx4 v[192:193], v[110:113], off offset:576
	v_mov_b32_e32 v222, 0x48000
	v_lshl_add_u64 v[190:191], v[246:247], 0, v[222:223]
	global_load_dwordx4 v[218:221], v[190:191], off
	s_waitcnt vmcnt(12)
	v_permlane16_swap_b32 v242, v244
	v_permlane16_swap_b32 v243, v245
	s_nop 1
	v_lshlrev_b32_e32 v210, 16, v242
	v_and_b32_e32 v211, 0xffff0000, v242
	v_lshlrev_b32_e32 v212, 16, v243
	v_and_b32_e32 v213, 0xffff0000, v243
	v_pk_fma_f32 v[114:115], v[114:115], v[142:143], v[210:211]
	v_pk_fma_f32 v[116:117], v[116:117], v[144:145], v[212:213]
	v_lshlrev_b32_e32 v214, 16, v244
	v_and_b32_e32 v215, 0xffff0000, v244
	v_lshlrev_b32_e32 v216, 16, v245
	v_and_b32_e32 v217, 0xffff0000, v245
	v_pk_fma_f32 v[106:107], v[106:107], v[138:139], v[214:215]
	v_pk_fma_f32 v[108:109], v[108:109], v[140:141], v[216:217]
	v_mov_b32_e32 v222, 0x10000
	v_lshl_add_u64 v[192:193], v[162:163], 0, v[222:223]
	global_store_dwordx4 v[192:193], v[114:117], off
	global_store_dwordx4 v[192:193], v[106:109], off offset:64
	global_load_dwordx4 v[242:245], v[190:191], off offset:256
	s_waitcnt vmcnt(14)
	v_permlane16_swap_b32 v164, v166
	v_permlane16_swap_b32 v165, v167
	s_nop 1
	v_lshlrev_b32_e32 v210, 16, v164
	v_and_b32_e32 v211, 0xffff0000, v164
	v_lshlrev_b32_e32 v212, 16, v165
	v_and_b32_e32 v213, 0xffff0000, v165
	v_pk_fma_f32 v[102:103], v[102:103], v[134:135], v[210:211]
	v_pk_fma_f32 v[104:105], v[104:105], v[136:137], v[212:213]
	v_lshlrev_b32_e32 v214, 16, v166
	v_and_b32_e32 v215, 0xffff0000, v166
	v_lshlrev_b32_e32 v216, 16, v167
	v_and_b32_e32 v217, 0xffff0000, v167
	v_pk_fma_f32 v[94:95], v[94:95], v[130:131], v[214:215]
	v_pk_fma_f32 v[96:97], v[96:97], v[132:133], v[216:217]
	v_mov_b32_e32 v222, 0x10000
	v_lshl_add_u64 v[192:193], v[162:163], 0, v[222:223]
	global_store_dwordx4 v[192:193], v[102:105], off offset:512
	global_store_dwordx4 v[192:193], v[94:97], off offset:576
	v_mov_b32_e32 v222, 0x50000
	v_lshl_add_u64 v[190:191], v[246:247], 0, v[222:223]
	global_load_dwordx4 v[164:167], v[190:191], off
	s_waitcnt vmcnt(16)
	v_permlane16_swap_b32 v168, v170
	v_permlane16_swap_b32 v169, v171
	s_nop 1
	v_lshlrev_b32_e32 v210, 16, v168
	v_and_b32_e32 v211, 0xffff0000, v168
	v_lshlrev_b32_e32 v212, 16, v169
	v_and_b32_e32 v213, 0xffff0000, v169
	v_pk_fma_f32 v[98:99], v[98:99], v[142:143], v[210:211]
	v_pk_fma_f32 v[100:101], v[100:101], v[144:145], v[212:213]
	v_lshlrev_b32_e32 v214, 16, v170
	v_and_b32_e32 v215, 0xffff0000, v170
	v_lshlrev_b32_e32 v216, 16, v171
	v_and_b32_e32 v217, 0xffff0000, v171
	v_pk_fma_f32 v[90:91], v[90:91], v[138:139], v[214:215]
	v_pk_fma_f32 v[92:93], v[92:93], v[140:141], v[216:217]
	v_mov_b32_e32 v222, 0x20000
	v_lshl_add_u64 v[192:193], v[162:163], 0, v[222:223]
	global_store_dwordx4 v[192:193], v[98:101], off
	global_store_dwordx4 v[192:193], v[90:93], off offset:64
	global_load_dwordx4 v[168:171], v[190:191], off offset:256
	s_waitcnt vmcnt(18)
	v_permlane16_swap_b32 v172, v174
	v_permlane16_swap_b32 v173, v175
	s_nop 1
	v_lshlrev_b32_e32 v210, 16, v172
	v_and_b32_e32 v211, 0xffff0000, v172
	v_lshlrev_b32_e32 v212, 16, v173
	v_and_b32_e32 v213, 0xffff0000, v173
	v_pk_fma_f32 v[86:87], v[86:87], v[134:135], v[210:211]
	v_pk_fma_f32 v[88:89], v[88:89], v[136:137], v[212:213]
	v_lshlrev_b32_e32 v214, 16, v174
	v_and_b32_e32 v215, 0xffff0000, v174
	v_lshlrev_b32_e32 v216, 16, v175
	v_and_b32_e32 v217, 0xffff0000, v175
	v_pk_fma_f32 v[78:79], v[78:79], v[130:131], v[214:215]
	v_pk_fma_f32 v[80:81], v[80:81], v[132:133], v[216:217]
	v_mov_b32_e32 v222, 0x20000
	v_lshl_add_u64 v[192:193], v[162:163], 0, v[222:223]
	global_store_dwordx4 v[192:193], v[86:89], off offset:512
	global_store_dwordx4 v[192:193], v[78:81], off offset:576
	v_mov_b32_e32 v222, 0x58000
	v_lshl_add_u64 v[190:191], v[246:247], 0, v[222:223]
	global_load_dwordx4 v[172:175], v[190:191], off
	s_waitcnt vmcnt(20)
	v_permlane16_swap_b32 v176, v178
	v_permlane16_swap_b32 v177, v179
	s_nop 1
	v_lshlrev_b32_e32 v210, 16, v176
	v_and_b32_e32 v211, 0xffff0000, v176
	v_lshlrev_b32_e32 v212, 16, v177
	v_and_b32_e32 v213, 0xffff0000, v177
	v_pk_fma_f32 v[82:83], v[82:83], v[142:143], v[210:211]
	v_pk_fma_f32 v[84:85], v[84:85], v[144:145], v[212:213]
	v_lshlrev_b32_e32 v214, 16, v178
	v_and_b32_e32 v215, 0xffff0000, v178
	v_lshlrev_b32_e32 v216, 16, v179
	v_and_b32_e32 v217, 0xffff0000, v179
	v_pk_fma_f32 v[74:75], v[74:75], v[138:139], v[214:215]
	v_pk_fma_f32 v[76:77], v[76:77], v[140:141], v[216:217]
	v_mov_b32_e32 v222, 0x30000
	v_lshl_add_u64 v[192:193], v[162:163], 0, v[222:223]
	global_store_dwordx4 v[192:193], v[82:85], off
	global_store_dwordx4 v[192:193], v[74:77], off offset:64
	global_load_dwordx4 v[176:179], v[190:191], off offset:256
	s_waitcnt vmcnt(22)
	v_permlane16_swap_b32 v180, v182
	v_permlane16_swap_b32 v181, v183
	s_nop 1
	v_lshlrev_b32_e32 v210, 16, v180
	v_and_b32_e32 v211, 0xffff0000, v180
	v_lshlrev_b32_e32 v212, 16, v181
	v_and_b32_e32 v213, 0xffff0000, v181
	v_pk_fma_f32 v[70:71], v[70:71], v[134:135], v[210:211]
	v_pk_fma_f32 v[72:73], v[72:73], v[136:137], v[212:213]
	v_lshlrev_b32_e32 v214, 16, v182
	v_and_b32_e32 v215, 0xffff0000, v182
	v_lshlrev_b32_e32 v216, 16, v183
	v_and_b32_e32 v217, 0xffff0000, v183
	v_pk_fma_f32 v[66:67], v[66:67], v[130:131], v[214:215]
	v_pk_fma_f32 v[68:69], v[68:69], v[132:133], v[216:217]
	v_mov_b32_e32 v222, 0x30000
	v_lshl_add_u64 v[192:193], v[162:163], 0, v[222:223]
	global_store_dwordx4 v[192:193], v[70:73], off offset:512
	global_store_dwordx4 v[192:193], v[66:69], off offset:576
	s_waitcnt vmcnt(23)
	v_permlane16_swap_b32 v184, v186
	v_permlane16_swap_b32 v185, v187
	s_nop 1
	v_lshlrev_b32_e32 v210, 16, v184
	v_and_b32_e32 v211, 0xffff0000, v184
	v_lshlrev_b32_e32 v212, 16, v185
	v_and_b32_e32 v213, 0xffff0000, v185
	v_pk_fma_f32 v[62:63], v[62:63], v[142:143], v[210:211]
	v_pk_fma_f32 v[64:65], v[64:65], v[144:145], v[212:213]
	v_lshlrev_b32_e32 v214, 16, v186
	v_and_b32_e32 v215, 0xffff0000, v186
	v_lshlrev_b32_e32 v216, 16, v187
	v_and_b32_e32 v217, 0xffff0000, v187
	v_pk_fma_f32 v[58:59], v[58:59], v[138:139], v[214:215]
	v_pk_fma_f32 v[60:61], v[60:61], v[140:141], v[216:217]
	v_mov_b32_e32 v222, 0x80000
	v_lshl_add_u64 v[192:193], v[162:163], 0, v[222:223]
	global_store_dwordx4 v[192:193], v[62:65], off
	global_store_dwordx4 v[192:193], v[58:61], off offset:64
	s_waitcnt vmcnt(22)
	v_permlane16_swap_b32 v198, v200
	v_permlane16_swap_b32 v199, v201
	s_nop 1
	v_lshlrev_b32_e32 v210, 16, v198
	v_and_b32_e32 v211, 0xffff0000, v198
	v_lshlrev_b32_e32 v212, 16, v199
	v_and_b32_e32 v213, 0xffff0000, v199
	v_pk_fma_f32 v[54:55], v[54:55], v[134:135], v[210:211]
	v_pk_fma_f32 v[56:57], v[56:57], v[136:137], v[212:213]
	v_lshlrev_b32_e32 v214, 16, v200
	v_and_b32_e32 v215, 0xffff0000, v200
	v_lshlrev_b32_e32 v216, 16, v201
	v_and_b32_e32 v217, 0xffff0000, v201
	v_pk_fma_f32 v[44:45], v[44:45], v[130:131], v[214:215]
	v_pk_fma_f32 v[46:47], v[46:47], v[132:133], v[216:217]
	v_mov_b32_e32 v222, 0x80000
	v_lshl_add_u64 v[192:193], v[162:163], 0, v[222:223]
	global_store_dwordx4 v[192:193], v[54:57], off offset:512
	global_store_dwordx4 v[192:193], v[44:47], off offset:576
	s_waitcnt vmcnt(21)
	v_permlane16_swap_b32 v218, v220
	v_permlane16_swap_b32 v219, v221
	s_nop 1
	v_lshlrev_b32_e32 v210, 16, v218
	v_and_b32_e32 v211, 0xffff0000, v218
	v_lshlrev_b32_e32 v212, 16, v219
	v_and_b32_e32 v213, 0xffff0000, v219
	v_pk_fma_f32 v[50:51], v[50:51], v[142:143], v[210:211]
	v_pk_fma_f32 v[52:53], v[52:53], v[144:145], v[212:213]
	v_lshlrev_b32_e32 v214, 16, v220
	v_and_b32_e32 v215, 0xffff0000, v220
	v_lshlrev_b32_e32 v216, 16, v221
	v_and_b32_e32 v217, 0xffff0000, v221
	v_pk_fma_f32 v[40:41], v[40:41], v[138:139], v[214:215]
	v_pk_fma_f32 v[42:43], v[42:43], v[140:141], v[216:217]
	v_mov_b32_e32 v222, 0x90000
	v_lshl_add_u64 v[192:193], v[162:163], 0, v[222:223]
	global_store_dwordx4 v[192:193], v[50:53], off
	global_store_dwordx4 v[192:193], v[40:43], off offset:64
	s_waitcnt vmcnt(20)
	v_permlane16_swap_b32 v242, v244
	v_permlane16_swap_b32 v243, v245
	s_nop 1
	v_lshlrev_b32_e32 v210, 16, v242
	v_and_b32_e32 v211, 0xffff0000, v242
	v_lshlrev_b32_e32 v212, 16, v243
	v_and_b32_e32 v213, 0xffff0000, v243
	v_pk_fma_f32 v[36:37], v[36:37], v[134:135], v[210:211]
	v_pk_fma_f32 v[38:39], v[38:39], v[136:137], v[212:213]
	v_lshlrev_b32_e32 v214, 16, v244
	v_and_b32_e32 v215, 0xffff0000, v244
	v_lshlrev_b32_e32 v216, 16, v245
	v_and_b32_e32 v217, 0xffff0000, v245
	v_pk_fma_f32 v[28:29], v[28:29], v[130:131], v[214:215]
	v_pk_fma_f32 v[30:31], v[30:31], v[132:133], v[216:217]
	v_mov_b32_e32 v222, 0x90000
	v_lshl_add_u64 v[192:193], v[162:163], 0, v[222:223]
	global_store_dwordx4 v[192:193], v[36:39], off offset:512
	global_store_dwordx4 v[192:193], v[28:31], off offset:576
	s_waitcnt vmcnt(19)
	v_permlane16_swap_b32 v164, v166
	v_permlane16_swap_b32 v165, v167
	s_nop 1
	v_lshlrev_b32_e32 v210, 16, v164
	v_and_b32_e32 v211, 0xffff0000, v164
	v_lshlrev_b32_e32 v212, 16, v165
	v_and_b32_e32 v213, 0xffff0000, v165
	v_pk_fma_f32 v[32:33], v[32:33], v[142:143], v[210:211]
	v_pk_fma_f32 v[34:35], v[34:35], v[144:145], v[212:213]
	v_lshlrev_b32_e32 v214, 16, v166
	v_and_b32_e32 v215, 0xffff0000, v166
	v_lshlrev_b32_e32 v216, 16, v167
	v_and_b32_e32 v217, 0xffff0000, v167
	v_pk_fma_f32 v[24:25], v[24:25], v[138:139], v[214:215]
	v_pk_fma_f32 v[26:27], v[26:27], v[140:141], v[216:217]
	v_mov_b32_e32 v222, 0xa0000
	v_lshl_add_u64 v[192:193], v[162:163], 0, v[222:223]
	global_store_dwordx4 v[192:193], v[32:35], off
	global_store_dwordx4 v[192:193], v[24:27], off offset:64
	s_waitcnt vmcnt(18)
	v_permlane16_swap_b32 v168, v170
	v_permlane16_swap_b32 v169, v171
	s_nop 1
	v_lshlrev_b32_e32 v210, 16, v168
	v_and_b32_e32 v211, 0xffff0000, v168
	v_lshlrev_b32_e32 v212, 16, v169
	v_and_b32_e32 v213, 0xffff0000, v169
	v_pk_fma_f32 v[20:21], v[20:21], v[134:135], v[210:211]
	v_pk_fma_f32 v[22:23], v[22:23], v[136:137], v[212:213]
	v_lshlrev_b32_e32 v214, 16, v170
	v_and_b32_e32 v215, 0xffff0000, v170
	v_lshlrev_b32_e32 v216, 16, v171
	v_and_b32_e32 v217, 0xffff0000, v171
	v_pk_fma_f32 v[12:13], v[12:13], v[130:131], v[214:215]
	v_pk_fma_f32 v[14:15], v[14:15], v[132:133], v[216:217]
	v_mov_b32_e32 v222, 0xa0000
	v_lshl_add_u64 v[192:193], v[162:163], 0, v[222:223]
	global_store_dwordx4 v[192:193], v[20:23], off offset:512
	global_store_dwordx4 v[192:193], v[12:15], off offset:576
	s_waitcnt vmcnt(17)
	v_permlane16_swap_b32 v172, v174
	v_permlane16_swap_b32 v173, v175
	s_nop 1
	v_lshlrev_b32_e32 v210, 16, v172
	v_and_b32_e32 v211, 0xffff0000, v172
	v_lshlrev_b32_e32 v212, 16, v173
	v_and_b32_e32 v213, 0xffff0000, v173
	v_pk_fma_f32 v[16:17], v[16:17], v[142:143], v[210:211]
	v_pk_fma_f32 v[18:19], v[18:19], v[144:145], v[212:213]
	v_lshlrev_b32_e32 v214, 16, v174
	v_and_b32_e32 v215, 0xffff0000, v174
	v_lshlrev_b32_e32 v216, 16, v175
	v_and_b32_e32 v217, 0xffff0000, v175
	v_pk_fma_f32 v[8:9], v[8:9], v[138:139], v[214:215]
	v_pk_fma_f32 v[10:11], v[10:11], v[140:141], v[216:217]
	v_mov_b32_e32 v222, 0xb0000
	v_lshl_add_u64 v[192:193], v[162:163], 0, v[222:223]
	global_store_dwordx4 v[192:193], v[16:19], off
	global_store_dwordx4 v[192:193], v[8:11], off offset:64
	s_waitcnt vmcnt(16)
	v_permlane16_swap_b32 v176, v178
	v_permlane16_swap_b32 v177, v179
	s_nop 1
	v_lshlrev_b32_e32 v210, 16, v176
	v_and_b32_e32 v211, 0xffff0000, v176
	v_lshlrev_b32_e32 v212, 16, v177
	v_and_b32_e32 v213, 0xffff0000, v177
	v_pk_fma_f32 v[4:5], v[4:5], v[134:135], v[210:211]
	v_pk_fma_f32 v[6:7], v[6:7], v[136:137], v[212:213]
	v_lshlrev_b32_e32 v214, 16, v178
	v_and_b32_e32 v215, 0xffff0000, v178
	v_lshlrev_b32_e32 v216, 16, v179
	v_and_b32_e32 v217, 0xffff0000, v179
	v_pk_fma_f32 v[0:1], v[0:1], v[130:131], v[214:215]
	v_pk_fma_f32 v[2:3], v[2:3], v[132:133], v[216:217]
	v_mov_b32_e32 v222, 0xb0000
	v_lshl_add_u64 v[192:193], v[162:163], 0, v[222:223]
	global_store_dwordx4 v[192:193], v[4:7], off offset:512
	global_store_dwordx4 v[192:193], v[0:3], off offset:576
	s_mov_b32 s14, 0x30000
	s_mov_b32 s14, 0x80000
	s_mov_b32 s14, 0x90000
	s_mov_b32 s14, 0xa0000
	s_mov_b32 s14, 0xb0000
	s_and_b64 vcc, exec, s[0:1]
	s_mov_b32 s14, s43
	s_cbranch_vccz .LBB0_1418
	s_waitcnt vmcnt(0)
	s_cmpk_gt_u32 s24, 0xff
	s_cbranch_scc1 .LBB0_1425
	s_barrier

.LBB0_1435:
	s_add_u32 s20, s18, 0x100
	s_addc_u32 s21, s19, 0
	s_add_i32 s47, 0, 0x10000
	ds_read_b128 v[130:133], v214
	ds_read_b128 v[134:137], v214 offset:1024
	ds_read_b128 v[138:141], v214 offset:2048
	ds_read_b128 v[142:145], v214 offset:3072
	s_cmp_eq_u32 s46, 40
	s_cselect_b32 s25, s13, s21
	s_cselect_b32 s24, s12, s20
	s_cselect_b32 s23, s15, s45
	s_cselect_b32 s22, s14, s44
	v_lshl_add_u64 v[186:187], s[18:19], 0, v[150:151]
	s_add_i32 m0, s31, 0xc000
	ds_read_b128 v[154:157], v244
	ds_read_b128 v[158:161], v244 offset:1024
	ds_read_b128 v[162:165], v244 offset:2048
	ds_read_b128 v[166:169], v244 offset:3072
	ds_read_b128 v[170:173], v244 offset:4096
	ds_read_b128 v[174:177], v244 offset:5120
	ds_read_b128 v[178:181], v244 offset:6144
	ds_read_b128 v[182:185], v244 offset:7168
	global_load_lds_dwordx4 v[186:187], off
	v_lshl_add_u64 v[186:187], s[18:19], 0, v[152:153]
	s_add_i32 m0, s31, 0xe000
	s_nop 0
	global_load_lds_dwordx4 v[186:187], off
	s_waitcnt lgkmcnt(8)
	s_barrier
	s_waitcnt lgkmcnt(0)
	s_setprio 1
	s_waitcnt lgkmcnt(0)
	v_mfma_f32_16x16x32_bf16 v[126:129], v[130:133], v[154:157], v[126:129]
	v_mfma_f32_16x16x32_bf16 v[122:125], v[138:141], v[154:157], v[122:125]
	v_mfma_f32_16x16x32_bf16 v[114:117], v[130:133], v[162:165], v[114:117]
	v_mfma_f32_16x16x32_bf16 v[106:109], v[138:141], v[162:165], v[106:109]
	v_mfma_f32_16x16x32_bf16 v[98:101], v[130:133], v[170:173], v[98:101]
	v_mfma_f32_16x16x32_bf16 v[90:93], v[138:141], v[170:173], v[90:93]
	v_mfma_f32_16x16x32_bf16 v[82:85], v[130:133], v[178:181], v[82:85]
	v_mfma_f32_16x16x32_bf16 v[74:77], v[138:141], v[178:181], v[74:77]
	v_mfma_f32_16x16x32_bf16 v[126:129], v[134:137], v[158:161], v[126:129]
	v_mfma_f32_16x16x32_bf16 v[122:125], v[142:145], v[158:161], v[122:125]
	v_mfma_f32_16x16x32_bf16 v[114:117], v[134:137], v[166:169], v[114:117]
	v_mfma_f32_16x16x32_bf16 v[106:109], v[142:145], v[166:169], v[106:109]
	v_mfma_f32_16x16x32_bf16 v[98:101], v[134:137], v[174:177], v[98:101]
	v_mfma_f32_16x16x32_bf16 v[90:93], v[142:145], v[174:177], v[90:93]
	v_mfma_f32_16x16x32_bf16 v[82:85], v[134:137], v[182:185], v[82:85]
	v_mfma_f32_16x16x32_bf16 v[74:77], v[142:145], v[182:185], v[74:77]
	s_setprio 0
	s_barrier
	s_add_i32 s48, 0, 0x14000
	s_add_i32 s18, s47, s30
	s_mov_b32 m0, s18
	ds_read_b128 v[186:189], v214 offset:16384
	ds_read_b128 v[190:193], v214 offset:17408
	ds_read_b128 v[198:201], v214 offset:18432
	ds_read_b128 v[202:205], v214 offset:19456
	global_load_lds_dwordx4 v48, s[22:23]
	v_lshl_add_u64 v[208:209], s[22:23], 0, v[146:147]
	s_add_i32 m0, s18, 0x2000
	s_nop 0
	global_load_lds_dwordx4 v[208:209], off
	s_barrier
	s_waitcnt lgkmcnt(0)
	s_setprio 1
	s_waitcnt lgkmcnt(0)
	v_mfma_f32_16x16x32_bf16 v[118:121], v[186:189], v[154:157], v[118:121]
	v_mfma_f32_16x16x32_bf16 v[110:113], v[198:201], v[154:157], v[110:113]
	v_mfma_f32_16x16x32_bf16 v[102:105], v[186:189], v[162:165], v[102:105]
	v_mfma_f32_16x16x32_bf16 v[94:97], v[198:201], v[162:165], v[94:97]
	v_mfma_f32_16x16x32_bf16 v[86:89], v[186:189], v[170:173], v[86:89]
	v_mfma_f32_16x16x32_bf16 v[78:81], v[198:201], v[170:173], v[78:81]
	v_mfma_f32_16x16x32_bf16 v[70:73], v[186:189], v[178:181], v[70:73]
	v_mfma_f32_16x16x32_bf16 v[66:69], v[198:201], v[178:181], v[66:69]
	v_mfma_f32_16x16x32_bf16 v[118:121], v[190:193], v[158:161], v[118:121]
	v_mfma_f32_16x16x32_bf16 v[110:113], v[202:205], v[158:161], v[110:113]
	v_mfma_f32_16x16x32_bf16 v[102:105], v[190:193], v[166:169], v[102:105]
	v_mfma_f32_16x16x32_bf16 v[94:97], v[202:205], v[166:169], v[94:97]
	v_mfma_f32_16x16x32_bf16 v[86:89], v[190:193], v[174:177], v[86:89]
	v_mfma_f32_16x16x32_bf16 v[78:81], v[202:205], v[174:177], v[78:81]
	v_mfma_f32_16x16x32_bf16 v[70:73], v[190:193], v[182:185], v[70:73]
	v_mfma_f32_16x16x32_bf16 v[66:69], v[202:205], v[182:185], v[66:69]
	s_setprio 0
	s_mov_b32 m0, s31
	v_lshl_add_u64 v[210:211], s[24:25], 0, v[48:49]
	s_barrier
	ds_read_b128 v[154:157], v244 offset:16384
	ds_read_b128 v[158:161], v244 offset:17408
	ds_read_b128 v[162:165], v244 offset:18432
	ds_read_b128 v[166:169], v244 offset:19456
	ds_read_b128 v[170:173], v244 offset:20480
	ds_read_b128 v[174:177], v244 offset:21504
	ds_read_b128 v[178:181], v244 offset:22528
	ds_read_b128 v[182:185], v244 offset:23552
	global_load_lds_dwordx4 v[210:211], off
	v_lshl_add_u64 v[212:213], s[24:25], 0, v[146:147]
	s_mov_b32 m0, s34
	s_nop 0
	global_load_lds_dwordx4 v[212:213], off
	s_barrier
	s_waitcnt lgkmcnt(0)
	s_setprio 1
	s_waitcnt lgkmcnt(0)
	v_mfma_f32_16x16x32_bf16 v[62:65], v[130:133], v[154:157], v[62:65]
	v_mfma_f32_16x16x32_bf16 v[58:61], v[138:141], v[154:157], v[58:61]
	v_mfma_f32_16x16x32_bf16 v[50:53], v[130:133], v[162:165], v[50:53]
	v_mfma_f32_16x16x32_bf16 v[40:43], v[138:141], v[162:165], v[40:43]
	v_mfma_f32_16x16x32_bf16 v[32:35], v[130:133], v[170:173], v[32:35]
	v_mfma_f32_16x16x32_bf16 v[24:27], v[138:141], v[170:173], v[24:27]
	v_mfma_f32_16x16x32_bf16 v[16:19], v[130:133], v[178:181], v[16:19]
	v_mfma_f32_16x16x32_bf16 v[8:11], v[138:141], v[178:181], v[8:11]
	v_mfma_f32_16x16x32_bf16 v[62:65], v[134:137], v[158:161], v[62:65]
	v_mfma_f32_16x16x32_bf16 v[58:61], v[142:145], v[158:161], v[58:61]
	v_mfma_f32_16x16x32_bf16 v[50:53], v[134:137], v[166:169], v[50:53]
	v_mfma_f32_16x16x32_bf16 v[40:43], v[142:145], v[166:169], v[40:43]
	v_mfma_f32_16x16x32_bf16 v[32:35], v[134:137], v[174:177], v[32:35]
	v_mfma_f32_16x16x32_bf16 v[24:27], v[142:145], v[174:177], v[24:27]
	v_mfma_f32_16x16x32_bf16 v[16:19], v[134:137], v[182:185], v[16:19]
	v_mfma_f32_16x16x32_bf16 v[8:11], v[142:145], v[182:185], v[8:11]
	s_setprio 0
	s_barrier
	s_add_u32 s18, s22, 0xb0000
	s_addc_u32 s19, s23, 0
	s_add_i32 s47, s48, s30
	s_mov_b32 m0, s47
	s_nop 0
	global_load_lds_dwordx4 v48, s[18:19]
	s_add_i32 m0, s47, 0x2000
	s_nop 0
	global_load_lds_dwordx4 v146, s[18:19]
	s_waitcnt vmcnt(6)
	s_barrier
	s_setprio 1
	v_mfma_f32_16x16x32_bf16 v[54:57], v[186:189], v[154:157], v[54:57]
	v_mfma_f32_16x16x32_bf16 v[44:47], v[198:201], v[154:157], v[44:47]
	v_mfma_f32_16x16x32_bf16 v[36:39], v[186:189], v[162:165], v[36:39]
	v_mfma_f32_16x16x32_bf16 v[28:31], v[198:201], v[162:165], v[28:31]
	v_mfma_f32_16x16x32_bf16 v[20:23], v[186:189], v[170:173], v[20:23]
	v_mfma_f32_16x16x32_bf16 v[12:15], v[198:201], v[170:173], v[12:15]
	v_mfma_f32_16x16x32_bf16 v[4:7], v[186:189], v[178:181], v[4:7]
	v_mfma_f32_16x16x32_bf16 v[0:3], v[198:201], v[178:181], v[0:3]
	v_mfma_f32_16x16x32_bf16 v[54:57], v[190:193], v[158:161], v[54:57]
	v_mfma_f32_16x16x32_bf16 v[44:47], v[202:205], v[158:161], v[44:47]
	v_mfma_f32_16x16x32_bf16 v[36:39], v[190:193], v[166:169], v[36:39]
	v_mfma_f32_16x16x32_bf16 v[28:31], v[202:205], v[166:169], v[28:31]
	v_mfma_f32_16x16x32_bf16 v[20:23], v[190:193], v[174:177], v[20:23]
	v_mfma_f32_16x16x32_bf16 v[12:15], v[202:205], v[174:177], v[12:15]
	v_mfma_f32_16x16x32_bf16 v[4:7], v[190:193], v[182:185], v[4:7]
	v_mfma_f32_16x16x32_bf16 v[0:3], v[202:205], v[182:185], v[0:3]
	s_setprio 0
	s_add_i32 s47, 0, 0x18000
	s_barrier
	ds_read_b128 v[130:133], v214 offset:32768
	ds_read_b128 v[134:137], v214 offset:33792
	ds_read_b128 v[138:141], v214 offset:34816
	ds_read_b128 v[142:145], v214 offset:35840
	s_add_u32 s18, s24, 0xb0000
	s_addc_u32 s19, s25, 0
	s_mov_b32 m0, s35
	ds_read_b128 v[154:157], v244 offset:32768
	ds_read_b128 v[158:161], v244 offset:33792
	ds_read_b128 v[162:165], v244 offset:34816
	ds_read_b128 v[166:169], v244 offset:35840
	ds_read_b128 v[170:173], v244 offset:36864
	ds_read_b128 v[174:177], v244 offset:37888
	ds_read_b128 v[178:181], v244 offset:38912
	ds_read_b128 v[182:185], v244 offset:39936
	global_load_lds_dwordx4 v48, s[18:19]
	s_mov_b32 m0, s36
	s_nop 0
	global_load_lds_dwordx4 v146, s[18:19]
	s_waitcnt lgkmcnt(8)
	s_barrier
	s_waitcnt lgkmcnt(0)
	s_setprio 1
	s_waitcnt lgkmcnt(0)
	v_mfma_f32_16x16x32_bf16 v[126:129], v[130:133], v[154:157], v[126:129]
	v_mfma_f32_16x16x32_bf16 v[122:125], v[138:141], v[154:157], v[122:125]
	v_mfma_f32_16x16x32_bf16 v[114:117], v[130:133], v[162:165], v[114:117]
	v_mfma_f32_16x16x32_bf16 v[106:109], v[138:141], v[162:165], v[106:109]
	v_mfma_f32_16x16x32_bf16 v[98:101], v[130:133], v[170:173], v[98:101]
	v_mfma_f32_16x16x32_bf16 v[90:93], v[138:141], v[170:173], v[90:93]
	v_mfma_f32_16x16x32_bf16 v[82:85], v[130:133], v[178:181], v[82:85]
	v_mfma_f32_16x16x32_bf16 v[74:77], v[138:141], v[178:181], v[74:77]
	v_mfma_f32_16x16x32_bf16 v[126:129], v[134:137], v[158:161], v[126:129]
	v_mfma_f32_16x16x32_bf16 v[122:125], v[142:145], v[158:161], v[122:125]
	v_mfma_f32_16x16x32_bf16 v[114:117], v[134:137], v[166:169], v[114:117]
	v_mfma_f32_16x16x32_bf16 v[106:109], v[142:145], v[166:169], v[106:109]
	v_mfma_f32_16x16x32_bf16 v[98:101], v[134:137], v[174:177], v[98:101]
	v_mfma_f32_16x16x32_bf16 v[90:93], v[142:145], v[174:177], v[90:93]
	v_mfma_f32_16x16x32_bf16 v[82:85], v[134:137], v[182:185], v[82:85]
	v_mfma_f32_16x16x32_bf16 v[74:77], v[142:145], v[182:185], v[74:77]
	s_setprio 0
	s_barrier
	s_add_i32 s24, 0, 0x1c000
	s_add_i32 s18, s47, s30
	s_add_u32 s52, s22, s66
	s_addc_u32 s53, s23, s67
	s_mov_b32 m0, s18
	ds_read_b128 v[186:189], v214 offset:49152
	ds_read_b128 v[190:193], v214 offset:50176
	ds_read_b128 v[198:201], v214 offset:51200
	ds_read_b128 v[202:205], v214 offset:52224
	global_load_lds_dwordx4 v48, s[52:53]
	s_add_i32 m0, s18, 0x2000
	s_nop 0
	global_load_lds_dwordx4 v146, s[52:53]
	s_barrier
	s_waitcnt lgkmcnt(0)
	s_setprio 1
	s_waitcnt lgkmcnt(0)
	v_mfma_f32_16x16x32_bf16 v[118:121], v[186:189], v[154:157], v[118:121]
	v_mfma_f32_16x16x32_bf16 v[110:113], v[198:201], v[154:157], v[110:113]
	v_mfma_f32_16x16x32_bf16 v[102:105], v[186:189], v[162:165], v[102:105]
	v_mfma_f32_16x16x32_bf16 v[94:97], v[198:201], v[162:165], v[94:97]
	v_mfma_f32_16x16x32_bf16 v[86:89], v[186:189], v[170:173], v[86:89]
	v_mfma_f32_16x16x32_bf16 v[78:81], v[198:201], v[170:173], v[78:81]
	v_mfma_f32_16x16x32_bf16 v[70:73], v[186:189], v[178:181], v[70:73]
	v_mfma_f32_16x16x32_bf16 v[66:69], v[198:201], v[178:181], v[66:69]
	v_mfma_f32_16x16x32_bf16 v[118:121], v[190:193], v[158:161], v[118:121]
	v_mfma_f32_16x16x32_bf16 v[110:113], v[202:205], v[158:161], v[110:113]
	v_mfma_f32_16x16x32_bf16 v[102:105], v[190:193], v[166:169], v[102:105]
	v_mfma_f32_16x16x32_bf16 v[94:97], v[202:205], v[166:169], v[94:97]
	v_mfma_f32_16x16x32_bf16 v[86:89], v[190:193], v[174:177], v[86:89]
	v_mfma_f32_16x16x32_bf16 v[78:81], v[202:205], v[174:177], v[78:81]
	v_mfma_f32_16x16x32_bf16 v[70:73], v[190:193], v[182:185], v[70:73]
	v_mfma_f32_16x16x32_bf16 v[66:69], v[202:205], v[182:185], v[66:69]
	s_setprio 0
	s_mov_b32 m0, s39
	v_lshl_add_u64 v[206:207], v[210:211], 0, s[66:67]
	s_barrier
	ds_read_b128 v[154:157], v244 offset:49152
	ds_read_b128 v[158:161], v244 offset:50176
	ds_read_b128 v[162:165], v244 offset:51200
	ds_read_b128 v[166:169], v244 offset:52224
	ds_read_b128 v[170:173], v244 offset:53248
	ds_read_b128 v[174:177], v244 offset:54272
	ds_read_b128 v[178:181], v244 offset:55296
	ds_read_b128 v[182:185], v244 offset:56320
	global_load_lds_dwordx4 v[206:207], off
	v_lshl_add_u64 v[206:207], v[212:213], 0, s[66:67]
	s_mov_b32 m0, s40
	s_nop 0
	global_load_lds_dwordx4 v[206:207], off
	s_barrier
	s_waitcnt lgkmcnt(0)
	s_setprio 1
	s_waitcnt lgkmcnt(0)
	v_mfma_f32_16x16x32_bf16 v[62:65], v[130:133], v[154:157], v[62:65]
	v_mfma_f32_16x16x32_bf16 v[58:61], v[138:141], v[154:157], v[58:61]
	v_mfma_f32_16x16x32_bf16 v[50:53], v[130:133], v[162:165], v[50:53]
	v_mfma_f32_16x16x32_bf16 v[40:43], v[138:141], v[162:165], v[40:43]
	v_mfma_f32_16x16x32_bf16 v[32:35], v[130:133], v[170:173], v[32:35]
	v_mfma_f32_16x16x32_bf16 v[24:27], v[138:141], v[170:173], v[24:27]
	v_mfma_f32_16x16x32_bf16 v[16:19], v[130:133], v[178:181], v[16:19]
	v_mfma_f32_16x16x32_bf16 v[8:11], v[138:141], v[178:181], v[8:11]
	v_mfma_f32_16x16x32_bf16 v[62:65], v[134:137], v[158:161], v[62:65]
	v_mfma_f32_16x16x32_bf16 v[58:61], v[142:145], v[158:161], v[58:61]
	v_mfma_f32_16x16x32_bf16 v[50:53], v[134:137], v[166:169], v[50:53]
	v_mfma_f32_16x16x32_bf16 v[40:43], v[142:145], v[166:169], v[40:43]
	v_mfma_f32_16x16x32_bf16 v[32:35], v[134:137], v[174:177], v[32:35]
	v_mfma_f32_16x16x32_bf16 v[24:27], v[142:145], v[174:177], v[24:27]
	v_mfma_f32_16x16x32_bf16 v[16:19], v[134:137], v[182:185], v[16:19]
	v_mfma_f32_16x16x32_bf16 v[8:11], v[142:145], v[182:185], v[8:11]
	s_setprio 0
	s_barrier
	s_add_u32 s18, s22, 0xb0080
	s_addc_u32 s19, s23, 0
	s_add_i32 s22, s24, s30
	s_mov_b32 m0, s22
	s_nop 0
	global_load_lds_dwordx4 v48, s[18:19]
	s_add_i32 m0, s22, 0x2000
	s_nop 0
	global_load_lds_dwordx4 v146, s[18:19]
	s_waitcnt vmcnt(6)
	s_barrier
	s_setprio 1
	v_mfma_f32_16x16x32_bf16 v[54:57], v[186:189], v[154:157], v[54:57]
	v_mfma_f32_16x16x32_bf16 v[44:47], v[198:201], v[154:157], v[44:47]
	v_mfma_f32_16x16x32_bf16 v[36:39], v[186:189], v[162:165], v[36:39]
	v_mfma_f32_16x16x32_bf16 v[28:31], v[198:201], v[162:165], v[28:31]
	v_mfma_f32_16x16x32_bf16 v[20:23], v[186:189], v[170:173], v[20:23]
	v_mfma_f32_16x16x32_bf16 v[12:15], v[198:201], v[170:173], v[12:15]
	v_mfma_f32_16x16x32_bf16 v[4:7], v[186:189], v[178:181], v[4:7]
	v_mfma_f32_16x16x32_bf16 v[0:3], v[198:201], v[178:181], v[0:3]
	v_mfma_f32_16x16x32_bf16 v[54:57], v[190:193], v[158:161], v[54:57]
	v_mfma_f32_16x16x32_bf16 v[44:47], v[202:205], v[158:161], v[44:47]
	v_mfma_f32_16x16x32_bf16 v[36:39], v[190:193], v[166:169], v[36:39]
	v_mfma_f32_16x16x32_bf16 v[28:31], v[202:205], v[166:169], v[28:31]
	v_mfma_f32_16x16x32_bf16 v[20:23], v[190:193], v[174:177], v[20:23]
	v_mfma_f32_16x16x32_bf16 v[12:15], v[202:205], v[174:177], v[12:15]
	v_mfma_f32_16x16x32_bf16 v[4:7], v[190:193], v[182:185], v[4:7]
	v_mfma_f32_16x16x32_bf16 v[0:3], v[202:205], v[182:185], v[0:3]
	s_setprio 0
	s_add_i32 s46, s46, 2
	s_add_u32 s44, s44, 0x100
	s_addc_u32 s45, s45, 0
	s_cmp_gt_u32 s46, 41
	s_mov_b64 s[18:19], s[20:21]
	s_barrier
	s_cbranch_scc0 .LBB0_1435
	s_mul_hi_i32 s18, s16, 0x38e38e39
	s_lshr_b32 s19, s18, 31
	s_ashr_i32 s18, s18, 1
	s_add_i32 s18, s18, s19
	s_mul_i32 s19, s18, -9
	v_lshl_or_b32 v154, s17, 8, v243
	s_sub_i32 s17, 0, s16
	s_cmp_lg_u32 s19, s17
	s_cselect_b32 s17, s18, 32
	s_mul_hi_i32 s19, s17, 0x6000
	s_mulk_i32 s17, 0x6000
	s_add_u32 s18, s37, s17
	s_addc_u32 s19, s38, s19
	s_ashr_i32 s17, s16, 31
	s_lshl_b64 s[16:17], s[16:17], 18
	v_ashrrev_i32_e32 v155, 31, v154
	v_lshl_add_u64 v[156:157], s[16:17], 0, v[148:149]
	v_lshl_add_u64 v[130:131], v[154:155], 2, s[18:19]
	v_lshl_add_u64 v[154:155], v[156:157], 0, v[154:155]
	v_lshlrev_b64 v[184:185], 1, v[154:155]
	v_lshl_add_u64 v[154:155], s[10:11], 0, v[184:185]
	global_load_dwordx4 v[142:145], v[130:131], off
	global_load_dwordx4 v[138:141], v[130:131], off offset:64
	global_load_dwordx4 v[134:137], v[130:131], off offset:512
	s_nop 0
	global_load_dwordx4 v[130:133], v[130:131], off offset:576
	s_nop 0
	s_mov_b32 s16, 0x40000
	s_nop 0
	s_mov_b32 s17, 0x48000
	s_nop 0
	s_mov_b32 s18, 0x50000
	s_nop 0
	s_mov_b32 s19, 0x58000
	s_nop 0
	v_lshl_add_u64 v[184:185], s[6:7], 0, v[184:185]
	s_nop 0
	s_mov_b64 s[20:21], s[14:15]
	s_nop 0
	v_and_b32_e32 v210, 16, v224
	v_lshrrev_b32_e32 v211, 1, v210
	v_add_u32_e32 v210, v210, v211
	v_mov_b32_e32 v211, 0
	v_mov_b32_e32 v213, 0
	v_lshl_add_u64 v[214:215], v[154:155], 0, v[210:211]
	v_lshl_add_u64 v[216:217], v[184:185], 0, v[210:211]
	v_mov_b32_e32 v212, 0x0
	v_lshl_add_u64 v[218:219], v[214:215], 0, v[212:213]
	global_load_dwordx4 v[164:167], v[218:219], off
	global_load_dwordx4 v[168:171], v[218:219], off offset:256
	v_mov_b32_e32 v212, 0x8000
	v_lshl_add_u64 v[218:219], v[214:215], 0, v[212:213]
	global_load_dwordx4 v[172:175], v[218:219], off
	global_load_dwordx4 v[176:179], v[218:219], off offset:256
	v_mov_b32_e32 v212, 0x10000
	v_lshl_add_u64 v[218:219], v[214:215], 0, v[212:213]
	global_load_dwordx4 v[180:183], v[218:219], off
	global_load_dwordx4 v[198:201], v[218:219], off offset:256
	v_mov_b32_e32 v212, 0x18000
	v_lshl_add_u64 v[218:219], v[214:215], 0, v[212:213]
	global_load_dwordx4 v[202:205], v[218:219], off
	global_load_dwordx4 v[206:209], v[218:219], off offset:256
	s_waitcnt vmcnt(7)
	v_permlane16_swap_b32 v164, v166
	v_permlane16_swap_b32 v165, v167
	s_nop 1
	v_lshlrev_b32_e32 v186, 16, v164
	v_and_b32_e32 v187, 0xffff0000, v164
	v_lshlrev_b32_e32 v188, 16, v165
	v_and_b32_e32 v189, 0xffff0000, v165
	v_pk_fma_f32 v[126:127], v[126:127], v[142:143], v[186:187]
	v_pk_fma_f32 v[128:129], v[128:129], v[144:145], v[188:189]
	v_lshlrev_b32_e32 v190, 16, v166
	v_and_b32_e32 v191, 0xffff0000, v166
	v_lshlrev_b32_e32 v192, 16, v167
	v_and_b32_e32 v193, 0xffff0000, v167
	v_pk_fma_f32 v[122:123], v[122:123], v[138:139], v[190:191]
	v_pk_fma_f32 v[124:125], v[124:125], v[140:141], v[192:193]
	v_cvt_pk_bf16_f32 v126, v126, v127
	v_cvt_pk_bf16_f32 v127, v128, v129
	v_cvt_pk_bf16_f32 v128, v122, v123
	v_cvt_pk_bf16_f32 v129, v124, v125
	s_nop 1
	v_permlane16_swap_b32 v126, v128
	v_permlane16_swap_b32 v127, v129
	v_mov_b32_e32 v212, 0x0
	v_lshl_add_u64 v[220:221], v[216:217], 0, v[212:213]
	global_store_dwordx4 v[220:221], v[126:129], off
	v_mov_b32_e32 v212, 0x40000
	v_lshl_add_u64 v[218:219], v[214:215], 0, v[212:213]
	global_load_dwordx4 v[164:167], v[218:219], off
	s_waitcnt vmcnt(8)
	v_permlane16_swap_b32 v168, v170
	v_permlane16_swap_b32 v169, v171
	s_nop 1
	v_lshlrev_b32_e32 v186, 16, v168
	v_and_b32_e32 v187, 0xffff0000, v168
	v_lshlrev_b32_e32 v188, 16, v169
	v_and_b32_e32 v189, 0xffff0000, v169
	v_pk_fma_f32 v[118:119], v[118:119], v[134:135], v[186:187]
	v_pk_fma_f32 v[120:121], v[120:121], v[136:137], v[188:189]
	v_lshlrev_b32_e32 v190, 16, v170
	v_and_b32_e32 v191, 0xffff0000, v170
	v_lshlrev_b32_e32 v192, 16, v171
	v_and_b32_e32 v193, 0xffff0000, v171
	v_pk_fma_f32 v[110:111], v[110:111], v[130:131], v[190:191]
	v_pk_fma_f32 v[112:113], v[112:113], v[132:133], v[192:193]
	v_cvt_pk_bf16_f32 v118, v118, v119
	v_cvt_pk_bf16_f32 v119, v120, v121
	v_cvt_pk_bf16_f32 v120, v110, v111
	v_cvt_pk_bf16_f32 v121, v112, v113
	s_nop 1
	v_permlane16_swap_b32 v118, v120
	v_permlane16_swap_b32 v119, v121
	v_mov_b32_e32 v212, 0x0
	v_lshl_add_u64 v[220:221], v[216:217], 0, v[212:213]
	global_store_dwordx4 v[220:221], v[118:121], off offset:256
	global_load_dwordx4 v[168:171], v[218:219], off offset:256
	s_waitcnt vmcnt(9)
	v_permlane16_swap_b32 v172, v174
	v_permlane16_swap_b32 v173, v175
	s_nop 1
	v_lshlrev_b32_e32 v186, 16, v172
	v_and_b32_e32 v187, 0xffff0000, v172
	v_lshlrev_b32_e32 v188, 16, v173
	v_and_b32_e32 v189, 0xffff0000, v173
	v_pk_fma_f32 v[114:115], v[114:115], v[142:143], v[186:187]
	v_pk_fma_f32 v[116:117], v[116:117], v[144:145], v[188:189]
	v_lshlrev_b32_e32 v190, 16, v174
	v_and_b32_e32 v191, 0xffff0000, v174
	v_lshlrev_b32_e32 v192, 16, v175
	v_and_b32_e32 v193, 0xffff0000, v175
	v_pk_fma_f32 v[106:107], v[106:107], v[138:139], v[190:191]
	v_pk_fma_f32 v[108:109], v[108:109], v[140:141], v[192:193]
	v_cvt_pk_bf16_f32 v114, v114, v115
	v_cvt_pk_bf16_f32 v115, v116, v117
	v_cvt_pk_bf16_f32 v116, v106, v107
	v_cvt_pk_bf16_f32 v117, v108, v109
	s_nop 1
	v_permlane16_swap_b32 v114, v116
	v_permlane16_swap_b32 v115, v117
	v_mov_b32_e32 v212, 0x8000
	v_lshl_add_u64 v[220:221], v[216:217], 0, v[212:213]
	global_store_dwordx4 v[220:221], v[114:117], off
	v_mov_b32_e32 v212, 0x48000
	v_lshl_add_u64 v[218:219], v[214:215], 0, v[212:213]
	global_load_dwordx4 v[172:175], v[218:219], off
	s_waitcnt vmcnt(10)
	v_permlane16_swap_b32 v176, v178
	v_permlane16_swap_b32 v177, v179
	s_nop 1
	v_lshlrev_b32_e32 v186, 16, v176
	v_and_b32_e32 v187, 0xffff0000, v176
	v_lshlrev_b32_e32 v188, 16, v177
	v_and_b32_e32 v189, 0xffff0000, v177
	v_pk_fma_f32 v[102:103], v[102:103], v[134:135], v[186:187]
	v_pk_fma_f32 v[104:105], v[104:105], v[136:137], v[188:189]
	v_lshlrev_b32_e32 v190, 16, v178
	v_and_b32_e32 v191, 0xffff0000, v178
	v_lshlrev_b32_e32 v192, 16, v179
	v_and_b32_e32 v193, 0xffff0000, v179
	v_pk_fma_f32 v[94:95], v[94:95], v[130:131], v[190:191]
	v_pk_fma_f32 v[96:97], v[96:97], v[132:133], v[192:193]
	v_cvt_pk_bf16_f32 v102, v102, v103
	v_cvt_pk_bf16_f32 v103, v104, v105
	v_cvt_pk_bf16_f32 v104, v94, v95
	v_cvt_pk_bf16_f32 v105, v96, v97
	s_nop 1
	v_permlane16_swap_b32 v102, v104
	v_permlane16_swap_b32 v103, v105
	v_mov_b32_e32 v212, 0x8000
	v_lshl_add_u64 v[220:221], v[216:217], 0, v[212:213]
	global_store_dwordx4 v[220:221], v[102:105], off offset:256
	global_load_dwordx4 v[176:179], v[218:219], off offset:256
	s_waitcnt vmcnt(11)
	v_permlane16_swap_b32 v180, v182
	v_permlane16_swap_b32 v181, v183
	s_nop 1
	v_lshlrev_b32_e32 v186, 16, v180
	v_and_b32_e32 v187, 0xffff0000, v180
	v_lshlrev_b32_e32 v188, 16, v181
	v_and_b32_e32 v189, 0xffff0000, v181
	v_pk_fma_f32 v[98:99], v[98:99], v[142:143], v[186:187]
	v_pk_fma_f32 v[100:101], v[100:101], v[144:145], v[188:189]
	v_lshlrev_b32_e32 v190, 16, v182
	v_and_b32_e32 v191, 0xffff0000, v182
	v_lshlrev_b32_e32 v192, 16, v183
	v_and_b32_e32 v193, 0xffff0000, v183
	v_pk_fma_f32 v[90:91], v[90:91], v[138:139], v[190:191]
	v_pk_fma_f32 v[92:93], v[92:93], v[140:141], v[192:193]
	v_cvt_pk_bf16_f32 v98, v98, v99
	v_cvt_pk_bf16_f32 v99, v100, v101
	v_cvt_pk_bf16_f32 v100, v90, v91
	v_cvt_pk_bf16_f32 v101, v92, v93
	s_nop 1
	v_permlane16_swap_b32 v98, v100
	v_permlane16_swap_b32 v99, v101
	v_mov_b32_e32 v212, 0x10000
	v_lshl_add_u64 v[220:221], v[216:217], 0, v[212:213]
	global_store_dwordx4 v[220:221], v[98:101], off
	v_mov_b32_e32 v212, 0x50000
	v_lshl_add_u64 v[218:219], v[214:215], 0, v[212:213]
	global_load_dwordx4 v[180:183], v[218:219], off
	s_waitcnt vmcnt(12)
	v_permlane16_swap_b32 v198, v200
	v_permlane16_swap_b32 v199, v201
	s_nop 1
	v_lshlrev_b32_e32 v186, 16, v198
	v_and_b32_e32 v187, 0xffff0000, v198
	v_lshlrev_b32_e32 v188, 16, v199
	v_and_b32_e32 v189, 0xffff0000, v199
	v_pk_fma_f32 v[86:87], v[86:87], v[134:135], v[186:187]
	v_pk_fma_f32 v[88:89], v[88:89], v[136:137], v[188:189]
	v_lshlrev_b32_e32 v190, 16, v200
	v_and_b32_e32 v191, 0xffff0000, v200
	v_lshlrev_b32_e32 v192, 16, v201
	v_and_b32_e32 v193, 0xffff0000, v201
	v_pk_fma_f32 v[78:79], v[78:79], v[130:131], v[190:191]
	v_pk_fma_f32 v[80:81], v[80:81], v[132:133], v[192:193]
	v_cvt_pk_bf16_f32 v86, v86, v87
	v_cvt_pk_bf16_f32 v87, v88, v89
	v_cvt_pk_bf16_f32 v88, v78, v79
	v_cvt_pk_bf16_f32 v89, v80, v81
	s_nop 1
	v_permlane16_swap_b32 v86, v88
	v_permlane16_swap_b32 v87, v89
	v_mov_b32_e32 v212, 0x10000
	v_lshl_add_u64 v[220:221], v[216:217], 0, v[212:213]
	global_store_dwordx4 v[220:221], v[86:89], off offset:256
	global_load_dwordx4 v[198:201], v[218:219], off offset:256
	s_waitcnt vmcnt(13)
	v_permlane16_swap_b32 v202, v204
	v_permlane16_swap_b32 v203, v205
	s_nop 1
	v_lshlrev_b32_e32 v186, 16, v202
	v_and_b32_e32 v187, 0xffff0000, v202
	v_lshlrev_b32_e32 v188, 16, v203
	v_and_b32_e32 v189, 0xffff0000, v203
	v_pk_fma_f32 v[82:83], v[82:83], v[142:143], v[186:187]
	v_pk_fma_f32 v[84:85], v[84:85], v[144:145], v[188:189]
	v_lshlrev_b32_e32 v190, 16, v204
	v_and_b32_e32 v191, 0xffff0000, v204
	v_lshlrev_b32_e32 v192, 16, v205
	v_and_b32_e32 v193, 0xffff0000, v205
	v_pk_fma_f32 v[74:75], v[74:75], v[138:139], v[190:191]
	v_pk_fma_f32 v[76:77], v[76:77], v[140:141], v[192:193]
	v_cvt_pk_bf16_f32 v82, v82, v83
	v_cvt_pk_bf16_f32 v83, v84, v85
	v_cvt_pk_bf16_f32 v84, v74, v75
	v_cvt_pk_bf16_f32 v85, v76, v77
	s_nop 1
	v_permlane16_swap_b32 v82, v84
	v_permlane16_swap_b32 v83, v85
	v_mov_b32_e32 v212, 0x18000
	v_lshl_add_u64 v[220:221], v[216:217], 0, v[212:213]
	global_store_dwordx4 v[220:221], v[82:85], off
	v_mov_b32_e32 v212, 0x58000
	v_lshl_add_u64 v[218:219], v[214:215], 0, v[212:213]
	global_load_dwordx4 v[202:205], v[218:219], off
	s_waitcnt vmcnt(14)
	v_permlane16_swap_b32 v206, v208
	v_permlane16_swap_b32 v207, v209
	s_nop 1
	v_lshlrev_b32_e32 v186, 16, v206
	v_and_b32_e32 v187, 0xffff0000, v206
	v_lshlrev_b32_e32 v188, 16, v207
	v_and_b32_e32 v189, 0xffff0000, v207
	v_pk_fma_f32 v[70:71], v[70:71], v[134:135], v[186:187]
	v_pk_fma_f32 v[72:73], v[72:73], v[136:137], v[188:189]
	v_lshlrev_b32_e32 v190, 16, v208
	v_and_b32_e32 v191, 0xffff0000, v208
	v_lshlrev_b32_e32 v192, 16, v209
	v_and_b32_e32 v193, 0xffff0000, v209
	v_pk_fma_f32 v[66:67], v[66:67], v[130:131], v[190:191]
	v_pk_fma_f32 v[68:69], v[68:69], v[132:133], v[192:193]
	v_cvt_pk_bf16_f32 v70, v70, v71
	v_cvt_pk_bf16_f32 v71, v72, v73
	v_cvt_pk_bf16_f32 v72, v66, v67
	v_cvt_pk_bf16_f32 v73, v68, v69
	s_nop 1
	v_permlane16_swap_b32 v70, v72
	v_permlane16_swap_b32 v71, v73
	v_mov_b32_e32 v212, 0x18000
	v_lshl_add_u64 v[220:221], v[216:217], 0, v[212:213]
	global_store_dwordx4 v[220:221], v[70:73], off offset:256
	global_load_dwordx4 v[206:209], v[218:219], off offset:256
	s_waitcnt vmcnt(14)
	v_permlane16_swap_b32 v164, v166
	v_permlane16_swap_b32 v165, v167
	s_nop 1
	v_lshlrev_b32_e32 v186, 16, v164
	v_and_b32_e32 v187, 0xffff0000, v164
	v_lshlrev_b32_e32 v188, 16, v165
	v_and_b32_e32 v189, 0xffff0000, v165
	v_pk_fma_f32 v[62:63], v[62:63], v[142:143], v[186:187]
	v_pk_fma_f32 v[64:65], v[64:65], v[144:145], v[188:189]
	v_lshlrev_b32_e32 v190, 16, v166
	v_and_b32_e32 v191, 0xffff0000, v166
	v_lshlrev_b32_e32 v192, 16, v167
	v_and_b32_e32 v193, 0xffff0000, v167
	v_pk_fma_f32 v[58:59], v[58:59], v[138:139], v[190:191]
	v_pk_fma_f32 v[60:61], v[60:61], v[140:141], v[192:193]
	v_cvt_pk_bf16_f32 v62, v62, v63
	v_cvt_pk_bf16_f32 v63, v64, v65
	v_cvt_pk_bf16_f32 v64, v58, v59
	v_cvt_pk_bf16_f32 v65, v60, v61
	s_nop 1
	v_permlane16_swap_b32 v62, v64
	v_permlane16_swap_b32 v63, v65
	v_mov_b32_e32 v212, 0x40000
	v_lshl_add_u64 v[220:221], v[216:217], 0, v[212:213]
	global_store_dwordx4 v[220:221], v[62:65], off
	s_waitcnt vmcnt(13)
	v_permlane16_swap_b32 v168, v170
	v_permlane16_swap_b32 v169, v171
	s_nop 1
	v_lshlrev_b32_e32 v186, 16, v168
	v_and_b32_e32 v187, 0xffff0000, v168
	v_lshlrev_b32_e32 v188, 16, v169
	v_and_b32_e32 v189, 0xffff0000, v169
	v_pk_fma_f32 v[54:55], v[54:55], v[134:135], v[186:187]
	v_pk_fma_f32 v[56:57], v[56:57], v[136:137], v[188:189]
	v_lshlrev_b32_e32 v190, 16, v170
	v_and_b32_e32 v191, 0xffff0000, v170
	v_lshlrev_b32_e32 v192, 16, v171
	v_and_b32_e32 v193, 0xffff0000, v171
	v_pk_fma_f32 v[44:45], v[44:45], v[130:131], v[190:191]
	v_pk_fma_f32 v[46:47], v[46:47], v[132:133], v[192:193]
	v_cvt_pk_bf16_f32 v54, v54, v55
	v_cvt_pk_bf16_f32 v55, v56, v57
	v_cvt_pk_bf16_f32 v56, v44, v45
	v_cvt_pk_bf16_f32 v57, v46, v47
	s_nop 1
	v_permlane16_swap_b32 v54, v56
	v_permlane16_swap_b32 v55, v57
	v_mov_b32_e32 v212, 0x40000
	v_lshl_add_u64 v[220:221], v[216:217], 0, v[212:213]
	global_store_dwordx4 v[220:221], v[54:57], off offset:256
	s_waitcnt vmcnt(12)
	v_permlane16_swap_b32 v172, v174
	v_permlane16_swap_b32 v173, v175
	s_nop 1
	v_lshlrev_b32_e32 v186, 16, v172
	v_and_b32_e32 v187, 0xffff0000, v172
	v_lshlrev_b32_e32 v188, 16, v173
	v_and_b32_e32 v189, 0xffff0000, v173
	v_pk_fma_f32 v[50:51], v[50:51], v[142:143], v[186:187]
	v_pk_fma_f32 v[52:53], v[52:53], v[144:145], v[188:189]
	v_lshlrev_b32_e32 v190, 16, v174
	v_and_b32_e32 v191, 0xffff0000, v174
	v_lshlrev_b32_e32 v192, 16, v175
	v_and_b32_e32 v193, 0xffff0000, v175
	v_pk_fma_f32 v[40:41], v[40:41], v[138:139], v[190:191]
	v_pk_fma_f32 v[42:43], v[42:43], v[140:141], v[192:193]
	v_cvt_pk_bf16_f32 v50, v50, v51
	v_cvt_pk_bf16_f32 v51, v52, v53
	v_cvt_pk_bf16_f32 v52, v40, v41
	v_cvt_pk_bf16_f32 v53, v42, v43
	s_nop 1
	v_permlane16_swap_b32 v50, v52
	v_permlane16_swap_b32 v51, v53
	v_mov_b32_e32 v212, 0x48000
	v_lshl_add_u64 v[220:221], v[216:217], 0, v[212:213]
	global_store_dwordx4 v[220:221], v[50:53], off
	s_waitcnt vmcnt(11)
	v_permlane16_swap_b32 v176, v178
	v_permlane16_swap_b32 v177, v179
	s_nop 1
	v_lshlrev_b32_e32 v186, 16, v176
	v_and_b32_e32 v187, 0xffff0000, v176
	v_lshlrev_b32_e32 v188, 16, v177
	v_and_b32_e32 v189, 0xffff0000, v177
	v_pk_fma_f32 v[36:37], v[36:37], v[134:135], v[186:187]
	v_pk_fma_f32 v[38:39], v[38:39], v[136:137], v[188:189]
	v_lshlrev_b32_e32 v190, 16, v178
	v_and_b32_e32 v191, 0xffff0000, v178
	v_lshlrev_b32_e32 v192, 16, v179
	v_and_b32_e32 v193, 0xffff0000, v179
	v_pk_fma_f32 v[28:29], v[28:29], v[130:131], v[190:191]
	v_pk_fma_f32 v[30:31], v[30:31], v[132:133], v[192:193]
	v_cvt_pk_bf16_f32 v36, v36, v37
	v_cvt_pk_bf16_f32 v37, v38, v39
	v_cvt_pk_bf16_f32 v38, v28, v29
	v_cvt_pk_bf16_f32 v39, v30, v31
	s_nop 1
	v_permlane16_swap_b32 v36, v38
	v_permlane16_swap_b32 v37, v39
	v_mov_b32_e32 v212, 0x48000
	v_lshl_add_u64 v[220:221], v[216:217], 0, v[212:213]
	global_store_dwordx4 v[220:221], v[36:39], off offset:256
	s_waitcnt vmcnt(10)
	v_permlane16_swap_b32 v180, v182
	v_permlane16_swap_b32 v181, v183
	s_nop 1
	v_lshlrev_b32_e32 v186, 16, v180
	v_and_b32_e32 v187, 0xffff0000, v180
	v_lshlrev_b32_e32 v188, 16, v181
	v_and_b32_e32 v189, 0xffff0000, v181
	v_pk_fma_f32 v[32:33], v[32:33], v[142:143], v[186:187]
	v_pk_fma_f32 v[34:35], v[34:35], v[144:145], v[188:189]
	v_lshlrev_b32_e32 v190, 16, v182
	v_and_b32_e32 v191, 0xffff0000, v182
	v_lshlrev_b32_e32 v192, 16, v183
	v_and_b32_e32 v193, 0xffff0000, v183
	v_pk_fma_f32 v[24:25], v[24:25], v[138:139], v[190:191]
	v_pk_fma_f32 v[26:27], v[26:27], v[140:141], v[192:193]
	v_cvt_pk_bf16_f32 v32, v32, v33
	v_cvt_pk_bf16_f32 v33, v34, v35
	v_cvt_pk_bf16_f32 v34, v24, v25
	v_cvt_pk_bf16_f32 v35, v26, v27
	s_nop 1
	v_permlane16_swap_b32 v32, v34
	v_permlane16_swap_b32 v33, v35
	v_mov_b32_e32 v212, 0x50000
	v_lshl_add_u64 v[220:221], v[216:217], 0, v[212:213]
	global_store_dwordx4 v[220:221], v[32:35], off
	s_waitcnt vmcnt(9)
	v_permlane16_swap_b32 v198, v200
	v_permlane16_swap_b32 v199, v201
	s_nop 1
	v_lshlrev_b32_e32 v186, 16, v198
	v_and_b32_e32 v187, 0xffff0000, v198
	v_lshlrev_b32_e32 v188, 16, v199
	v_and_b32_e32 v189, 0xffff0000, v199
	v_pk_fma_f32 v[20:21], v[20:21], v[134:135], v[186:187]
	v_pk_fma_f32 v[22:23], v[22:23], v[136:137], v[188:189]
	v_lshlrev_b32_e32 v190, 16, v200
	v_and_b32_e32 v191, 0xffff0000, v200
	v_lshlrev_b32_e32 v192, 16, v201
	v_and_b32_e32 v193, 0xffff0000, v201
	v_pk_fma_f32 v[12:13], v[12:13], v[130:131], v[190:191]
	v_pk_fma_f32 v[14:15], v[14:15], v[132:133], v[192:193]
	v_cvt_pk_bf16_f32 v20, v20, v21
	v_cvt_pk_bf16_f32 v21, v22, v23
	v_cvt_pk_bf16_f32 v22, v12, v13
	v_cvt_pk_bf16_f32 v23, v14, v15
	s_nop 1
	v_permlane16_swap_b32 v20, v22
	v_permlane16_swap_b32 v21, v23
	v_mov_b32_e32 v212, 0x50000
	v_lshl_add_u64 v[220:221], v[216:217], 0, v[212:213]
	global_store_dwordx4 v[220:221], v[20:23], off offset:256
	s_waitcnt vmcnt(8)
	v_permlane16_swap_b32 v202, v204
	v_permlane16_swap_b32 v203, v205
	s_nop 1
	v_lshlrev_b32_e32 v186, 16, v202
	v_and_b32_e32 v187, 0xffff0000, v202
	v_lshlrev_b32_e32 v188, 16, v203
	v_and_b32_e32 v189, 0xffff0000, v203
	v_pk_fma_f32 v[16:17], v[16:17], v[142:143], v[186:187]
	v_pk_fma_f32 v[18:19], v[18:19], v[144:145], v[188:189]
	v_lshlrev_b32_e32 v190, 16, v204
	v_and_b32_e32 v191, 0xffff0000, v204
	v_lshlrev_b32_e32 v192, 16, v205
	v_and_b32_e32 v193, 0xffff0000, v205
	v_pk_fma_f32 v[8:9], v[8:9], v[138:139], v[190:191]
	v_pk_fma_f32 v[10:11], v[10:11], v[140:141], v[192:193]
	v_cvt_pk_bf16_f32 v16, v16, v17
	v_cvt_pk_bf16_f32 v17, v18, v19
	v_cvt_pk_bf16_f32 v18, v8, v9
	v_cvt_pk_bf16_f32 v19, v10, v11
	s_nop 1
	v_permlane16_swap_b32 v16, v18
	v_permlane16_swap_b32 v17, v19
	v_mov_b32_e32 v212, 0x58000
	v_lshl_add_u64 v[220:221], v[216:217], 0, v[212:213]
	global_store_dwordx4 v[220:221], v[16:19], off
	s_waitcnt vmcnt(7)
	v_permlane16_swap_b32 v206, v208
	v_permlane16_swap_b32 v207, v209
	s_nop 1
	v_lshlrev_b32_e32 v186, 16, v206
	v_and_b32_e32 v187, 0xffff0000, v206
	v_lshlrev_b32_e32 v188, 16, v207
	v_and_b32_e32 v189, 0xffff0000, v207
	v_pk_fma_f32 v[4:5], v[4:5], v[134:135], v[186:187]
	v_pk_fma_f32 v[6:7], v[6:7], v[136:137], v[188:189]
	v_lshlrev_b32_e32 v190, 16, v208
	v_and_b32_e32 v191, 0xffff0000, v208
	v_lshlrev_b32_e32 v192, 16, v209
	v_and_b32_e32 v193, 0xffff0000, v209
	v_pk_fma_f32 v[0:1], v[0:1], v[130:131], v[190:191]
	v_pk_fma_f32 v[2:3], v[2:3], v[132:133], v[192:193]
	v_cvt_pk_bf16_f32 v4, v4, v5
	v_cvt_pk_bf16_f32 v5, v6, v7
	v_cvt_pk_bf16_f32 v6, v0, v1
	v_cvt_pk_bf16_f32 v7, v2, v3
	s_nop 1
	v_permlane16_swap_b32 v4, v6
	v_permlane16_swap_b32 v5, v7
	v_mov_b32_e32 v212, 0x58000
	v_lshl_add_u64 v[220:221], v[216:217], 0, v[212:213]
	global_store_dwordx4 v[220:221], v[4:7], off offset:256
	s_mov_b32 s16, s43
	s_mov_b32 s17, s42
	s_and_b64 vcc, exec, s[0:1]
	s_mov_b64 s[18:19], s[12:13]
	s_cbranch_vccz .LBB0_1432
	s_waitcnt vmcnt(0)
	s_cmpk_gt_u32 s29, 0xff
	s_cbranch_scc1 .LBB0_1439
	s_barrier
